# GEMM loops: M0 write moved ahead of the address add so the s_nop before each LDS-DMA load is dropped
# speedup vs baseline: 1.0547x; 1.0015x over previous
; #define PG8_STAGE(bufoff, gbase, voff) do { _Pragma("unroll") for (int _i = 0; _i < 2; ++_i) \
;         __builtin_amdgcn_global_load_lds((const unsigned*)((const char*)(gbase) + (voff)[_i]), (LAS unsigned*)(lds + (bufoff) + ldsw + _i * 8192), 16, 0, 0); } while (0)
; #define PG8_LDA(dst, b, h) do { _Pragma("unroll") for (int m = 0; m < 4; ++m) _Pragma("unroll") for (int k = 0; k < 2; ++k) dst[m][k] = *(const LAS bf16x8*)(lds + PG8_SA(b, h) + aoff + m * 2048 + k * 1024); } while (0)
; #define PG8_LDB(dst, b, h) do { _Pragma("unroll") for (int n = 0; n < 2; ++n) _Pragma("unroll") for (int k = 0; k < 2; ++k) dst[n][k] = *(const LAS bf16x8*)(lds + PG8_SB(b, h) + boff + n * 2048 + k * 1024); } while (0)
; #define PG8_MMA(ai, bj, At, Bt) do { __builtin_amdgcn_s_setprio(1); _Pragma("unroll") for (int m = 0; m < 4; ++m) _Pragma("unroll") for (int n = 0; n < 2; ++n) _Pragma("unroll") for (int k = 0; k < 2; ++k) \
;         acc[ai][bj][m][n] = __builtin_amdgcn_mfma_f32_16x16x32_bf16(Bt[n][k], At[m][k], acc[ai][bj][m][n], 0, 0, 0); __builtin_amdgcn_s_setprio(0); } while (0)
; #define PG8_WAIT_L(n) asm volatile("s_waitcnt lgkmcnt(" #n ")" ::: "memory")
; #define PG8_BAR __builtin_amdgcn_s_barrier()
; #define PG8_SCHED __builtin_amdgcn_sched_barrier(0)
; template <class Epi>
; __device__ __forceinline__ void gemm_phase(LAS unsigned char* lds, const Gemm g, const StaticOrder& S, const Epi& E) {
;     ...
;         for (int t = 0; t < nt; t += 2) {
;             const bool last = (t == nt - 2);
;             const char* a1 = cA + (size_t)(t + 1) * kstep;
;             const char* a2 = last ? nA : cA + (size_t)(t + 2) * kstep; const char* b2 = last ? nB : cB + (size_t)(t + 2) * kstep;
;             const char* a3 = a2 + kstep; const char* b3 = b2 + kstep;
;             PG8_LDB(B0, 0, 0); PG8_SCHED; PG8_LDA(At, 0, 0); PG8_STAGE(PG8_SA(1, 1), a1 + hstep, voffA);
;             PG8_WAIT_L(8); PG8_BAR; PG8_WAIT_L(0); PG8_MMA(0, 0, At, B0); PG8_BAR; PG8_SCHED;
;             PG8_LDB(B1, 0, 1); PG8_STAGE(PG8_SB(0, 0), b2, voffB);
;             PG8_BAR; PG8_WAIT_L(0); PG8_MMA(0, 1, At, B1); PG8_BAR;
;             PG8_LDA(At, 0, 1); PG8_STAGE(PG8_SA(0, 0), a2, voffA);
;             PG8_BAR; PG8_WAIT_L(0); PG8_MMA(1, 0, At, B0); PG8_BAR; PG8_SCHED;
.LBB0_2079:
	s_add_u32 s0, s22, 0xfffc0080
	s_addc_u32 s1, s23, -1
	s_add_i32 s62, 0, 0x10000
	v_add_u32_e32 v142, s62, v161
	ds_read_b128 v[122:125], v142
	ds_read_b128 v[126:129], v142 offset:1024
	ds_read_b128 v[138:141], v142 offset:2048
	ds_read_b128 v[142:145], v142 offset:3072
	s_cmp_eq_u32 s61, 12
	s_cselect_b32 s27, s15, s1
	s_cselect_b32 s26, s57, s0
	s_cselect_b32 s25, s13, s60
	s_cselect_b32 s24, s58, s59
	v_lshl_add_u64 v[186:187], s[22:23], 0, v[152:153]
	s_add_i32 m0, s21, 0xc000
	ds_read_b128 v[166:169], v165
	ds_read_b128 v[170:173], v165 offset:1024
	ds_read_b128 v[174:177], v165 offset:2048
	ds_read_b128 v[190:193], v165 offset:3072
	ds_read_b128 v[194:197], v165 offset:4096
	ds_read_b128 v[198:201], v165 offset:5120
	ds_read_b128 v[202:205], v165 offset:6144
	ds_read_b128 v[206:209], v165 offset:7168
	global_load_lds_dwordx4 v[186:187], off
	s_add_i32 m0, s21, 0xe000
	v_lshl_add_u64 v[186:187], s[22:23], 0, v[154:155]
	global_load_lds_dwordx4 v[186:187], off
	s_waitcnt lgkmcnt(8)
	s_barrier
	s_waitcnt lgkmcnt(0)
	v_mfma_f32_16x16x32_bf16 v[134:137], v[122:125], v[166:169], v[134:137]
	v_mfma_f32_16x16x32_bf16 v[130:133], v[138:141], v[166:169], v[130:133]
	v_mfma_f32_16x16x32_bf16 v[118:121], v[122:125], v[174:177], v[118:121]
	v_mfma_f32_16x16x32_bf16 v[114:117], v[138:141], v[174:177], v[114:117]
	v_mfma_f32_16x16x32_bf16 v[110:113], v[122:125], v[194:197], v[110:113]
	v_mfma_f32_16x16x32_bf16 v[106:109], v[138:141], v[194:197], v[106:109]
	v_mfma_f32_16x16x32_bf16 v[102:105], v[122:125], v[202:205], v[102:105]
	v_mfma_f32_16x16x32_bf16 v[98:101], v[138:141], v[202:205], v[98:101]
	v_mfma_f32_16x16x32_bf16 v[134:137], v[126:129], v[170:173], v[134:137]
	v_mfma_f32_16x16x32_bf16 v[130:133], v[142:145], v[170:173], v[130:133]
	v_mfma_f32_16x16x32_bf16 v[118:121], v[126:129], v[190:193], v[118:121]
	v_mfma_f32_16x16x32_bf16 v[114:117], v[142:145], v[190:193], v[114:117]
	v_mfma_f32_16x16x32_bf16 v[110:113], v[126:129], v[198:201], v[110:113]
	v_mfma_f32_16x16x32_bf16 v[106:109], v[142:145], v[198:201], v[106:109]
	v_mfma_f32_16x16x32_bf16 v[102:105], v[126:129], v[206:209], v[102:105]
	v_mfma_f32_16x16x32_bf16 v[98:101], v[142:145], v[206:209], v[98:101]
	s_barrier
	s_add_i32 s0, 0, 0x14000
	s_add_i32 s1, s62, s36
	v_add_u32_e32 v158, s0, v161
	v_lshl_add_u64 v[186:187], s[24:25], 0, v[4:5]
	s_mov_b32 m0, s1
	ds_read_b128 v[210:213], v158
	ds_read_b128 v[214:217], v158 offset:1024
	ds_read_b128 v[218:221], v158 offset:2048
	ds_read_b128 v[222:225], v158 offset:3072
	global_load_lds_dwordx4 v[186:187], off
	s_add_i32 m0, s1, 0x2000
	v_lshl_add_u64 v[226:227], s[24:25], 0, v[146:147]
	global_load_lds_dwordx4 v[226:227], off
	s_barrier
	s_waitcnt lgkmcnt(0)
	v_mfma_f32_16x16x32_bf16 v[70:73], v[210:213], v[166:169], v[70:73]
	v_mfma_f32_16x16x32_bf16 v[66:69], v[218:221], v[166:169], v[66:69]
	v_mfma_f32_16x16x32_bf16 v[54:57], v[210:213], v[174:177], v[54:57]
	v_mfma_f32_16x16x32_bf16 v[50:53], v[218:221], v[174:177], v[50:53]
	v_mfma_f32_16x16x32_bf16 v[46:49], v[210:213], v[194:197], v[46:49]
	v_mfma_f32_16x16x32_bf16 v[42:45], v[218:221], v[194:197], v[42:45]
	v_mfma_f32_16x16x32_bf16 v[38:41], v[210:213], v[202:205], v[38:41]
	v_mfma_f32_16x16x32_bf16 v[34:37], v[218:221], v[202:205], v[34:37]
	v_mfma_f32_16x16x32_bf16 v[70:73], v[214:217], v[170:173], v[70:73]
	v_mfma_f32_16x16x32_bf16 v[66:69], v[222:225], v[170:173], v[66:69]
	v_mfma_f32_16x16x32_bf16 v[54:57], v[214:217], v[190:193], v[54:57]
	v_mfma_f32_16x16x32_bf16 v[50:53], v[222:225], v[190:193], v[50:53]
	v_mfma_f32_16x16x32_bf16 v[46:49], v[214:217], v[198:201], v[46:49]
	v_mfma_f32_16x16x32_bf16 v[42:45], v[222:225], v[198:201], v[42:45]
	v_mfma_f32_16x16x32_bf16 v[38:41], v[214:217], v[206:209], v[38:41]
	v_mfma_f32_16x16x32_bf16 v[34:37], v[222:225], v[206:209], v[34:37]
	s_mov_b32 m0, s21
	v_lshl_add_u64 v[242:243], s[26:27], 0, v[150:151]
	s_barrier
	ds_read_b128 v[166:169], v165 offset:16384
	ds_read_b128 v[170:173], v165 offset:17408
	ds_read_b128 v[174:177], v165 offset:18432
	ds_read_b128 v[190:193], v165 offset:19456
	ds_read_b128 v[194:197], v165 offset:20480
	ds_read_b128 v[198:201], v165 offset:21504
	ds_read_b128 v[202:205], v165 offset:22528
	ds_read_b128 v[206:209], v165 offset:23552
	global_load_lds_dwordx4 v[242:243], off
	s_mov_b32 m0, s42
	v_lshl_add_u64 v[244:245], s[26:27], 0, v[148:149]
	global_load_lds_dwordx4 v[244:245], off
	s_barrier
	s_waitcnt lgkmcnt(0)
	v_mfma_f32_16x16x32_bf16 v[94:97], v[122:125], v[166:169], v[94:97]
	v_mfma_f32_16x16x32_bf16 v[90:93], v[138:141], v[166:169], v[90:93]
	v_mfma_f32_16x16x32_bf16 v[86:89], v[122:125], v[174:177], v[86:89]
	v_mfma_f32_16x16x32_bf16 v[82:85], v[138:141], v[174:177], v[82:85]
	v_mfma_f32_16x16x32_bf16 v[78:81], v[122:125], v[194:197], v[78:81]
	v_mfma_f32_16x16x32_bf16 v[74:77], v[138:141], v[194:197], v[74:77]
	v_mfma_f32_16x16x32_bf16 v[62:65], v[122:125], v[202:205], v[62:65]
	v_mfma_f32_16x16x32_bf16 v[58:61], v[138:141], v[202:205], v[58:61]
	v_mfma_f32_16x16x32_bf16 v[94:97], v[126:129], v[170:173], v[94:97]
	v_mfma_f32_16x16x32_bf16 v[90:93], v[142:145], v[170:173], v[90:93]
	v_mfma_f32_16x16x32_bf16 v[86:89], v[126:129], v[190:193], v[86:89]
	v_mfma_f32_16x16x32_bf16 v[82:85], v[142:145], v[190:193], v[82:85]
	v_mfma_f32_16x16x32_bf16 v[78:81], v[126:129], v[198:201], v[78:81]
	v_mfma_f32_16x16x32_bf16 v[74:77], v[142:145], v[198:201], v[74:77]
	v_mfma_f32_16x16x32_bf16 v[62:65], v[126:129], v[206:209], v[62:65]
	v_mfma_f32_16x16x32_bf16 v[58:61], v[142:145], v[206:209], v[58:61]
	s_barrier
; #define PG8_STAGE(bufoff, gbase, voff) do { _Pragma("unroll") for (int _i = 0; _i < 2; ++_i) \
;         __builtin_amdgcn_global_load_lds((const unsigned*)((const char*)(gbase) + (voff)[_i]), (LAS unsigned*)(lds + (bufoff) + ldsw + _i * 8192), 16, 0, 0); } while (0)
; #define PG8_LDA(dst, b, h) do { _Pragma("unroll") for (int m = 0; m < 4; ++m) _Pragma("unroll") for (int k = 0; k < 2; ++k) dst[m][k] = *(const LAS bf16x8*)(lds + PG8_SA(b, h) + aoff + m * 2048 + k * 1024); } while (0)
; #define PG8_LDB(dst, b, h) do { _Pragma("unroll") for (int n = 0; n < 2; ++n) _Pragma("unroll") for (int k = 0; k < 2; ++k) dst[n][k] = *(const LAS bf16x8*)(lds + PG8_SB(b, h) + boff + n * 2048 + k * 1024); } while (0)
; #define PG8_MMA(ai, bj, At, Bt) do { __builtin_amdgcn_s_setprio(1); _Pragma("unroll") for (int m = 0; m < 4; ++m) _Pragma("unroll") for (int n = 0; n < 2; ++n) _Pragma("unroll") for (int k = 0; k < 2; ++k) \
;         acc[ai][bj][m][n] = __builtin_amdgcn_mfma_f32_16x16x32_bf16(Bt[n][k], At[m][k], acc[ai][bj][m][n], 0, 0, 0); __builtin_amdgcn_s_setprio(0); } while (0)
; #define PG8_WAIT_V(n) asm volatile("s_waitcnt vmcnt(" #n ")" ::: "memory")
; #define PG8_WAIT_L(n) asm volatile("s_waitcnt lgkmcnt(" #n ")" ::: "memory")
; #define PG8_BAR __builtin_amdgcn_s_barrier()
; #define PG8_SCHED __builtin_amdgcn_sched_barrier(0)
; template <class Epi>
; __device__ __forceinline__ void gemm_phase(LAS unsigned char* lds, const Gemm g, const StaticOrder& S, const Epi& E) {
;     ...
;             PG8_STAGE(PG8_SB(0, 1), b2 + hstep, voffB);
;             PG8_WAIT_V(6); PG8_BAR; PG8_MMA(1, 1, At, B1); PG8_BAR;
;             PG8_LDB(B0, 1, 0); PG8_SCHED; PG8_LDA(At, 1, 0); PG8_STAGE(PG8_SA(0, 1), a2 + hstep, voffA);
;             PG8_WAIT_L(8); PG8_BAR; PG8_WAIT_L(0); PG8_MMA(0, 0, At, B0); PG8_BAR; PG8_SCHED;
;             PG8_LDB(B1, 1, 1); PG8_STAGE(PG8_SB(1, 0), b3, voffB);
;             PG8_BAR; PG8_WAIT_L(0); PG8_MMA(0, 1, At, B1); PG8_BAR;
;             PG8_LDA(At, 1, 1); PG8_STAGE(PG8_SA(1, 0), a3, voffA);
;             PG8_BAR; PG8_WAIT_L(0); PG8_MMA(1, 0, At, B0); PG8_BAR; PG8_SCHED;
	s_add_u32 s62, s24, 0x40000
	s_addc_u32 s63, s25, 0
	s_add_i32 s0, s0, s36
	s_mov_b32 m0, s0
	v_lshl_add_u64 v[122:123], s[62:63], 0, v[4:5]
	global_load_lds_dwordx4 v[122:123], off
	s_add_i32 m0, s0, 0x2000
	v_lshl_add_u64 v[122:123], s[62:63], 0, v[146:147]
	global_load_lds_dwordx4 v[122:123], off
	s_waitcnt vmcnt(6)
	s_barrier
	v_mfma_f32_16x16x32_bf16 v[30:33], v[210:213], v[166:169], v[30:33]
	v_mfma_f32_16x16x32_bf16 v[26:29], v[218:221], v[166:169], v[26:29]
	v_mfma_f32_16x16x32_bf16 v[22:25], v[210:213], v[174:177], v[22:25]
	v_mfma_f32_16x16x32_bf16 v[18:21], v[218:221], v[174:177], v[18:21]
	v_mfma_f32_16x16x32_bf16 v[14:17], v[210:213], v[194:197], v[14:17]
	v_mfma_f32_16x16x32_bf16 v[10:13], v[218:221], v[194:197], v[10:13]
	v_mfma_f32_16x16x32_bf16 v[6:9], v[210:213], v[202:205], v[6:9]
	v_mfma_f32_16x16x32_bf16 v[0:3], v[218:221], v[202:205], v[0:3]
	v_mfma_f32_16x16x32_bf16 v[30:33], v[214:217], v[170:173], v[30:33]
	v_mfma_f32_16x16x32_bf16 v[26:29], v[222:225], v[170:173], v[26:29]
	v_mfma_f32_16x16x32_bf16 v[22:25], v[214:217], v[190:193], v[22:25]
	v_mfma_f32_16x16x32_bf16 v[18:21], v[222:225], v[190:193], v[18:21]
	v_mfma_f32_16x16x32_bf16 v[14:17], v[214:217], v[198:201], v[14:17]
	v_mfma_f32_16x16x32_bf16 v[10:13], v[222:225], v[198:201], v[10:13]
	v_mfma_f32_16x16x32_bf16 v[6:9], v[214:217], v[206:209], v[6:9]
	v_mfma_f32_16x16x32_bf16 v[0:3], v[222:225], v[206:209], v[0:3]
	s_add_i32 s0, 0, 0x18000
	v_add_u32_e32 v142, s0, v161
	s_barrier
	ds_read_b128 v[122:125], v142
	ds_read_b128 v[126:129], v142 offset:1024
	ds_read_b128 v[138:141], v142 offset:2048
	ds_read_b128 v[142:145], v142 offset:3072
	s_add_u32 s26, s26, 0x40000
	s_addc_u32 s27, s27, 0
	s_mov_b32 m0, s43
	v_lshl_add_u64 v[210:211], s[26:27], 0, v[150:151]
	ds_read_b128 v[166:169], v165 offset:32768
	ds_read_b128 v[170:173], v165 offset:33792
	ds_read_b128 v[174:177], v165 offset:34816
	ds_read_b128 v[190:193], v165 offset:35840
	ds_read_b128 v[194:197], v165 offset:36864
	ds_read_b128 v[198:201], v165 offset:37888
	ds_read_b128 v[202:205], v165 offset:38912
	ds_read_b128 v[206:209], v165 offset:39936
	global_load_lds_dwordx4 v[210:211], off
	s_mov_b32 m0, s48
	v_lshl_add_u64 v[210:211], s[26:27], 0, v[148:149]
	global_load_lds_dwordx4 v[210:211], off
	s_waitcnt lgkmcnt(8)
	s_barrier
	s_waitcnt lgkmcnt(0)
	v_mfma_f32_16x16x32_bf16 v[134:137], v[122:125], v[166:169], v[134:137]
	v_mfma_f32_16x16x32_bf16 v[130:133], v[138:141], v[166:169], v[130:133]
	v_mfma_f32_16x16x32_bf16 v[118:121], v[122:125], v[174:177], v[118:121]
	v_mfma_f32_16x16x32_bf16 v[114:117], v[138:141], v[174:177], v[114:117]
	v_mfma_f32_16x16x32_bf16 v[110:113], v[122:125], v[194:197], v[110:113]
	v_mfma_f32_16x16x32_bf16 v[106:109], v[138:141], v[194:197], v[106:109]
	v_mfma_f32_16x16x32_bf16 v[102:105], v[122:125], v[202:205], v[102:105]
	v_mfma_f32_16x16x32_bf16 v[98:101], v[138:141], v[202:205], v[98:101]
	v_mfma_f32_16x16x32_bf16 v[134:137], v[126:129], v[170:173], v[134:137]
	v_mfma_f32_16x16x32_bf16 v[130:133], v[142:145], v[170:173], v[130:133]
	v_mfma_f32_16x16x32_bf16 v[118:121], v[126:129], v[190:193], v[118:121]
	v_mfma_f32_16x16x32_bf16 v[114:117], v[142:145], v[190:193], v[114:117]
	v_mfma_f32_16x16x32_bf16 v[110:113], v[126:129], v[198:201], v[110:113]
	v_mfma_f32_16x16x32_bf16 v[106:109], v[142:145], v[198:201], v[106:109]
	v_mfma_f32_16x16x32_bf16 v[102:105], v[126:129], v[206:209], v[102:105]
	v_mfma_f32_16x16x32_bf16 v[98:101], v[142:145], v[206:209], v[98:101]
	s_barrier
	s_add_i32 s1, 0, 0x1c000
	s_add_i32 s0, s0, s36
	v_add_u32_e32 v158, s1, v161
	v_lshl_add_u64 v[186:187], v[186:187], 0, s[86:87]
	s_mov_b32 m0, s0
	ds_read_b128 v[210:213], v158
	ds_read_b128 v[214:217], v158 offset:1024
	ds_read_b128 v[218:221], v158 offset:2048
	ds_read_b128 v[222:225], v158 offset:3072
	global_load_lds_dwordx4 v[186:187], off
	s_add_i32 m0, s0, 0x2000
	v_lshl_add_u64 v[186:187], v[226:227], 0, s[86:87]
	global_load_lds_dwordx4 v[186:187], off
	s_barrier
	s_waitcnt lgkmcnt(0)
	v_mfma_f32_16x16x32_bf16 v[70:73], v[210:213], v[166:169], v[70:73]
	v_mfma_f32_16x16x32_bf16 v[66:69], v[218:221], v[166:169], v[66:69]
	v_mfma_f32_16x16x32_bf16 v[54:57], v[210:213], v[174:177], v[54:57]
	v_mfma_f32_16x16x32_bf16 v[50:53], v[218:221], v[174:177], v[50:53]
	v_mfma_f32_16x16x32_bf16 v[46:49], v[210:213], v[194:197], v[46:49]
	v_mfma_f32_16x16x32_bf16 v[42:45], v[218:221], v[194:197], v[42:45]
	v_mfma_f32_16x16x32_bf16 v[38:41], v[210:213], v[202:205], v[38:41]
	v_mfma_f32_16x16x32_bf16 v[34:37], v[218:221], v[202:205], v[34:37]
	v_mfma_f32_16x16x32_bf16 v[70:73], v[214:217], v[170:173], v[70:73]
	v_mfma_f32_16x16x32_bf16 v[66:69], v[222:225], v[170:173], v[66:69]
	v_mfma_f32_16x16x32_bf16 v[54:57], v[214:217], v[190:193], v[54:57]
	v_mfma_f32_16x16x32_bf16 v[50:53], v[222:225], v[190:193], v[50:53]
	v_mfma_f32_16x16x32_bf16 v[46:49], v[214:217], v[198:201], v[46:49]
	v_mfma_f32_16x16x32_bf16 v[42:45], v[222:225], v[198:201], v[42:45]
	v_mfma_f32_16x16x32_bf16 v[38:41], v[214:217], v[206:209], v[38:41]
	v_mfma_f32_16x16x32_bf16 v[34:37], v[222:225], v[206:209], v[34:37]
	s_mov_b32 m0, s51
	v_lshl_add_u64 v[186:187], v[242:243], 0, s[86:87]
	s_barrier
	ds_read_b128 v[166:169], v165 offset:49152
	ds_read_b128 v[170:173], v165 offset:50176
	ds_read_b128 v[174:177], v165 offset:51200
	ds_read_b128 v[190:193], v165 offset:52224
	ds_read_b128 v[194:197], v165 offset:53248
	ds_read_b128 v[198:201], v165 offset:54272
	ds_read_b128 v[202:205], v165 offset:55296
	ds_read_b128 v[206:209], v165 offset:56320
	global_load_lds_dwordx4 v[186:187], off
	s_mov_b32 m0, s54
	v_lshl_add_u64 v[186:187], v[244:245], 0, s[86:87]
	global_load_lds_dwordx4 v[186:187], off
	s_barrier
; #define PG8_STAGE(bufoff, gbase, voff) do { _Pragma("unroll") for (int _i = 0; _i < 2; ++_i) \
;         __builtin_amdgcn_global_load_lds((const unsigned*)((const char*)(gbase) + (voff)[_i]), (LAS unsigned*)(lds + (bufoff) + ldsw + _i * 8192), 16, 0, 0); } while (0)
; #define PG8_MMA(ai, bj, At, Bt) do { __builtin_amdgcn_s_setprio(1); _Pragma("unroll") for (int m = 0; m < 4; ++m) _Pragma("unroll") for (int n = 0; n < 2; ++n) _Pragma("unroll") for (int k = 0; k < 2; ++k) \
;         acc[ai][bj][m][n] = __builtin_amdgcn_mfma_f32_16x16x32_bf16(Bt[n][k], At[m][k], acc[ai][bj][m][n], 0, 0, 0); __builtin_amdgcn_s_setprio(0); } while (0)
; #define PG8_WAIT_V(n) asm volatile("s_waitcnt vmcnt(" #n ")" ::: "memory")
; #define PG8_BAR __builtin_amdgcn_s_barrier()
; template <class Epi>
; __device__ __forceinline__ void gemm_phase(LAS unsigned char* lds, const Gemm g, const StaticOrder& S, const Epi& E) {
;     ...
;             PG8_STAGE(PG8_SB(1, 1), b3 + hstep, voffB);
;             PG8_WAIT_V(6); PG8_BAR; PG8_MMA(1, 1, At, B1); PG8_BAR;
;     __device__ __forceinline__ void operator()(const f32x4 (&acc)[2][2][4][2], const Unit& u, int wr, int wc, int fr, int fq) const {
;         const int row0 = u.pm * 256 + wr * 64 + fr, col0 = u.pn * 256 + wc * 32 + 8 * fq;
;         f32x4 ra = (f32x4){1.f, 1.f, 1.f, 1.f}, rb = ra;
;         f32x4 swv[4] = {(f32x4){0.f, 0.f, 0.f, 0.f}, (f32x4){0.f, 0.f, 0.f, 0.f}, (f32x4){0.f, 0.f, 0.f, 0.f}, (f32x4){0.f, 0.f, 0.f, 0.f}};
;         if (ss) { load_rstd(ss, row0, ra, rb); const float* swp = sw + (size_t)(u.pm >> 3) * ldc + col0;
;             swv[0] = *(const f32x4*)(swp); swv[1] = *(const f32x4*)(swp + 4); swv[2] = *(const f32x4*)(swp + 128); swv[3] = *(const f32x4*)(swp + 132); }
	s_waitcnt lgkmcnt(0)
	v_mfma_f32_16x16x32_bf16 v[94:97], v[122:125], v[166:169], v[94:97]
	v_mfma_f32_16x16x32_bf16 v[90:93], v[138:141], v[166:169], v[90:93]
	v_mfma_f32_16x16x32_bf16 v[86:89], v[122:125], v[174:177], v[86:89]
	v_mfma_f32_16x16x32_bf16 v[82:85], v[138:141], v[174:177], v[82:85]
	v_mfma_f32_16x16x32_bf16 v[78:81], v[122:125], v[194:197], v[78:81]
	v_mfma_f32_16x16x32_bf16 v[74:77], v[138:141], v[194:197], v[74:77]
	v_mfma_f32_16x16x32_bf16 v[62:65], v[122:125], v[202:205], v[62:65]
	v_mfma_f32_16x16x32_bf16 v[58:61], v[138:141], v[202:205], v[58:61]
	v_mfma_f32_16x16x32_bf16 v[94:97], v[126:129], v[170:173], v[94:97]
	v_mfma_f32_16x16x32_bf16 v[90:93], v[142:145], v[170:173], v[90:93]
	v_mfma_f32_16x16x32_bf16 v[86:89], v[126:129], v[190:193], v[86:89]
	v_mfma_f32_16x16x32_bf16 v[82:85], v[142:145], v[190:193], v[82:85]
	v_mfma_f32_16x16x32_bf16 v[78:81], v[126:129], v[198:201], v[78:81]
	v_mfma_f32_16x16x32_bf16 v[74:77], v[142:145], v[198:201], v[74:77]
	v_mfma_f32_16x16x32_bf16 v[62:65], v[126:129], v[206:209], v[62:65]
	v_mfma_f32_16x16x32_bf16 v[58:61], v[142:145], v[206:209], v[58:61]
	s_barrier
	s_add_u32 s24, s24, 0x40080
	s_addc_u32 s25, s25, 0
	s_add_i32 s0, s1, s36
	s_mov_b32 m0, s0
	v_lshl_add_u64 v[122:123], s[24:25], 0, v[4:5]
	global_load_lds_dwordx4 v[122:123], off
	s_add_i32 m0, s0, 0x2000
	v_lshl_add_u64 v[122:123], s[24:25], 0, v[146:147]
	global_load_lds_dwordx4 v[122:123], off
	s_waitcnt vmcnt(6)
	s_barrier
	v_mfma_f32_16x16x32_bf16 v[30:33], v[210:213], v[166:169], v[30:33]
	v_mfma_f32_16x16x32_bf16 v[26:29], v[218:221], v[166:169], v[26:29]
	v_mfma_f32_16x16x32_bf16 v[22:25], v[210:213], v[174:177], v[22:25]
	v_mfma_f32_16x16x32_bf16 v[18:21], v[218:221], v[174:177], v[18:21]
	v_mfma_f32_16x16x32_bf16 v[14:17], v[210:213], v[194:197], v[14:17]
	v_mfma_f32_16x16x32_bf16 v[10:13], v[218:221], v[194:197], v[10:13]
	v_mfma_f32_16x16x32_bf16 v[6:9], v[210:213], v[202:205], v[6:9]
	v_mfma_f32_16x16x32_bf16 v[0:3], v[218:221], v[202:205], v[0:3]
	v_mfma_f32_16x16x32_bf16 v[30:33], v[214:217], v[170:173], v[30:33]
	v_mfma_f32_16x16x32_bf16 v[26:29], v[222:225], v[170:173], v[26:29]
	v_mfma_f32_16x16x32_bf16 v[22:25], v[214:217], v[190:193], v[22:25]
	v_mfma_f32_16x16x32_bf16 v[18:21], v[222:225], v[190:193], v[18:21]
	v_mfma_f32_16x16x32_bf16 v[14:17], v[214:217], v[198:201], v[14:17]
	v_mfma_f32_16x16x32_bf16 v[10:13], v[222:225], v[198:201], v[10:13]
	v_mfma_f32_16x16x32_bf16 v[6:9], v[214:217], v[206:209], v[6:9]
	v_mfma_f32_16x16x32_bf16 v[0:3], v[222:225], v[206:209], v[0:3]
	s_add_i32 s61, s61, 2
	s_add_u32 s22, s22, 0x100
	s_addc_u32 s23, s23, 0
	s_add_u32 s59, s59, 0x100
	s_addc_u32 s60, s60, 0
	s_cmp_gt_u32 s61, 13
	s_barrier
	s_cbranch_scc0 .LBB0_2079
	v_lshl_add_u32 v174, s20, 8, v159
	v_ashrrev_i32_e32 v175, 31, v174
	v_lshl_add_u64 v[122:123], v[174:175], 2, s[10:11]
	global_load_dword v190, v[122:123], off
	global_load_dword v191, v[122:123], off offset:64
	global_load_dword v192, v[122:123], off offset:128
	global_load_dword v193, v[122:123], off offset:192
	global_load_dword v194, v[122:123], off offset:512
	global_load_dword v195, v[122:123], off offset:576
	global_load_dword v196, v[122:123], off offset:640
	global_load_dword v197, v[122:123], off offset:704
	s_ashr_i32 s0, s20, 3
	s_mul_hi_i32 s23, s0, s52
	s_mul_i32 s22, s0, s52
	s_lshl_b64 s[22:23], s[22:23], 2
	v_lshl_or_b32 v176, s56, 8, v163
	s_add_u32 s22, s49, s22
	s_addc_u32 s23, s50, s23
	v_ashrrev_i32_e32 v177, 31, v176
	v_lshl_add_u64 v[200:201], v[176:177], 2, s[22:23]
	global_load_dwordx4 v[138:141], v[200:201], off offset:16
	global_load_dwordx4 v[142:145], v[200:201], off
	global_load_dwordx4 v[122:125], v[200:201], off offset:528
	global_load_dwordx4 v[126:129], v[200:201], off offset:512
	s_and_b64 vcc, exec, s[4:5]
	s_mov_b32 s56, s12
	s_mov_b32 s20, s14
	s_mov_b64 s[24:25], s[18:19]
	s_waitcnt vmcnt(4)
	v_fmamk_f32 v202, v190, 0x3a800000, v229
	v_rsq_f32_e32 v172, v202
	v_fmamk_f32 v202, v194, 0x3a800000, v229
	v_rsq_f32_e32 v164, v202
	v_fmamk_f32 v202, v191, 0x3a800000, v229
	v_rsq_f32_e32 v170, v202
	v_fmamk_f32 v202, v195, 0x3a800000, v229
	v_rsq_f32_e32 v162, v202
	v_fmamk_f32 v202, v192, 0x3a800000, v229
	v_rsq_f32_e32 v168, v202
	v_fmamk_f32 v202, v196, 0x3a800000, v229
	v_rsq_f32_e32 v160, v202
	v_fmamk_f32 v202, v193, 0x3a800000, v229
	v_fmamk_f32 v203, v197, 0x3a800000, v229
	v_rsq_f32_e32 v166, v202
	v_rsq_f32_e32 v158, v203
	s_waitcnt vmcnt(0)
; __device__ __forceinline__ unsigned cvt_pk_bf16(float lo, float hi) { unsigned r; asm volatile("s_nop 0\n\tv_cvt_pk_bf16_f32 %0, %1, %2" : "=v"(r) : "v"(lo), "v"(hi)); return r; }
;     __device__ __forceinline__ void operator()(const f32x4 (&acc)[2][2][4][2], const Unit& u, int wr, int wc, int fr, int fq) const {
;     ...
;         for (int bj = 0; bj < 2; ++bj) {
;             const f32x4 s0 = swv[2 * bj], s1 = swv[2 * bj + 1];
; #pragma unroll
;             for (int ai = 0; ai < 2; ++ai)
; #pragma unroll
;                 for (int m = 0; m < 4; ++m) { const int r = row0 + ai * 128 + m * 16;
;                     const float rstd = ai ? rb[m] : ra[m];
;                     const f32x4 v0 = acc[ai][bj][m][0] * rstd + s0, v1 = acc[ai][bj][m][1] * rstd + s1;
;                     uint4 st; st.x = cvt_pk_bf16(v0[0], v0[1]); st.y = cvt_pk_bf16(v0[2], v0[3]); st.z = cvt_pk_bf16(v1[0], v1[1]); st.w = cvt_pk_bf16(v1[2], v1[3]);
;                     *(uint4*)(O + (size_t)r * ldc + col0 + bj * 128) = st; }
	v_pk_fma_f32 v[130:131], v[130:131], v[172:173], v[138:139] op_sel_hi:[1,0,1]
	v_pk_fma_f32 v[136:137], v[136:137], v[172:173], v[144:145] op_sel_hi:[1,0,1]
	v_pk_fma_f32 v[134:135], v[134:135], v[172:173], v[142:143] op_sel_hi:[1,0,1]
	v_pk_fma_f32 v[132:133], v[132:133], v[172:173], v[140:141] op_sel_hi:[1,0,1]
	s_nop 0
	v_cvt_pk_bf16_f32 v134, v134, v135
	s_nop 0
	v_cvt_pk_bf16_f32 v135, v136, v137
	s_nop 0
	v_cvt_pk_bf16_f32 v136, v130, v131
	v_mad_i64_i32 v[130:131], s[22:23], v174, s52, 0
	s_nop 0
	v_cvt_pk_bf16_f32 v137, v132, v133
	v_lshl_add_u64 v[130:131], v[130:131], 1, s[8:9]
	v_lshlrev_b64 v[132:133], 1, v[176:177]
	v_lshl_add_u64 v[130:131], v[130:131], 0, v[132:133]
	global_store_dwordx4 v[130:131], v[134:137], off
	v_pk_fma_f32 v[118:119], v[118:119], v[170:171], v[142:143] op_sel_hi:[1,0,1]
	v_pk_fma_f32 v[114:115], v[114:115], v[170:171], v[138:139] op_sel_hi:[1,0,1]
	v_or_b32_e32 v136, 16, v174
	v_pk_fma_f32 v[120:121], v[120:121], v[170:171], v[144:145] op_sel_hi:[1,0,1]
	v_pk_fma_f32 v[134:135], v[116:117], v[170:171], v[140:141] op_sel_hi:[1,0,1]
	s_nop 0
	v_cvt_pk_bf16_f32 v116, v118, v119
	s_nop 0
	v_cvt_pk_bf16_f32 v117, v120, v121
	s_nop 0
	v_cvt_pk_bf16_f32 v118, v114, v115
	v_mad_i64_i32 v[114:115], s[22:23], v136, s52, 0
	v_lshl_add_u64 v[114:115], v[114:115], 1, s[8:9]
	v_lshl_add_u64 v[114:115], v[114:115], 0, v[132:133]
	s_nop 0
	v_cvt_pk_bf16_f32 v119, v134, v135
	global_store_dwordx4 v[114:115], v[116:119], off
	v_pk_fma_f32 v[110:111], v[110:111], v[168:169], v[142:143] op_sel_hi:[1,0,1]
	v_pk_fma_f32 v[106:107], v[106:107], v[168:169], v[138:139] op_sel_hi:[1,0,1]
	v_or_b32_e32 v118, 32, v174
	v_pk_fma_f32 v[112:113], v[112:113], v[168:169], v[144:145] op_sel_hi:[1,0,1]
	v_pk_fma_f32 v[116:117], v[108:109], v[168:169], v[140:141] op_sel_hi:[1,0,1]
	s_nop 0
	v_cvt_pk_bf16_f32 v108, v110, v111
	s_nop 0
	v_cvt_pk_bf16_f32 v109, v112, v113
	s_nop 0
	v_cvt_pk_bf16_f32 v110, v106, v107
	v_mad_i64_i32 v[106:107], s[22:23], v118, s52, 0
	v_lshl_add_u64 v[106:107], v[106:107], 1, s[8:9]
	v_lshl_add_u64 v[106:107], v[106:107], 0, v[132:133]
	s_nop 0
	v_cvt_pk_bf16_f32 v111, v116, v117
	global_store_dwordx4 v[106:107], v[108:111], off
	v_pk_fma_f32 v[102:103], v[102:103], v[166:167], v[142:143] op_sel_hi:[1,0,1]
	v_pk_fma_f32 v[104:105], v[104:105], v[166:167], v[144:145] op_sel_hi:[1,0,1]
	v_or_b32_e32 v110, 48, v174
	v_pk_fma_f32 v[108:109], v[100:101], v[166:167], v[140:141] op_sel_hi:[1,0,1]
	v_pk_fma_f32 v[100:101], v[98:99], v[166:167], v[138:139] op_sel_hi:[1,0,1]
	s_nop 0
	v_cvt_pk_bf16_f32 v98, v102, v103
	v_mad_i64_i32 v[102:103], s[22:23], v110, s52, 0
	v_lshl_add_u64 v[102:103], v[102:103], 1, s[8:9]
	s_nop 0
	v_cvt_pk_bf16_f32 v99, v104, v105
	s_nop 0
	v_cvt_pk_bf16_f32 v100, v100, v101
	v_lshl_add_u64 v[102:103], v[102:103], 0, v[132:133]
	s_nop 0
	v_cvt_pk_bf16_f32 v101, v108, v109
	global_store_dwordx4 v[102:103], v[98:101], off
	v_pk_fma_f32 v[94:95], v[94:95], v[164:165], v[142:143] op_sel_hi:[1,0,1]
	v_pk_fma_f32 v[96:97], v[96:97], v[164:165], v[144:145] op_sel_hi:[1,0,1]
	v_add_u32_e32 v100, 0x80, v174
	v_pk_fma_f32 v[98:99], v[92:93], v[164:165], v[140:141] op_sel_hi:[1,0,1]
	v_pk_fma_f32 v[92:93], v[90:91], v[164:165], v[138:139] op_sel_hi:[1,0,1]
	s_nop 0
	v_cvt_pk_bf16_f32 v90, v94, v95
	v_mad_i64_i32 v[94:95], s[22:23], v100, s52, 0
	v_lshl_add_u64 v[94:95], v[94:95], 1, s[8:9]
	s_nop 0
	v_cvt_pk_bf16_f32 v91, v96, v97
	s_nop 0
	v_cvt_pk_bf16_f32 v92, v92, v93
	v_lshl_add_u64 v[94:95], v[94:95], 0, v[132:133]
	s_nop 0
	v_cvt_pk_bf16_f32 v93, v98, v99
	global_store_dwordx4 v[94:95], v[90:93], off
	v_pk_fma_f32 v[86:87], v[86:87], v[162:163], v[142:143] op_sel_hi:[1,0,1]
	v_pk_fma_f32 v[88:89], v[88:89], v[162:163], v[144:145] op_sel_hi:[1,0,1]
	v_add_u32_e32 v92, 0x90, v174
	v_pk_fma_f32 v[90:91], v[84:85], v[162:163], v[140:141] op_sel_hi:[1,0,1]
	v_pk_fma_f32 v[84:85], v[82:83], v[162:163], v[138:139] op_sel_hi:[1,0,1]
	s_nop 0
	v_cvt_pk_bf16_f32 v82, v86, v87
	v_mad_i64_i32 v[86:87], s[22:23], v92, s52, 0
	v_lshl_add_u64 v[86:87], v[86:87], 1, s[8:9]
	s_nop 0
	v_cvt_pk_bf16_f32 v83, v88, v89
	s_nop 0
	v_cvt_pk_bf16_f32 v84, v84, v85
	v_lshl_add_u64 v[86:87], v[86:87], 0, v[132:133]
	s_nop 0
	v_cvt_pk_bf16_f32 v85, v90, v91
	global_store_dwordx4 v[86:87], v[82:85], off
	v_pk_fma_f32 v[78:79], v[78:79], v[160:161], v[142:143] op_sel_hi:[1,0,1]
	v_pk_fma_f32 v[80:81], v[80:81], v[160:161], v[144:145] op_sel_hi:[1,0,1]
	v_add_u32_e32 v84, 0xa0, v174
	v_pk_fma_f32 v[82:83], v[76:77], v[160:161], v[140:141] op_sel_hi:[1,0,1]
	v_pk_fma_f32 v[76:77], v[74:75], v[160:161], v[138:139] op_sel_hi:[1,0,1]
	s_nop 0
	v_cvt_pk_bf16_f32 v74, v78, v79
	v_mad_i64_i32 v[78:79], s[22:23], v84, s52, 0
	v_lshl_add_u64 v[78:79], v[78:79], 1, s[8:9]
	s_nop 0
	v_cvt_pk_bf16_f32 v75, v80, v81
	s_nop 0
	v_cvt_pk_bf16_f32 v76, v76, v77
	v_lshl_add_u64 v[78:79], v[78:79], 0, v[132:133]
	s_nop 0
	v_cvt_pk_bf16_f32 v77, v82, v83
	global_store_dwordx4 v[78:79], v[74:77], off
; __device__ __forceinline__ unsigned cvt_pk_bf16(float lo, float hi) { unsigned r; asm volatile("s_nop 0\n\tv_cvt_pk_bf16_f32 %0, %1, %2" : "=v"(r) : "v"(lo), "v"(hi)); return r; }
;     __device__ __forceinline__ void operator()(const f32x4 (&acc)[2][2][4][2], const Unit& u, int wr, int wc, int fr, int fq) const {
;     ...
;         for (int bj = 0; bj < 2; ++bj) {
;             const f32x4 s0 = swv[2 * bj], s1 = swv[2 * bj + 1];
; #pragma unroll
;             for (int ai = 0; ai < 2; ++ai)
; #pragma unroll
;                 for (int m = 0; m < 4; ++m) { const int r = row0 + ai * 128 + m * 16;
;                     const float rstd = ai ? rb[m] : ra[m];
;                     const f32x4 v0 = acc[ai][bj][m][0] * rstd + s0, v1 = acc[ai][bj][m][1] * rstd + s1;
;                     uint4 st; st.x = cvt_pk_bf16(v0[0], v0[1]); st.y = cvt_pk_bf16(v0[2], v0[3]); st.z = cvt_pk_bf16(v1[0], v1[1]); st.w = cvt_pk_bf16(v1[2], v1[3]);
;                     *(uint4*)(O + (size_t)r * ldc + col0 + bj * 128) = st; }
	v_pk_fma_f32 v[62:63], v[62:63], v[158:159], v[142:143] op_sel_hi:[1,0,1]
	v_pk_fma_f32 v[64:65], v[64:65], v[158:159], v[144:145] op_sel_hi:[1,0,1]
	v_add_u32_e32 v76, 0xb0, v174
	v_pk_fma_f32 v[74:75], v[60:61], v[158:159], v[140:141] op_sel_hi:[1,0,1]
	v_pk_fma_f32 v[60:61], v[58:59], v[158:159], v[138:139] op_sel_hi:[1,0,1]
	s_nop 0
	v_cvt_pk_bf16_f32 v58, v62, v63
	v_mad_i64_i32 v[62:63], s[22:23], v76, s52, 0
	v_lshl_add_u64 v[62:63], v[62:63], 1, s[8:9]
	s_nop 0
	v_cvt_pk_bf16_f32 v59, v64, v65
	v_lshl_add_u64 v[62:63], v[62:63], 0, v[132:133]
	s_nop 0
	v_cvt_pk_bf16_f32 v60, v60, v61
	s_nop 0
	v_cvt_pk_bf16_f32 v61, v74, v75
	global_store_dwordx4 v[62:63], v[58:61], off
	v_pk_fma_f32 v[64:65], v[68:69], v[172:173], v[124:125] op_sel_hi:[1,0,1]
	v_pk_fma_f32 v[66:67], v[66:67], v[172:173], v[122:123] op_sel_hi:[1,0,1]
	v_pk_fma_f32 v[58:59], v[70:71], v[172:173], v[126:127] op_sel_hi:[1,0,1]
	v_pk_fma_f32 v[60:61], v[72:73], v[172:173], v[128:129] op_sel_hi:[1,0,1]
	s_nop 0
	v_cvt_pk_bf16_f32 v58, v58, v59
	v_pk_fma_f32 v[56:57], v[56:57], v[170:171], v[128:129] op_sel_hi:[1,0,1]
	s_nop 0
	v_cvt_pk_bf16_f32 v59, v60, v61
	s_nop 0
	v_cvt_pk_bf16_f32 v60, v66, v67
	s_nop 0
	v_cvt_pk_bf16_f32 v61, v64, v65
	global_store_dwordx4 v[130:131], v[58:61], off offset:256
	v_pk_fma_f32 v[54:55], v[54:55], v[170:171], v[126:127] op_sel_hi:[1,0,1]
	v_pk_fma_f32 v[48:49], v[48:49], v[168:169], v[128:129] op_sel_hi:[1,0,1]
	v_pk_fma_f32 v[58:59], v[52:53], v[170:171], v[124:125] op_sel_hi:[1,0,1]
	v_pk_fma_f32 v[52:53], v[50:51], v[170:171], v[122:123] op_sel_hi:[1,0,1]
	s_nop 0
	v_cvt_pk_bf16_f32 v50, v54, v55
	s_nop 0
	v_cvt_pk_bf16_f32 v51, v56, v57
	v_pk_fma_f32 v[46:47], v[46:47], v[168:169], v[126:127] op_sel_hi:[1,0,1]
	s_nop 0
	v_cvt_pk_bf16_f32 v52, v52, v53
	s_nop 0
	v_cvt_pk_bf16_f32 v53, v58, v59
	global_store_dwordx4 v[114:115], v[50:53], off offset:256
	v_pk_fma_f32 v[40:41], v[40:41], v[166:167], v[128:129] op_sel_hi:[1,0,1]
	v_pk_fma_f32 v[38:39], v[38:39], v[166:167], v[126:127] op_sel_hi:[1,0,1]
	v_pk_fma_f32 v[50:51], v[44:45], v[168:169], v[124:125] op_sel_hi:[1,0,1]
	v_pk_fma_f32 v[44:45], v[42:43], v[168:169], v[122:123] op_sel_hi:[1,0,1]
	s_nop 0
	v_cvt_pk_bf16_f32 v42, v46, v47
	s_nop 0
	v_cvt_pk_bf16_f32 v43, v48, v49
	v_pk_fma_f32 v[32:33], v[32:33], v[164:165], v[128:129] op_sel_hi:[1,0,1]
	s_nop 0
	v_cvt_pk_bf16_f32 v44, v44, v45
	s_nop 0
	v_cvt_pk_bf16_f32 v45, v50, v51
	global_store_dwordx4 v[106:107], v[42:45], off offset:256
	v_pk_fma_f32 v[30:31], v[30:31], v[164:165], v[126:127] op_sel_hi:[1,0,1]
	v_pk_fma_f32 v[24:25], v[24:25], v[162:163], v[128:129] op_sel_hi:[1,0,1]
	v_pk_fma_f32 v[42:43], v[36:37], v[166:167], v[124:125] op_sel_hi:[1,0,1]
	v_pk_fma_f32 v[36:37], v[34:35], v[166:167], v[122:123] op_sel_hi:[1,0,1]
	s_nop 0
	v_cvt_pk_bf16_f32 v34, v38, v39
	s_nop 0
	v_cvt_pk_bf16_f32 v35, v40, v41
	v_pk_fma_f32 v[22:23], v[22:23], v[162:163], v[126:127] op_sel_hi:[1,0,1]
	s_nop 0
	v_cvt_pk_bf16_f32 v36, v36, v37
	s_nop 0
	v_cvt_pk_bf16_f32 v37, v42, v43
	global_store_dwordx4 v[102:103], v[34:37], off offset:256
	v_pk_fma_f32 v[16:17], v[16:17], v[160:161], v[128:129] op_sel_hi:[1,0,1]
	v_pk_fma_f32 v[14:15], v[14:15], v[160:161], v[126:127] op_sel_hi:[1,0,1]
	v_pk_fma_f32 v[34:35], v[28:29], v[164:165], v[124:125] op_sel_hi:[1,0,1]
	v_pk_fma_f32 v[28:29], v[26:27], v[164:165], v[122:123] op_sel_hi:[1,0,1]
	s_nop 0
	v_cvt_pk_bf16_f32 v26, v30, v31
	s_nop 0
	v_cvt_pk_bf16_f32 v27, v32, v33
	s_mov_b64 s[22:23], s[16:17]
	s_nop 0
	v_cvt_pk_bf16_f32 v28, v28, v29
	s_nop 0
	v_cvt_pk_bf16_f32 v29, v34, v35
	global_store_dwordx4 v[94:95], v[26:29], off offset:256
	v_pk_fma_f32 v[8:9], v[8:9], v[158:159], v[128:129] op_sel_hi:[1,0,1]
	v_pk_fma_f32 v[6:7], v[6:7], v[158:159], v[126:127] op_sel_hi:[1,0,1]
	v_pk_fma_f32 v[26:27], v[20:21], v[162:163], v[124:125] op_sel_hi:[1,0,1]
	v_pk_fma_f32 v[20:21], v[18:19], v[162:163], v[122:123] op_sel_hi:[1,0,1]
	s_nop 0
	v_cvt_pk_bf16_f32 v18, v22, v23
	s_nop 0
	v_cvt_pk_bf16_f32 v19, v24, v25
	s_nop 0
	s_nop 0
	v_cvt_pk_bf16_f32 v20, v20, v21
	s_nop 0
	v_cvt_pk_bf16_f32 v21, v26, v27
	global_store_dwordx4 v[86:87], v[18:21], off offset:256
	s_nop 1
	v_pk_fma_f32 v[18:19], v[12:13], v[160:161], v[124:125] op_sel_hi:[1,0,1]
	v_pk_fma_f32 v[12:13], v[10:11], v[160:161], v[122:123] op_sel_hi:[1,0,1]
	s_nop 0
	v_cvt_pk_bf16_f32 v10, v14, v15
	s_nop 0
	v_cvt_pk_bf16_f32 v11, v16, v17
	s_nop 0
	s_nop 0
	v_cvt_pk_bf16_f32 v12, v12, v13
	s_nop 0
	v_cvt_pk_bf16_f32 v13, v18, v19
	global_store_dwordx4 v[78:79], v[10:13], off offset:256
	s_nop 1
	v_pk_fma_f32 v[10:11], v[2:3], v[158:159], v[124:125] op_sel_hi:[1,0,1]
	v_pk_fma_f32 v[2:3], v[0:1], v[158:159], v[122:123] op_sel_hi:[1,0,1]
	s_nop 0
	v_cvt_pk_bf16_f32 v0, v6, v7
	s_nop 0
	v_cvt_pk_bf16_f32 v1, v8, v9
	s_nop 0
	s_nop 0
	v_cvt_pk_bf16_f32 v2, v2, v3
	s_nop 0
	v_cvt_pk_bf16_f32 v3, v10, v11
	global_store_dwordx4 v[62:63], v[0:3], off offset:256
	s_cbranch_vccz .LBB0_2076
	s_waitcnt vmcnt(0)
	s_cmpk_gt_u32 s28, 0xff
	s_cbranch_scc1 .LBB0_2083
	s_barrier

; #define PG8_STAGE(bufoff, gbase, voff) do { _Pragma("unroll") for (int _i = 0; _i < 2; ++_i) \
;         __builtin_amdgcn_global_load_lds((const unsigned*)((const char*)(gbase) + (voff)[_i]), (LAS unsigned*)(lds + (bufoff) + ldsw + _i * 8192), 16, 0, 0); } while (0)
; #define PG8_LDA(dst, b, h) do { _Pragma("unroll") for (int m = 0; m < 4; ++m) _Pragma("unroll") for (int k = 0; k < 2; ++k) dst[m][k] = *(const LAS bf16x8*)(lds + PG8_SA(b, h) + aoff + m * 2048 + k * 1024); } while (0)
; #define PG8_LDB(dst, b, h) do { _Pragma("unroll") for (int n = 0; n < 2; ++n) _Pragma("unroll") for (int k = 0; k < 2; ++k) dst[n][k] = *(const LAS bf16x8*)(lds + PG8_SB(b, h) + boff + n * 2048 + k * 1024); } while (0)
; #define PG8_MMA(ai, bj, At, Bt) do { __builtin_amdgcn_s_setprio(1); _Pragma("unroll") for (int m = 0; m < 4; ++m) _Pragma("unroll") for (int n = 0; n < 2; ++n) _Pragma("unroll") for (int k = 0; k < 2; ++k) \
;         acc[ai][bj][m][n] = __builtin_amdgcn_mfma_f32_16x16x32_bf16(Bt[n][k], At[m][k], acc[ai][bj][m][n], 0, 0, 0); __builtin_amdgcn_s_setprio(0); } while (0)
; #define PG8_WAIT_L(n) asm volatile("s_waitcnt lgkmcnt(" #n ")" ::: "memory")
; #define PG8_BAR __builtin_amdgcn_s_barrier()
; #define PG8_SCHED __builtin_amdgcn_sched_barrier(0)
; template <class Epi>
; __device__ __forceinline__ void gemm_phase(LAS unsigned char* lds, const Gemm g, const StaticOrder& S, const Epi& E) {
;     ...
;         for (int t = 0; t < nt; t += 2) {
;             const bool last = (t == nt - 2);
;             const char* a1 = cA + (size_t)(t + 1) * kstep;
;             const char* a2 = last ? nA : cA + (size_t)(t + 2) * kstep; const char* b2 = last ? nB : cB + (size_t)(t + 2) * kstep;
;             const char* a3 = a2 + kstep; const char* b3 = b2 + kstep;
;             PG8_LDB(B0, 0, 0); PG8_SCHED; PG8_LDA(At, 0, 0); PG8_STAGE(PG8_SA(1, 1), a1 + hstep, voffA);
;             PG8_WAIT_L(8); PG8_BAR; PG8_WAIT_L(0); PG8_MMA(0, 0, At, B0); PG8_BAR; PG8_SCHED;
;             PG8_LDB(B1, 0, 1); PG8_STAGE(PG8_SB(0, 0), b2, voffB);
;             PG8_BAR; PG8_WAIT_L(0); PG8_MMA(0, 1, At, B1); PG8_BAR;
;             PG8_LDA(At, 0, 1); PG8_STAGE(PG8_SA(0, 0), a2, voffA);
;             PG8_BAR; PG8_WAIT_L(0); PG8_MMA(1, 0, At, B0); PG8_BAR; PG8_SCHED;
.LBB0_2403:
	s_add_u32 s14, s12, 0x100
	s_addc_u32 s15, s13, 0
	s_add_i32 s0, 0, 0x10000
	v_add_u32_e32 v156, s0, v141
	ds_read_b128 v[144:147], v156
	ds_read_b128 v[148:151], v156 offset:1024
	ds_read_b128 v[152:155], v156 offset:2048
	ds_read_b128 v[156:159], v156 offset:3072
	s_cmp_eq_u32 s41, 2
	s_cselect_b32 s19, s7, s15
	s_cselect_b32 s18, s6, s14
	s_cselect_b32 s17, s9, s40
	s_cselect_b32 s16, s8, s39
	v_lshl_add_u64 v[176:177], s[12:13], 0, v[136:137]
	s_add_i32 m0, s26, 0xc000
	ds_read_b128 v[160:163], v143
	ds_read_b128 v[164:167], v143 offset:1024
	ds_read_b128 v[168:171], v143 offset:2048
	ds_read_b128 v[172:175], v143 offset:3072
	ds_read_b128 v[190:193], v143 offset:4096
	ds_read_b128 v[194:197], v143 offset:5120
	ds_read_b128 v[198:201], v143 offset:6144
	ds_read_b128 v[202:205], v143 offset:7168
	global_load_lds_dwordx4 v[176:177], off
	s_add_i32 m0, s26, 0xe000
	v_lshl_add_u64 v[176:177], s[12:13], 0, v[138:139]
	global_load_lds_dwordx4 v[176:177], off
	s_waitcnt lgkmcnt(8)
	s_barrier
	s_waitcnt lgkmcnt(0)
	v_mfma_f32_16x16x32_bf16 v[126:129], v[144:147], v[160:163], v[126:129]
	v_mfma_f32_16x16x32_bf16 v[122:125], v[152:155], v[160:163], v[122:125]
	v_mfma_f32_16x16x32_bf16 v[118:121], v[144:147], v[168:171], v[118:121]
	v_mfma_f32_16x16x32_bf16 v[114:117], v[152:155], v[168:171], v[114:117]
	v_mfma_f32_16x16x32_bf16 v[110:113], v[144:147], v[190:193], v[110:113]
	v_mfma_f32_16x16x32_bf16 v[106:109], v[152:155], v[190:193], v[106:109]
	v_mfma_f32_16x16x32_bf16 v[102:105], v[144:147], v[198:201], v[102:105]
	v_mfma_f32_16x16x32_bf16 v[98:101], v[152:155], v[198:201], v[98:101]
	v_mfma_f32_16x16x32_bf16 v[126:129], v[148:151], v[164:167], v[126:129]
	v_mfma_f32_16x16x32_bf16 v[122:125], v[156:159], v[164:167], v[122:125]
	v_mfma_f32_16x16x32_bf16 v[118:121], v[148:151], v[172:175], v[118:121]
	v_mfma_f32_16x16x32_bf16 v[114:117], v[156:159], v[172:175], v[114:117]
	v_mfma_f32_16x16x32_bf16 v[110:113], v[148:151], v[194:197], v[110:113]
	v_mfma_f32_16x16x32_bf16 v[106:109], v[156:159], v[194:197], v[106:109]
	v_mfma_f32_16x16x32_bf16 v[102:105], v[148:151], v[202:205], v[102:105]
	v_mfma_f32_16x16x32_bf16 v[98:101], v[156:159], v[202:205], v[98:101]
	s_barrier
	s_add_i32 s1, 0, 0x14000
	v_add_u32_e32 v176, s1, v141
	s_add_i32 s0, s0, s25
	ds_read_b128 v[206:209], v176
	ds_read_b128 v[210:213], v176 offset:1024
	ds_read_b128 v[214:217], v176 offset:2048
	ds_read_b128 v[218:221], v176 offset:3072
	v_lshl_add_u64 v[176:177], s[16:17], 0, v[4:5]
	s_mov_b32 m0, s0
	v_lshl_add_u64 v[186:187], s[16:17], 0, v[130:131]
	global_load_lds_dwordx4 v[176:177], off
	s_add_i32 m0, s0, 0x2000
	s_nop 0
	global_load_lds_dwordx4 v[186:187], off
	s_barrier
	s_waitcnt lgkmcnt(0)
	v_mfma_f32_16x16x32_bf16 v[74:77], v[206:209], v[160:163], v[74:77]
	v_mfma_f32_16x16x32_bf16 v[66:69], v[214:217], v[160:163], v[66:69]
	v_mfma_f32_16x16x32_bf16 v[58:61], v[206:209], v[168:171], v[58:61]
	v_mfma_f32_16x16x32_bf16 v[50:53], v[214:217], v[168:171], v[50:53]
	v_mfma_f32_16x16x32_bf16 v[46:49], v[206:209], v[190:193], v[46:49]
	v_mfma_f32_16x16x32_bf16 v[42:45], v[214:217], v[190:193], v[42:45]
	v_mfma_f32_16x16x32_bf16 v[38:41], v[206:209], v[198:201], v[38:41]
	v_mfma_f32_16x16x32_bf16 v[34:37], v[214:217], v[198:201], v[34:37]
	v_mfma_f32_16x16x32_bf16 v[74:77], v[210:213], v[164:167], v[74:77]
	v_mfma_f32_16x16x32_bf16 v[66:69], v[218:221], v[164:167], v[66:69]
	v_mfma_f32_16x16x32_bf16 v[58:61], v[210:213], v[172:175], v[58:61]
	v_mfma_f32_16x16x32_bf16 v[50:53], v[218:221], v[172:175], v[50:53]
	v_mfma_f32_16x16x32_bf16 v[46:49], v[210:213], v[194:197], v[46:49]
	v_mfma_f32_16x16x32_bf16 v[42:45], v[218:221], v[194:197], v[42:45]
	v_mfma_f32_16x16x32_bf16 v[38:41], v[210:213], v[202:205], v[38:41]
	v_mfma_f32_16x16x32_bf16 v[34:37], v[218:221], v[202:205], v[34:37]
	s_mov_b32 m0, s26
	v_lshl_add_u64 v[222:223], s[18:19], 0, v[134:135]
	s_barrier
	ds_read_b128 v[160:163], v143 offset:16384
	ds_read_b128 v[164:167], v143 offset:17408
	ds_read_b128 v[168:171], v143 offset:18432
	ds_read_b128 v[172:175], v143 offset:19456
	ds_read_b128 v[190:193], v143 offset:20480
	ds_read_b128 v[194:197], v143 offset:21504
	ds_read_b128 v[198:201], v143 offset:22528
	ds_read_b128 v[202:205], v143 offset:23552
	global_load_lds_dwordx4 v[222:223], off
	s_mov_b32 m0, s27
	v_lshl_add_u64 v[224:225], s[18:19], 0, v[132:133]
	global_load_lds_dwordx4 v[224:225], off
	s_barrier
	s_waitcnt lgkmcnt(0)
	v_mfma_f32_16x16x32_bf16 v[94:97], v[144:147], v[160:163], v[94:97]
	v_mfma_f32_16x16x32_bf16 v[90:93], v[152:155], v[160:163], v[90:93]
	v_mfma_f32_16x16x32_bf16 v[86:89], v[144:147], v[168:171], v[86:89]
	v_mfma_f32_16x16x32_bf16 v[82:85], v[152:155], v[168:171], v[82:85]
	v_mfma_f32_16x16x32_bf16 v[78:81], v[144:147], v[190:193], v[78:81]
	v_mfma_f32_16x16x32_bf16 v[70:73], v[152:155], v[190:193], v[70:73]
	v_mfma_f32_16x16x32_bf16 v[62:65], v[144:147], v[198:201], v[62:65]
	v_mfma_f32_16x16x32_bf16 v[54:57], v[152:155], v[198:201], v[54:57]
	v_mfma_f32_16x16x32_bf16 v[94:97], v[148:151], v[164:167], v[94:97]
	v_mfma_f32_16x16x32_bf16 v[90:93], v[156:159], v[164:167], v[90:93]
	v_mfma_f32_16x16x32_bf16 v[86:89], v[148:151], v[172:175], v[86:89]
	v_mfma_f32_16x16x32_bf16 v[82:85], v[156:159], v[172:175], v[82:85]
	v_mfma_f32_16x16x32_bf16 v[78:81], v[148:151], v[194:197], v[78:81]
	v_mfma_f32_16x16x32_bf16 v[70:73], v[156:159], v[194:197], v[70:73]
	v_mfma_f32_16x16x32_bf16 v[62:65], v[148:151], v[202:205], v[62:65]
	v_mfma_f32_16x16x32_bf16 v[54:57], v[156:159], v[202:205], v[54:57]
	s_barrier
; #define PG8_STAGE(bufoff, gbase, voff) do { _Pragma("unroll") for (int _i = 0; _i < 2; ++_i) \
;         __builtin_amdgcn_global_load_lds((const unsigned*)((const char*)(gbase) + (voff)[_i]), (LAS unsigned*)(lds + (bufoff) + ldsw + _i * 8192), 16, 0, 0); } while (0)
; #define PG8_LDA(dst, b, h) do { _Pragma("unroll") for (int m = 0; m < 4; ++m) _Pragma("unroll") for (int k = 0; k < 2; ++k) dst[m][k] = *(const LAS bf16x8*)(lds + PG8_SA(b, h) + aoff + m * 2048 + k * 1024); } while (0)
; #define PG8_LDB(dst, b, h) do { _Pragma("unroll") for (int n = 0; n < 2; ++n) _Pragma("unroll") for (int k = 0; k < 2; ++k) dst[n][k] = *(const LAS bf16x8*)(lds + PG8_SB(b, h) + boff + n * 2048 + k * 1024); } while (0)
; #define PG8_MMA(ai, bj, At, Bt) do { __builtin_amdgcn_s_setprio(1); _Pragma("unroll") for (int m = 0; m < 4; ++m) _Pragma("unroll") for (int n = 0; n < 2; ++n) _Pragma("unroll") for (int k = 0; k < 2; ++k) \
;         acc[ai][bj][m][n] = __builtin_amdgcn_mfma_f32_16x16x32_bf16(Bt[n][k], At[m][k], acc[ai][bj][m][n], 0, 0, 0); __builtin_amdgcn_s_setprio(0); } while (0)
; #define PG8_WAIT_V(n) asm volatile("s_waitcnt vmcnt(" #n ")" ::: "memory")
; #define PG8_WAIT_L(n) asm volatile("s_waitcnt lgkmcnt(" #n ")" ::: "memory")
; #define PG8_BAR __builtin_amdgcn_s_barrier()
; #define PG8_SCHED __builtin_amdgcn_sched_barrier(0)
; template <class Epi>
; __device__ __forceinline__ void gemm_phase(LAS unsigned char* lds, const Gemm g, const StaticOrder& S, const Epi& E) {
;     ...
;             PG8_STAGE(PG8_SB(0, 1), b2 + hstep, voffB);
;             PG8_WAIT_V(6); PG8_BAR; PG8_MMA(1, 1, At, B1); PG8_BAR;
;             PG8_LDB(B0, 1, 0); PG8_SCHED; PG8_LDA(At, 1, 0); PG8_STAGE(PG8_SA(0, 1), a2 + hstep, voffA);
;             PG8_WAIT_L(8); PG8_BAR; PG8_WAIT_L(0); PG8_MMA(0, 0, At, B0); PG8_BAR; PG8_SCHED;
;             PG8_LDB(B1, 1, 1); PG8_STAGE(PG8_SB(1, 0), b3, voffB);
;             PG8_BAR; PG8_WAIT_L(0); PG8_MMA(0, 1, At, B1); PG8_BAR;
;             PG8_LDA(At, 1, 1); PG8_STAGE(PG8_SA(1, 0), a3, voffA);
;             PG8_BAR; PG8_WAIT_L(0); PG8_MMA(1, 0, At, B0); PG8_BAR; PG8_SCHED;
	s_add_u32 s12, s16, 0x18000
	s_addc_u32 s13, s17, 0
	s_add_i32 s0, s1, s25
	s_mov_b32 m0, s0
	v_lshl_add_u64 v[144:145], s[12:13], 0, v[4:5]
	global_load_lds_dwordx4 v[144:145], off
	s_add_i32 m0, s0, 0x2000
	v_lshl_add_u64 v[144:145], s[12:13], 0, v[130:131]
	global_load_lds_dwordx4 v[144:145], off
	s_waitcnt vmcnt(6)
	s_barrier
	v_mfma_f32_16x16x32_bf16 v[30:33], v[206:209], v[160:163], v[30:33]
	v_mfma_f32_16x16x32_bf16 v[26:29], v[214:217], v[160:163], v[26:29]
	v_mfma_f32_16x16x32_bf16 v[22:25], v[206:209], v[168:171], v[22:25]
	v_mfma_f32_16x16x32_bf16 v[18:21], v[214:217], v[168:171], v[18:21]
	v_mfma_f32_16x16x32_bf16 v[14:17], v[206:209], v[190:193], v[14:17]
	v_mfma_f32_16x16x32_bf16 v[10:13], v[214:217], v[190:193], v[10:13]
	v_mfma_f32_16x16x32_bf16 v[6:9], v[206:209], v[198:201], v[6:9]
	v_mfma_f32_16x16x32_bf16 v[0:3], v[214:217], v[198:201], v[0:3]
	v_mfma_f32_16x16x32_bf16 v[30:33], v[210:213], v[164:167], v[30:33]
	v_mfma_f32_16x16x32_bf16 v[26:29], v[218:221], v[164:167], v[26:29]
	v_mfma_f32_16x16x32_bf16 v[22:25], v[210:213], v[172:175], v[22:25]
	v_mfma_f32_16x16x32_bf16 v[18:21], v[218:221], v[172:175], v[18:21]
	v_mfma_f32_16x16x32_bf16 v[14:17], v[210:213], v[194:197], v[14:17]
	v_mfma_f32_16x16x32_bf16 v[10:13], v[218:221], v[194:197], v[10:13]
	v_mfma_f32_16x16x32_bf16 v[6:9], v[210:213], v[202:205], v[6:9]
	v_mfma_f32_16x16x32_bf16 v[0:3], v[218:221], v[202:205], v[0:3]
	s_add_i32 s0, 0, 0x18000
	v_add_u32_e32 v156, s0, v141
	s_barrier
	ds_read_b128 v[144:147], v156
	ds_read_b128 v[148:151], v156 offset:1024
	ds_read_b128 v[152:155], v156 offset:2048
	ds_read_b128 v[156:159], v156 offset:3072
	s_add_u32 s12, s18, 0x18000
	s_addc_u32 s13, s19, 0
	s_mov_b32 m0, s28
	v_lshl_add_u64 v[206:207], s[12:13], 0, v[134:135]
	ds_read_b128 v[160:163], v143 offset:32768
	ds_read_b128 v[164:167], v143 offset:33792
	ds_read_b128 v[168:171], v143 offset:34816
	ds_read_b128 v[172:175], v143 offset:35840
	ds_read_b128 v[190:193], v143 offset:36864
	ds_read_b128 v[194:197], v143 offset:37888
	ds_read_b128 v[198:201], v143 offset:38912
	ds_read_b128 v[202:205], v143 offset:39936
	global_load_lds_dwordx4 v[206:207], off
	s_mov_b32 m0, s29
	v_lshl_add_u64 v[206:207], s[12:13], 0, v[132:133]
	global_load_lds_dwordx4 v[206:207], off
	s_waitcnt lgkmcnt(8)
	s_barrier
	s_waitcnt lgkmcnt(0)
	v_mfma_f32_16x16x32_bf16 v[126:129], v[144:147], v[160:163], v[126:129]
	v_mfma_f32_16x16x32_bf16 v[122:125], v[152:155], v[160:163], v[122:125]
	v_mfma_f32_16x16x32_bf16 v[118:121], v[144:147], v[168:171], v[118:121]
	v_mfma_f32_16x16x32_bf16 v[114:117], v[152:155], v[168:171], v[114:117]
	v_mfma_f32_16x16x32_bf16 v[110:113], v[144:147], v[190:193], v[110:113]
	v_mfma_f32_16x16x32_bf16 v[106:109], v[152:155], v[190:193], v[106:109]
	v_mfma_f32_16x16x32_bf16 v[102:105], v[144:147], v[198:201], v[102:105]
	v_mfma_f32_16x16x32_bf16 v[98:101], v[152:155], v[198:201], v[98:101]
	v_mfma_f32_16x16x32_bf16 v[126:129], v[148:151], v[164:167], v[126:129]
	v_mfma_f32_16x16x32_bf16 v[122:125], v[156:159], v[164:167], v[122:125]
	v_mfma_f32_16x16x32_bf16 v[118:121], v[148:151], v[172:175], v[118:121]
	v_mfma_f32_16x16x32_bf16 v[114:117], v[156:159], v[172:175], v[114:117]
	v_mfma_f32_16x16x32_bf16 v[110:113], v[148:151], v[194:197], v[110:113]
	v_mfma_f32_16x16x32_bf16 v[106:109], v[156:159], v[194:197], v[106:109]
	v_mfma_f32_16x16x32_bf16 v[102:105], v[148:151], v[202:205], v[102:105]
	v_mfma_f32_16x16x32_bf16 v[98:101], v[156:159], v[202:205], v[98:101]
	s_barrier
	s_add_i32 s1, 0, 0x1c000
	s_add_i32 s0, s0, s25
	v_add_u32_e32 v218, s1, v141
	v_lshl_add_u64 v[176:177], v[176:177], 0, s[86:87]
	s_mov_b32 m0, s0
	ds_read_b128 v[206:209], v218
	ds_read_b128 v[210:213], v218 offset:1024
	ds_read_b128 v[214:217], v218 offset:2048
	ds_read_b128 v[218:221], v218 offset:3072
	global_load_lds_dwordx4 v[176:177], off
	s_add_i32 m0, s0, 0x2000
	v_lshl_add_u64 v[176:177], v[186:187], 0, s[86:87]
	global_load_lds_dwordx4 v[176:177], off
	s_barrier
	s_waitcnt lgkmcnt(0)
	v_mfma_f32_16x16x32_bf16 v[74:77], v[206:209], v[160:163], v[74:77]
	v_mfma_f32_16x16x32_bf16 v[66:69], v[214:217], v[160:163], v[66:69]
	v_mfma_f32_16x16x32_bf16 v[58:61], v[206:209], v[168:171], v[58:61]
	v_mfma_f32_16x16x32_bf16 v[50:53], v[214:217], v[168:171], v[50:53]
	v_mfma_f32_16x16x32_bf16 v[46:49], v[206:209], v[190:193], v[46:49]
	v_mfma_f32_16x16x32_bf16 v[42:45], v[214:217], v[190:193], v[42:45]
	v_mfma_f32_16x16x32_bf16 v[38:41], v[206:209], v[198:201], v[38:41]
	v_mfma_f32_16x16x32_bf16 v[34:37], v[214:217], v[198:201], v[34:37]
	v_mfma_f32_16x16x32_bf16 v[74:77], v[210:213], v[164:167], v[74:77]
	v_mfma_f32_16x16x32_bf16 v[66:69], v[218:221], v[164:167], v[66:69]
	v_mfma_f32_16x16x32_bf16 v[58:61], v[210:213], v[172:175], v[58:61]
	v_mfma_f32_16x16x32_bf16 v[50:53], v[218:221], v[172:175], v[50:53]
	v_mfma_f32_16x16x32_bf16 v[46:49], v[210:213], v[194:197], v[46:49]
	v_mfma_f32_16x16x32_bf16 v[42:45], v[218:221], v[194:197], v[42:45]
	v_mfma_f32_16x16x32_bf16 v[38:41], v[210:213], v[202:205], v[38:41]
	v_mfma_f32_16x16x32_bf16 v[34:37], v[218:221], v[202:205], v[34:37]
	s_mov_b32 m0, s30
	v_lshl_add_u64 v[176:177], v[222:223], 0, s[86:87]
	s_barrier
	ds_read_b128 v[160:163], v143 offset:49152
	ds_read_b128 v[164:167], v143 offset:50176
	ds_read_b128 v[168:171], v143 offset:51200
	ds_read_b128 v[172:175], v143 offset:52224
	ds_read_b128 v[190:193], v143 offset:53248
	ds_read_b128 v[194:197], v143 offset:54272
	ds_read_b128 v[198:201], v143 offset:55296
	ds_read_b128 v[202:205], v143 offset:56320
	global_load_lds_dwordx4 v[176:177], off
	s_mov_b32 m0, s31
	v_lshl_add_u64 v[176:177], v[224:225], 0, s[86:87]
	global_load_lds_dwordx4 v[176:177], off
	s_barrier
; __device__ __forceinline__ unsigned cvt_pk_bf16(float lo, float hi) { unsigned r; asm volatile("s_nop 0\n\tv_cvt_pk_bf16_f32 %0, %1, %2" : "=v"(r) : "v"(lo), "v"(hi)); return r; }
; #define PG8_STAGE(bufoff, gbase, voff) do { _Pragma("unroll") for (int _i = 0; _i < 2; ++_i) \
;         __builtin_amdgcn_global_load_lds((const unsigned*)((const char*)(gbase) + (voff)[_i]), (LAS unsigned*)(lds + (bufoff) + ldsw + _i * 8192), 16, 0, 0); } while (0)
; #define PG8_MMA(ai, bj, At, Bt) do { __builtin_amdgcn_s_setprio(1); _Pragma("unroll") for (int m = 0; m < 4; ++m) _Pragma("unroll") for (int n = 0; n < 2; ++n) _Pragma("unroll") for (int k = 0; k < 2; ++k) \
;         acc[ai][bj][m][n] = __builtin_amdgcn_mfma_f32_16x16x32_bf16(Bt[n][k], At[m][k], acc[ai][bj][m][n], 0, 0, 0); __builtin_amdgcn_s_setprio(0); } while (0)
; #define PG8_WAIT_V(n) asm volatile("s_waitcnt vmcnt(" #n ")" ::: "memory")
; #define PG8_BAR __builtin_amdgcn_s_barrier()
; template <class Epi>
; __device__ __forceinline__ void gemm_phase(LAS unsigned char* lds, const Gemm g, const StaticOrder& S, const Epi& E) {
;     ...
;             PG8_STAGE(PG8_SB(1, 1), b3 + hstep, voffB);
;             PG8_WAIT_V(6); PG8_BAR; PG8_MMA(1, 1, At, B1); PG8_BAR;
;     __device__ __forceinline__ void operator()(const f32x4 (&acc)[2][2][4][2], const Unit& u, int wr, int wc, int fr, int fq) const {
;     ...
;         for (int bj = 0; bj < 2; ++bj) {
;             const f32x4 s0 = swv[2 * bj], s1 = swv[2 * bj + 1];
; #pragma unroll
;             for (int ai = 0; ai < 2; ++ai)
; #pragma unroll
;                 for (int m = 0; m < 4; ++m) { const int r = row0 + ai * 128 + m * 16;
;                     const float rstd = ai ? rb[m] : ra[m];
;                     const f32x4 v0 = acc[ai][bj][m][0] * rstd + s0, v1 = acc[ai][bj][m][1] * rstd + s1;
;                     uint4 st; st.x = cvt_pk_bf16(v0[0], v0[1]); st.y = cvt_pk_bf16(v0[2], v0[3]); st.z = cvt_pk_bf16(v1[0], v1[1]); st.w = cvt_pk_bf16(v1[2], v1[3]);
;                     *(uint4*)(O + (size_t)r * ldc + col0 + bj * 128) = st; }
	s_waitcnt lgkmcnt(0)
	v_mfma_f32_16x16x32_bf16 v[94:97], v[144:147], v[160:163], v[94:97]
	v_mfma_f32_16x16x32_bf16 v[90:93], v[152:155], v[160:163], v[90:93]
	v_mfma_f32_16x16x32_bf16 v[86:89], v[144:147], v[168:171], v[86:89]
	v_mfma_f32_16x16x32_bf16 v[82:85], v[152:155], v[168:171], v[82:85]
	v_mfma_f32_16x16x32_bf16 v[78:81], v[144:147], v[190:193], v[78:81]
	v_mfma_f32_16x16x32_bf16 v[70:73], v[152:155], v[190:193], v[70:73]
	v_mfma_f32_16x16x32_bf16 v[62:65], v[144:147], v[198:201], v[62:65]
	v_mfma_f32_16x16x32_bf16 v[54:57], v[152:155], v[198:201], v[54:57]
	v_mfma_f32_16x16x32_bf16 v[94:97], v[148:151], v[164:167], v[94:97]
	v_mfma_f32_16x16x32_bf16 v[90:93], v[156:159], v[164:167], v[90:93]
	v_mfma_f32_16x16x32_bf16 v[86:89], v[148:151], v[172:175], v[86:89]
	v_mfma_f32_16x16x32_bf16 v[82:85], v[156:159], v[172:175], v[82:85]
	v_mfma_f32_16x16x32_bf16 v[78:81], v[148:151], v[194:197], v[78:81]
	v_mfma_f32_16x16x32_bf16 v[70:73], v[156:159], v[194:197], v[70:73]
	v_mfma_f32_16x16x32_bf16 v[62:65], v[148:151], v[202:205], v[62:65]
	v_mfma_f32_16x16x32_bf16 v[54:57], v[156:159], v[202:205], v[54:57]
	s_barrier
	s_add_u32 s12, s16, 0x18080
	s_addc_u32 s13, s17, 0
	s_add_i32 s0, s1, s25
	s_mov_b32 m0, s0
	v_lshl_add_u64 v[144:145], s[12:13], 0, v[4:5]
	global_load_lds_dwordx4 v[144:145], off
	s_add_i32 m0, s0, 0x2000
	v_lshl_add_u64 v[144:145], s[12:13], 0, v[130:131]
	global_load_lds_dwordx4 v[144:145], off
	s_waitcnt vmcnt(6)
	s_barrier
	v_mfma_f32_16x16x32_bf16 v[30:33], v[206:209], v[160:163], v[30:33]
	v_mfma_f32_16x16x32_bf16 v[26:29], v[214:217], v[160:163], v[26:29]
	v_mfma_f32_16x16x32_bf16 v[22:25], v[206:209], v[168:171], v[22:25]
	v_mfma_f32_16x16x32_bf16 v[18:21], v[214:217], v[168:171], v[18:21]
	v_mfma_f32_16x16x32_bf16 v[14:17], v[206:209], v[190:193], v[14:17]
	v_mfma_f32_16x16x32_bf16 v[10:13], v[214:217], v[190:193], v[10:13]
	v_mfma_f32_16x16x32_bf16 v[6:9], v[206:209], v[198:201], v[6:9]
	v_mfma_f32_16x16x32_bf16 v[0:3], v[214:217], v[198:201], v[0:3]
	v_mfma_f32_16x16x32_bf16 v[30:33], v[210:213], v[164:167], v[30:33]
	v_mfma_f32_16x16x32_bf16 v[26:29], v[218:221], v[164:167], v[26:29]
	v_mfma_f32_16x16x32_bf16 v[22:25], v[210:213], v[172:175], v[22:25]
	v_mfma_f32_16x16x32_bf16 v[18:21], v[218:221], v[172:175], v[18:21]
	v_mfma_f32_16x16x32_bf16 v[14:17], v[210:213], v[194:197], v[14:17]
	v_mfma_f32_16x16x32_bf16 v[10:13], v[218:221], v[194:197], v[10:13]
	v_mfma_f32_16x16x32_bf16 v[6:9], v[210:213], v[202:205], v[6:9]
	v_mfma_f32_16x16x32_bf16 v[0:3], v[218:221], v[202:205], v[0:3]
	s_add_i32 s41, s41, 2
	s_add_u32 s39, s39, 0x100
	s_addc_u32 s40, s40, 0
	s_cmp_gt_u32 s41, 3
	s_mov_b64 s[12:13], s[14:15]
	s_barrier
	s_cbranch_scc0 .LBB0_2403
	v_lshl_or_b32 v144, s37, 8, v142
	v_pk_add_f32 v[126:127], v[126:127], 0 op_sel_hi:[1,0]
	v_lshl_add_u32 v148, s38, 8, v140
	v_ashrrev_i32_e32 v145, 31, v144
	v_pk_add_f32 v[128:129], v[128:129], 0 op_sel_hi:[1,0]
	v_pk_add_f32 v[146:147], v[124:125], 0 op_sel_hi:[1,0]
	v_pk_add_f32 v[124:125], v[122:123], 0 op_sel_hi:[1,0]
	s_nop 0
	v_cvt_pk_bf16_f32 v122, v126, v127
	v_mov_b64_e32 v[126:127], s[10:11]
	s_nop 0
	v_cvt_pk_bf16_f32 v123, v128, v129
	v_mad_i64_i32 v[128:129], s[12:13], v148, s83, v[126:127]
	v_lshlrev_b64 v[144:145], 1, v[144:145]
	s_nop 0
	v_cvt_pk_bf16_f32 v124, v124, v125
	v_lshl_add_u64 v[128:129], v[128:129], 0, v[144:145]
	s_nop 0
	v_cvt_pk_bf16_f32 v125, v146, v147
	global_store_dwordx4 v[128:129], v[122:125], off
	v_pk_add_f32 v[118:119], v[118:119], 0 op_sel_hi:[1,0]
	v_pk_add_f32 v[120:121], v[120:121], 0 op_sel_hi:[1,0]
	v_or_b32_e32 v124, 16, v148
	v_pk_add_f32 v[122:123], v[116:117], 0 op_sel_hi:[1,0]
	v_pk_add_f32 v[116:117], v[114:115], 0 op_sel_hi:[1,0]
	s_nop 0
	v_cvt_pk_bf16_f32 v114, v118, v119
	v_mad_i64_i32 v[118:119], s[12:13], v124, s83, v[126:127]
	s_nop 0
	v_cvt_pk_bf16_f32 v115, v120, v121
	s_nop 0
	v_cvt_pk_bf16_f32 v116, v116, v117
	v_lshl_add_u64 v[118:119], v[118:119], 0, v[144:145]
	s_nop 0
	v_cvt_pk_bf16_f32 v117, v122, v123
	global_store_dwordx4 v[118:119], v[114:117], off
	v_pk_add_f32 v[110:111], v[110:111], 0 op_sel_hi:[1,0]
	v_pk_add_f32 v[112:113], v[112:113], 0 op_sel_hi:[1,0]
	v_or_b32_e32 v116, 32, v148
	v_pk_add_f32 v[114:115], v[108:109], 0 op_sel_hi:[1,0]
	v_pk_add_f32 v[108:109], v[106:107], 0 op_sel_hi:[1,0]
	s_nop 0
	v_cvt_pk_bf16_f32 v106, v110, v111
	v_mad_i64_i32 v[110:111], s[12:13], v116, s83, v[126:127]
	s_nop 0
	v_cvt_pk_bf16_f32 v107, v112, v113
	s_nop 0
	v_cvt_pk_bf16_f32 v108, v108, v109
	v_lshl_add_u64 v[110:111], v[110:111], 0, v[144:145]
	s_nop 0
	v_cvt_pk_bf16_f32 v109, v114, v115
	global_store_dwordx4 v[110:111], v[106:109], off
	v_pk_add_f32 v[102:103], v[102:103], 0 op_sel_hi:[1,0]
	v_pk_add_f32 v[104:105], v[104:105], 0 op_sel_hi:[1,0]
	v_or_b32_e32 v108, 48, v148
	v_pk_add_f32 v[106:107], v[100:101], 0 op_sel_hi:[1,0]
	v_pk_add_f32 v[100:101], v[98:99], 0 op_sel_hi:[1,0]
	s_nop 0
	v_cvt_pk_bf16_f32 v98, v102, v103
	v_mad_i64_i32 v[102:103], s[12:13], v108, s83, v[126:127]
	s_nop 0
	v_cvt_pk_bf16_f32 v99, v104, v105
	s_nop 0
	v_cvt_pk_bf16_f32 v100, v100, v101
	v_lshl_add_u64 v[102:103], v[102:103], 0, v[144:145]
	s_nop 0
	v_cvt_pk_bf16_f32 v101, v106, v107
	global_store_dwordx4 v[102:103], v[98:101], off
	v_pk_add_f32 v[94:95], v[94:95], 0 op_sel_hi:[1,0]
	v_pk_add_f32 v[96:97], v[96:97], 0 op_sel_hi:[1,0]
	v_add_u32_e32 v100, 0x80, v148
	v_pk_add_f32 v[98:99], v[92:93], 0 op_sel_hi:[1,0]
	v_pk_add_f32 v[92:93], v[90:91], 0 op_sel_hi:[1,0]
	s_nop 0
	v_cvt_pk_bf16_f32 v90, v94, v95
	v_mad_i64_i32 v[94:95], s[12:13], v100, s83, v[126:127]
	s_nop 0
; __device__ __forceinline__ unsigned cvt_pk_bf16(float lo, float hi) { unsigned r; asm volatile("s_nop 0\n\tv_cvt_pk_bf16_f32 %0, %1, %2" : "=v"(r) : "v"(lo), "v"(hi)); return r; }
;     __device__ __forceinline__ void operator()(const f32x4 (&acc)[2][2][4][2], const Unit& u, int wr, int wc, int fr, int fq) const {
;     ...
;         for (int bj = 0; bj < 2; ++bj) {
;             const f32x4 s0 = swv[2 * bj], s1 = swv[2 * bj + 1];
; #pragma unroll
;             for (int ai = 0; ai < 2; ++ai)
; #pragma unroll
;                 for (int m = 0; m < 4; ++m) { const int r = row0 + ai * 128 + m * 16;
;                     const float rstd = ai ? rb[m] : ra[m];
;                     const f32x4 v0 = acc[ai][bj][m][0] * rstd + s0, v1 = acc[ai][bj][m][1] * rstd + s1;
;                     uint4 st; st.x = cvt_pk_bf16(v0[0], v0[1]); st.y = cvt_pk_bf16(v0[2], v0[3]); st.z = cvt_pk_bf16(v1[0], v1[1]); st.w = cvt_pk_bf16(v1[2], v1[3]);
;                     *(uint4*)(O + (size_t)r * ldc + col0 + bj * 128) = st; }
	v_cvt_pk_bf16_f32 v91, v96, v97
	s_nop 0
	v_cvt_pk_bf16_f32 v92, v92, v93
	v_lshl_add_u64 v[94:95], v[94:95], 0, v[144:145]
	s_nop 0
	v_cvt_pk_bf16_f32 v93, v98, v99
	global_store_dwordx4 v[94:95], v[90:93], off
	v_pk_add_f32 v[86:87], v[86:87], 0 op_sel_hi:[1,0]
	v_pk_add_f32 v[88:89], v[88:89], 0 op_sel_hi:[1,0]
	v_add_u32_e32 v92, 0x90, v148
	v_pk_add_f32 v[90:91], v[84:85], 0 op_sel_hi:[1,0]
	v_pk_add_f32 v[84:85], v[82:83], 0 op_sel_hi:[1,0]
	s_nop 0
	v_cvt_pk_bf16_f32 v82, v86, v87
	v_mad_i64_i32 v[86:87], s[12:13], v92, s83, v[126:127]
	s_nop 0
	v_cvt_pk_bf16_f32 v83, v88, v89
	s_nop 0
	v_cvt_pk_bf16_f32 v84, v84, v85
	v_lshl_add_u64 v[86:87], v[86:87], 0, v[144:145]
	s_nop 0
	v_cvt_pk_bf16_f32 v85, v90, v91
	global_store_dwordx4 v[86:87], v[82:85], off
	v_pk_add_f32 v[78:79], v[78:79], 0 op_sel_hi:[1,0]
	v_pk_add_f32 v[80:81], v[80:81], 0 op_sel_hi:[1,0]
	v_add_u32_e32 v84, 0xa0, v148
	v_pk_add_f32 v[82:83], v[72:73], 0 op_sel_hi:[1,0]
	v_pk_add_f32 v[72:73], v[70:71], 0 op_sel_hi:[1,0]
	s_nop 0
	v_cvt_pk_bf16_f32 v70, v78, v79
	v_mad_i64_i32 v[78:79], s[12:13], v84, s83, v[126:127]
	s_nop 0
	v_cvt_pk_bf16_f32 v71, v80, v81
	s_nop 0
	v_cvt_pk_bf16_f32 v72, v72, v73
	v_lshl_add_u64 v[78:79], v[78:79], 0, v[144:145]
	s_nop 0
	v_cvt_pk_bf16_f32 v73, v82, v83
	global_store_dwordx4 v[78:79], v[70:73], off
	v_pk_add_f32 v[62:63], v[62:63], 0 op_sel_hi:[1,0]
	v_pk_add_f32 v[64:65], v[64:65], 0 op_sel_hi:[1,0]
	v_add_u32_e32 v72, 0xb0, v148
	v_pk_add_f32 v[70:71], v[56:57], 0 op_sel_hi:[1,0]
	v_pk_add_f32 v[56:57], v[54:55], 0 op_sel_hi:[1,0]
	s_nop 0
	v_cvt_pk_bf16_f32 v54, v62, v63
	v_mad_i64_i32 v[62:63], s[12:13], v72, s83, v[126:127]
	s_nop 0
	v_cvt_pk_bf16_f32 v55, v64, v65
	s_nop 0
	v_cvt_pk_bf16_f32 v56, v56, v57
	s_nop 0
	v_cvt_pk_bf16_f32 v57, v70, v71
	v_lshl_add_u64 v[62:63], v[62:63], 0, v[144:145]
	global_store_dwordx4 v[62:63], v[54:57], off
	v_pk_add_f32 v[64:65], v[68:69], 0 op_sel_hi:[1,0]
	v_pk_add_f32 v[66:67], v[66:67], 0 op_sel_hi:[1,0]
	v_pk_add_f32 v[56:57], v[76:77], 0 op_sel_hi:[1,0]
	v_pk_add_f32 v[54:55], v[74:75], 0 op_sel_hi:[1,0]
	v_pk_add_f32 v[48:49], v[48:49], 0 op_sel_hi:[1,0]
	s_nop 0
	v_cvt_pk_bf16_f32 v54, v54, v55
	s_nop 0
	v_cvt_pk_bf16_f32 v55, v56, v57
	s_nop 0
	v_cvt_pk_bf16_f32 v56, v66, v67
	s_nop 0
	v_cvt_pk_bf16_f32 v57, v64, v65
	global_store_dwordx4 v[128:129], v[54:57], off offset:256
	v_pk_add_f32 v[46:47], v[46:47], 0 op_sel_hi:[1,0]
	v_pk_add_f32 v[40:41], v[40:41], 0 op_sel_hi:[1,0]
	v_pk_add_f32 v[54:55], v[60:61], 0 op_sel_hi:[1,0]
	v_pk_add_f32 v[56:57], v[58:59], 0 op_sel_hi:[1,0]
	v_pk_add_f32 v[58:59], v[52:53], 0 op_sel_hi:[1,0]
	v_pk_add_f32 v[52:53], v[50:51], 0 op_sel_hi:[1,0]
	s_nop 0
	v_cvt_pk_bf16_f32 v50, v56, v57
	s_nop 0
	v_cvt_pk_bf16_f32 v51, v54, v55
	v_pk_add_f32 v[38:39], v[38:39], 0 op_sel_hi:[1,0]
	s_nop 0
	v_cvt_pk_bf16_f32 v52, v52, v53
	s_nop 0
	v_cvt_pk_bf16_f32 v53, v58, v59
	global_store_dwordx4 v[118:119], v[50:53], off offset:256
	v_pk_add_f32 v[32:33], v[32:33], 0 op_sel_hi:[1,0]
	v_pk_add_f32 v[30:31], v[30:31], 0 op_sel_hi:[1,0]
	v_pk_add_f32 v[50:51], v[44:45], 0 op_sel_hi:[1,0]
	v_pk_add_f32 v[44:45], v[42:43], 0 op_sel_hi:[1,0]
	s_nop 0
	v_cvt_pk_bf16_f32 v42, v46, v47
	s_nop 0
	v_cvt_pk_bf16_f32 v43, v48, v49
	v_pk_add_f32 v[24:25], v[24:25], 0 op_sel_hi:[1,0]
	s_nop 0
	v_cvt_pk_bf16_f32 v44, v44, v45
	s_nop 0
	v_cvt_pk_bf16_f32 v45, v50, v51
	global_store_dwordx4 v[110:111], v[42:45], off offset:256
	v_pk_add_f32 v[22:23], v[22:23], 0 op_sel_hi:[1,0]
	v_pk_add_f32 v[16:17], v[16:17], 0 op_sel_hi:[1,0]
	v_pk_add_f32 v[42:43], v[36:37], 0 op_sel_hi:[1,0]
	v_pk_add_f32 v[36:37], v[34:35], 0 op_sel_hi:[1,0]
	s_nop 0
	v_cvt_pk_bf16_f32 v34, v38, v39
	s_nop 0
	v_cvt_pk_bf16_f32 v35, v40, v41
	v_pk_add_f32 v[14:15], v[14:15], 0 op_sel_hi:[1,0]
	s_nop 0
	v_cvt_pk_bf16_f32 v36, v36, v37
	s_nop 0
	v_cvt_pk_bf16_f32 v37, v42, v43
	global_store_dwordx4 v[102:103], v[34:37], off offset:256
	s_and_b64 vcc, exec, s[4:5]
	s_mov_b32 s37, s35
	v_pk_add_f32 v[34:35], v[28:29], 0 op_sel_hi:[1,0]
	v_pk_add_f32 v[28:29], v[26:27], 0 op_sel_hi:[1,0]
	s_nop 0
	v_cvt_pk_bf16_f32 v26, v30, v31
	s_nop 0
	v_cvt_pk_bf16_f32 v27, v32, v33
	s_mov_b32 s38, s36
	s_nop 0
	v_cvt_pk_bf16_f32 v28, v28, v29
	s_nop 0
	v_cvt_pk_bf16_f32 v29, v34, v35
	global_store_dwordx4 v[94:95], v[26:29], off offset:256
	s_mov_b64 s[14:15], s[8:9]
	s_mov_b64 s[12:13], s[6:7]
	v_pk_add_f32 v[26:27], v[20:21], 0 op_sel_hi:[1,0]
	v_pk_add_f32 v[20:21], v[18:19], 0 op_sel_hi:[1,0]
	s_nop 0
	v_cvt_pk_bf16_f32 v18, v22, v23
	s_nop 0
	v_cvt_pk_bf16_f32 v19, v24, v25
	v_pk_add_f32 v[8:9], v[8:9], 0 op_sel_hi:[1,0]
	s_nop 0
	v_cvt_pk_bf16_f32 v20, v20, v21
	s_nop 0
	v_cvt_pk_bf16_f32 v21, v26, v27
	global_store_dwordx4 v[86:87], v[18:21], off offset:256
	v_pk_add_f32 v[6:7], v[6:7], 0 op_sel_hi:[1,0]
	s_nop 0
	v_pk_add_f32 v[18:19], v[12:13], 0 op_sel_hi:[1,0]
	v_pk_add_f32 v[12:13], v[10:11], 0 op_sel_hi:[1,0]
	s_nop 0
	v_cvt_pk_bf16_f32 v10, v14, v15
	s_nop 0
	v_cvt_pk_bf16_f32 v11, v16, v17
	s_nop 0
	s_nop 0
	v_cvt_pk_bf16_f32 v12, v12, v13
	s_nop 0
	v_cvt_pk_bf16_f32 v13, v18, v19
	global_store_dwordx4 v[78:79], v[10:13], off offset:256
	s_nop 1
	v_pk_add_f32 v[10:11], v[2:3], 0 op_sel_hi:[1,0]
	v_pk_add_f32 v[2:3], v[0:1], 0 op_sel_hi:[1,0]
	s_nop 0
	v_cvt_pk_bf16_f32 v0, v6, v7
	s_nop 0
	v_cvt_pk_bf16_f32 v1, v8, v9
	s_nop 0
	s_nop 0
	v_cvt_pk_bf16_f32 v2, v2, v3
	s_nop 0
	v_cvt_pk_bf16_f32 v3, v10, v11
	global_store_dwordx4 v[62:63], v[0:3], off offset:256
	s_cbranch_vccz .LBB0_2396
	s_waitcnt vmcnt(0)
	s_cmpk_gt_u32 s20, 0xff
	s_cbranch_scc1 .LBB0_2407
	s_barrier

; #define PG8_STAGE(bufoff, gbase, voff) do { _Pragma("unroll") for (int _i = 0; _i < 2; ++_i) \
;         __builtin_amdgcn_global_load_lds((const unsigned*)((const char*)(gbase) + (voff)[_i]), (LAS unsigned*)(lds + (bufoff) + ldsw + _i * 8192), 16, 0, 0); } while (0)
; #define PG8_LDA(dst, b, h) do { _Pragma("unroll") for (int m = 0; m < 4; ++m) _Pragma("unroll") for (int k = 0; k < 2; ++k) dst[m][k] = *(const LAS bf16x8*)(lds + PG8_SA(b, h) + aoff + m * 2048 + k * 1024); } while (0)
; #define PG8_LDB(dst, b, h) do { _Pragma("unroll") for (int n = 0; n < 2; ++n) _Pragma("unroll") for (int k = 0; k < 2; ++k) dst[n][k] = *(const LAS bf16x8*)(lds + PG8_SB(b, h) + boff + n * 2048 + k * 1024); } while (0)
; #define PG8_MMA(ai, bj, At, Bt) do { __builtin_amdgcn_s_setprio(1); _Pragma("unroll") for (int m = 0; m < 4; ++m) _Pragma("unroll") for (int n = 0; n < 2; ++n) _Pragma("unroll") for (int k = 0; k < 2; ++k) \
;         acc[ai][bj][m][n] = __builtin_amdgcn_mfma_f32_16x16x32_bf16(Bt[n][k], At[m][k], acc[ai][bj][m][n], 0, 0, 0); __builtin_amdgcn_s_setprio(0); } while (0)
; #define PG8_WAIT_L(n) asm volatile("s_waitcnt lgkmcnt(" #n ")" ::: "memory")
; #define PG8_BAR __builtin_amdgcn_s_barrier()
; #define PG8_SCHED __builtin_amdgcn_sched_barrier(0)
; template <class Epi>
; __device__ __forceinline__ void gemm_phase(LAS unsigned char* lds, const Gemm g, const StaticOrder& S, const Epi& E) {
;     ...
;         for (int t = 0; t < nt; t += 2) {
;             const bool last = (t == nt - 2);
;             const char* a1 = cA + (size_t)(t + 1) * kstep;
;             const char* a2 = last ? nA : cA + (size_t)(t + 2) * kstep; const char* b2 = last ? nB : cB + (size_t)(t + 2) * kstep;
;             const char* a3 = a2 + kstep; const char* b3 = b2 + kstep;
;             PG8_LDB(B0, 0, 0); PG8_SCHED; PG8_LDA(At, 0, 0); PG8_STAGE(PG8_SA(1, 1), a1 + hstep, voffA);
;             PG8_WAIT_L(8); PG8_BAR; PG8_WAIT_L(0); PG8_MMA(0, 0, At, B0); PG8_BAR; PG8_SCHED;
;             PG8_LDB(B1, 0, 1); PG8_STAGE(PG8_SB(0, 0), b2, voffB);
;             PG8_BAR; PG8_WAIT_L(0); PG8_MMA(0, 1, At, B1); PG8_BAR;
;             PG8_LDA(At, 0, 1); PG8_STAGE(PG8_SA(0, 0), a2, voffA);
;             PG8_BAR; PG8_WAIT_L(0); PG8_MMA(1, 0, At, B0); PG8_BAR; PG8_SCHED;
.LBB0_2732:
	s_add_u32 s0, s16, 0xfffe0080
	s_addc_u32 s1, s17, -1
	s_add_i32 s48, 0, 0x10000
	v_add_u32_e32 v156, s48, v141
	ds_read_b128 v[144:147], v156
	ds_read_b128 v[148:151], v156 offset:1024
	ds_read_b128 v[152:155], v156 offset:2048
	ds_read_b128 v[156:159], v156 offset:3072
	s_cmp_eq_u32 s43, 4
	s_cselect_b32 s21, s11, s1
	s_cselect_b32 s20, s39, s0
	s_cselect_b32 s19, s9, s42
	s_cselect_b32 s18, s40, s41
	v_lshl_add_u64 v[176:177], s[16:17], 0, v[136:137]
	s_add_i32 m0, s28, 0xc000
	ds_read_b128 v[160:163], v143
	ds_read_b128 v[164:167], v143 offset:1024
	ds_read_b128 v[168:171], v143 offset:2048
	ds_read_b128 v[172:175], v143 offset:3072
	ds_read_b128 v[190:193], v143 offset:4096
	ds_read_b128 v[194:197], v143 offset:5120
	ds_read_b128 v[198:201], v143 offset:6144
	ds_read_b128 v[202:205], v143 offset:7168
	global_load_lds_dwordx4 v[176:177], off
	s_add_i32 m0, s28, 0xe000
	v_lshl_add_u64 v[176:177], s[16:17], 0, v[138:139]
	global_load_lds_dwordx4 v[176:177], off
	s_waitcnt lgkmcnt(8)
	s_barrier
	s_waitcnt lgkmcnt(0)
	v_mfma_f32_16x16x32_bf16 v[126:129], v[144:147], v[160:163], v[126:129]
	v_mfma_f32_16x16x32_bf16 v[122:125], v[152:155], v[160:163], v[122:125]
	v_mfma_f32_16x16x32_bf16 v[118:121], v[144:147], v[168:171], v[118:121]
	v_mfma_f32_16x16x32_bf16 v[114:117], v[152:155], v[168:171], v[114:117]
	v_mfma_f32_16x16x32_bf16 v[110:113], v[144:147], v[190:193], v[110:113]
	v_mfma_f32_16x16x32_bf16 v[106:109], v[152:155], v[190:193], v[106:109]
	v_mfma_f32_16x16x32_bf16 v[102:105], v[144:147], v[198:201], v[102:105]
	v_mfma_f32_16x16x32_bf16 v[98:101], v[152:155], v[198:201], v[98:101]
	v_mfma_f32_16x16x32_bf16 v[126:129], v[148:151], v[164:167], v[126:129]
	v_mfma_f32_16x16x32_bf16 v[122:125], v[156:159], v[164:167], v[122:125]
	v_mfma_f32_16x16x32_bf16 v[118:121], v[148:151], v[172:175], v[118:121]
	v_mfma_f32_16x16x32_bf16 v[114:117], v[156:159], v[172:175], v[114:117]
	v_mfma_f32_16x16x32_bf16 v[110:113], v[148:151], v[194:197], v[110:113]
	v_mfma_f32_16x16x32_bf16 v[106:109], v[156:159], v[194:197], v[106:109]
	v_mfma_f32_16x16x32_bf16 v[102:105], v[148:151], v[202:205], v[102:105]
	v_mfma_f32_16x16x32_bf16 v[98:101], v[156:159], v[202:205], v[98:101]
	s_barrier
	s_add_i32 s49, 0, 0x14000
	v_add_u32_e32 v176, s49, v141
	s_add_i32 s0, s48, s27
	ds_read_b128 v[206:209], v176
	ds_read_b128 v[210:213], v176 offset:1024
	ds_read_b128 v[214:217], v176 offset:2048
	ds_read_b128 v[218:221], v176 offset:3072
	v_lshl_add_u64 v[176:177], s[18:19], 0, v[4:5]
	s_mov_b32 m0, s0
	v_lshl_add_u64 v[186:187], s[18:19], 0, v[130:131]
	global_load_lds_dwordx4 v[176:177], off
	s_add_i32 m0, s0, 0x2000
	s_nop 0
	global_load_lds_dwordx4 v[186:187], off
	s_barrier
	s_waitcnt lgkmcnt(0)
	v_mfma_f32_16x16x32_bf16 v[70:73], v[206:209], v[160:163], v[70:73]
	v_mfma_f32_16x16x32_bf16 v[66:69], v[214:217], v[160:163], v[66:69]
	v_mfma_f32_16x16x32_bf16 v[54:57], v[206:209], v[168:171], v[54:57]
	v_mfma_f32_16x16x32_bf16 v[50:53], v[214:217], v[168:171], v[50:53]
	v_mfma_f32_16x16x32_bf16 v[46:49], v[206:209], v[190:193], v[46:49]
	v_mfma_f32_16x16x32_bf16 v[42:45], v[214:217], v[190:193], v[42:45]
	v_mfma_f32_16x16x32_bf16 v[38:41], v[206:209], v[198:201], v[38:41]
	v_mfma_f32_16x16x32_bf16 v[34:37], v[214:217], v[198:201], v[34:37]
	v_mfma_f32_16x16x32_bf16 v[70:73], v[210:213], v[164:167], v[70:73]
	v_mfma_f32_16x16x32_bf16 v[66:69], v[218:221], v[164:167], v[66:69]
	v_mfma_f32_16x16x32_bf16 v[54:57], v[210:213], v[172:175], v[54:57]
	v_mfma_f32_16x16x32_bf16 v[50:53], v[218:221], v[172:175], v[50:53]
	v_mfma_f32_16x16x32_bf16 v[46:49], v[210:213], v[194:197], v[46:49]
	v_mfma_f32_16x16x32_bf16 v[42:45], v[218:221], v[194:197], v[42:45]
	v_mfma_f32_16x16x32_bf16 v[38:41], v[210:213], v[202:205], v[38:41]
	v_mfma_f32_16x16x32_bf16 v[34:37], v[218:221], v[202:205], v[34:37]
	s_mov_b32 m0, s28
	v_lshl_add_u64 v[222:223], s[20:21], 0, v[134:135]
	s_barrier
	ds_read_b128 v[160:163], v143 offset:16384
	ds_read_b128 v[164:167], v143 offset:17408
	ds_read_b128 v[168:171], v143 offset:18432
	ds_read_b128 v[172:175], v143 offset:19456
	ds_read_b128 v[190:193], v143 offset:20480
	ds_read_b128 v[194:197], v143 offset:21504
	ds_read_b128 v[198:201], v143 offset:22528
	ds_read_b128 v[202:205], v143 offset:23552
	global_load_lds_dwordx4 v[222:223], off
	s_mov_b32 m0, s29
	v_lshl_add_u64 v[224:225], s[20:21], 0, v[132:133]
	global_load_lds_dwordx4 v[224:225], off
	s_barrier
	s_waitcnt lgkmcnt(0)
	v_mfma_f32_16x16x32_bf16 v[94:97], v[144:147], v[160:163], v[94:97]
	v_mfma_f32_16x16x32_bf16 v[90:93], v[152:155], v[160:163], v[90:93]
	v_mfma_f32_16x16x32_bf16 v[86:89], v[144:147], v[168:171], v[86:89]
	v_mfma_f32_16x16x32_bf16 v[82:85], v[152:155], v[168:171], v[82:85]
	v_mfma_f32_16x16x32_bf16 v[78:81], v[144:147], v[190:193], v[78:81]
	v_mfma_f32_16x16x32_bf16 v[74:77], v[152:155], v[190:193], v[74:77]
	v_mfma_f32_16x16x32_bf16 v[62:65], v[144:147], v[198:201], v[62:65]
	v_mfma_f32_16x16x32_bf16 v[58:61], v[152:155], v[198:201], v[58:61]
	v_mfma_f32_16x16x32_bf16 v[94:97], v[148:151], v[164:167], v[94:97]
	v_mfma_f32_16x16x32_bf16 v[90:93], v[156:159], v[164:167], v[90:93]
	v_mfma_f32_16x16x32_bf16 v[86:89], v[148:151], v[172:175], v[86:89]
	v_mfma_f32_16x16x32_bf16 v[82:85], v[156:159], v[172:175], v[82:85]
	v_mfma_f32_16x16x32_bf16 v[78:81], v[148:151], v[194:197], v[78:81]
	v_mfma_f32_16x16x32_bf16 v[74:77], v[156:159], v[194:197], v[74:77]
	v_mfma_f32_16x16x32_bf16 v[62:65], v[148:151], v[202:205], v[62:65]
	v_mfma_f32_16x16x32_bf16 v[58:61], v[156:159], v[202:205], v[58:61]
	s_barrier
; #define PG8_STAGE(bufoff, gbase, voff) do { _Pragma("unroll") for (int _i = 0; _i < 2; ++_i) \
;         __builtin_amdgcn_global_load_lds((const unsigned*)((const char*)(gbase) + (voff)[_i]), (LAS unsigned*)(lds + (bufoff) + ldsw + _i * 8192), 16, 0, 0); } while (0)
; #define PG8_LDA(dst, b, h) do { _Pragma("unroll") for (int m = 0; m < 4; ++m) _Pragma("unroll") for (int k = 0; k < 2; ++k) dst[m][k] = *(const LAS bf16x8*)(lds + PG8_SA(b, h) + aoff + m * 2048 + k * 1024); } while (0)
; #define PG8_LDB(dst, b, h) do { _Pragma("unroll") for (int n = 0; n < 2; ++n) _Pragma("unroll") for (int k = 0; k < 2; ++k) dst[n][k] = *(const LAS bf16x8*)(lds + PG8_SB(b, h) + boff + n * 2048 + k * 1024); } while (0)
; #define PG8_MMA(ai, bj, At, Bt) do { __builtin_amdgcn_s_setprio(1); _Pragma("unroll") for (int m = 0; m < 4; ++m) _Pragma("unroll") for (int n = 0; n < 2; ++n) _Pragma("unroll") for (int k = 0; k < 2; ++k) \
;         acc[ai][bj][m][n] = __builtin_amdgcn_mfma_f32_16x16x32_bf16(Bt[n][k], At[m][k], acc[ai][bj][m][n], 0, 0, 0); __builtin_amdgcn_s_setprio(0); } while (0)
; #define PG8_WAIT_V(n) asm volatile("s_waitcnt vmcnt(" #n ")" ::: "memory")
; #define PG8_WAIT_L(n) asm volatile("s_waitcnt lgkmcnt(" #n ")" ::: "memory")
; #define PG8_BAR __builtin_amdgcn_s_barrier()
; #define PG8_SCHED __builtin_amdgcn_sched_barrier(0)
; template <class Epi>
; __device__ __forceinline__ void gemm_phase(LAS unsigned char* lds, const Gemm g, const StaticOrder& S, const Epi& E) {
;     ...
;             PG8_STAGE(PG8_SB(0, 1), b2 + hstep, voffB);
;             PG8_WAIT_V(6); PG8_BAR; PG8_MMA(1, 1, At, B1); PG8_BAR;
;             PG8_LDB(B0, 1, 0); PG8_SCHED; PG8_LDA(At, 1, 0); PG8_STAGE(PG8_SA(0, 1), a2 + hstep, voffA);
;             PG8_WAIT_L(8); PG8_BAR; PG8_WAIT_L(0); PG8_MMA(0, 0, At, B0); PG8_BAR; PG8_SCHED;
;             PG8_LDB(B1, 1, 1); PG8_STAGE(PG8_SB(1, 0), b3, voffB);
;             PG8_BAR; PG8_WAIT_L(0); PG8_MMA(0, 1, At, B1); PG8_BAR;
;             PG8_LDA(At, 1, 1); PG8_STAGE(PG8_SA(1, 0), a3, voffA);
;             PG8_BAR; PG8_WAIT_L(0); PG8_MMA(1, 0, At, B0); PG8_BAR; PG8_SCHED;
	s_add_u32 s0, s18, 0x20000
	s_addc_u32 s1, s19, 0
	s_add_i32 s48, s49, s27
	s_mov_b32 m0, s48
	v_lshl_add_u64 v[144:145], s[0:1], 0, v[4:5]
	global_load_lds_dwordx4 v[144:145], off
	s_add_i32 m0, s48, 0x2000
	v_lshl_add_u64 v[144:145], s[0:1], 0, v[130:131]
	global_load_lds_dwordx4 v[144:145], off
	s_waitcnt vmcnt(6)
	s_barrier
	v_mfma_f32_16x16x32_bf16 v[30:33], v[206:209], v[160:163], v[30:33]
	v_mfma_f32_16x16x32_bf16 v[26:29], v[214:217], v[160:163], v[26:29]
	v_mfma_f32_16x16x32_bf16 v[22:25], v[206:209], v[168:171], v[22:25]
	v_mfma_f32_16x16x32_bf16 v[18:21], v[214:217], v[168:171], v[18:21]
	v_mfma_f32_16x16x32_bf16 v[14:17], v[206:209], v[190:193], v[14:17]
	v_mfma_f32_16x16x32_bf16 v[10:13], v[214:217], v[190:193], v[10:13]
	v_mfma_f32_16x16x32_bf16 v[6:9], v[206:209], v[198:201], v[6:9]
	v_mfma_f32_16x16x32_bf16 v[0:3], v[214:217], v[198:201], v[0:3]
	v_mfma_f32_16x16x32_bf16 v[30:33], v[210:213], v[164:167], v[30:33]
	v_mfma_f32_16x16x32_bf16 v[26:29], v[218:221], v[164:167], v[26:29]
	v_mfma_f32_16x16x32_bf16 v[22:25], v[210:213], v[172:175], v[22:25]
	v_mfma_f32_16x16x32_bf16 v[18:21], v[218:221], v[172:175], v[18:21]
	v_mfma_f32_16x16x32_bf16 v[14:17], v[210:213], v[194:197], v[14:17]
	v_mfma_f32_16x16x32_bf16 v[10:13], v[218:221], v[194:197], v[10:13]
	v_mfma_f32_16x16x32_bf16 v[6:9], v[210:213], v[202:205], v[6:9]
	v_mfma_f32_16x16x32_bf16 v[0:3], v[218:221], v[202:205], v[0:3]
	s_add_i32 s48, 0, 0x18000
	v_add_u32_e32 v156, s48, v141
	s_barrier
	ds_read_b128 v[144:147], v156
	ds_read_b128 v[148:151], v156 offset:1024
	ds_read_b128 v[152:155], v156 offset:2048
	ds_read_b128 v[156:159], v156 offset:3072
	s_add_u32 s0, s20, 0x20000
	s_addc_u32 s1, s21, 0
	s_mov_b32 m0, s30
	v_lshl_add_u64 v[206:207], s[0:1], 0, v[134:135]
	ds_read_b128 v[160:163], v143 offset:32768
	ds_read_b128 v[164:167], v143 offset:33792
	ds_read_b128 v[168:171], v143 offset:34816
	ds_read_b128 v[172:175], v143 offset:35840
	ds_read_b128 v[190:193], v143 offset:36864
	ds_read_b128 v[194:197], v143 offset:37888
	ds_read_b128 v[198:201], v143 offset:38912
	ds_read_b128 v[202:205], v143 offset:39936
	global_load_lds_dwordx4 v[206:207], off
	s_mov_b32 m0, s31
	v_lshl_add_u64 v[206:207], s[0:1], 0, v[132:133]
	global_load_lds_dwordx4 v[206:207], off
	s_waitcnt lgkmcnt(8)
	s_barrier
	s_waitcnt lgkmcnt(0)
	v_mfma_f32_16x16x32_bf16 v[126:129], v[144:147], v[160:163], v[126:129]
	v_mfma_f32_16x16x32_bf16 v[122:125], v[152:155], v[160:163], v[122:125]
	v_mfma_f32_16x16x32_bf16 v[118:121], v[144:147], v[168:171], v[118:121]
	v_mfma_f32_16x16x32_bf16 v[114:117], v[152:155], v[168:171], v[114:117]
	v_mfma_f32_16x16x32_bf16 v[110:113], v[144:147], v[190:193], v[110:113]
	v_mfma_f32_16x16x32_bf16 v[106:109], v[152:155], v[190:193], v[106:109]
	v_mfma_f32_16x16x32_bf16 v[102:105], v[144:147], v[198:201], v[102:105]
	v_mfma_f32_16x16x32_bf16 v[98:101], v[152:155], v[198:201], v[98:101]
	v_mfma_f32_16x16x32_bf16 v[126:129], v[148:151], v[164:167], v[126:129]
	v_mfma_f32_16x16x32_bf16 v[122:125], v[156:159], v[164:167], v[122:125]
	v_mfma_f32_16x16x32_bf16 v[118:121], v[148:151], v[172:175], v[118:121]
	v_mfma_f32_16x16x32_bf16 v[114:117], v[156:159], v[172:175], v[114:117]
	v_mfma_f32_16x16x32_bf16 v[110:113], v[148:151], v[194:197], v[110:113]
	v_mfma_f32_16x16x32_bf16 v[106:109], v[156:159], v[194:197], v[106:109]
	v_mfma_f32_16x16x32_bf16 v[102:105], v[148:151], v[202:205], v[102:105]
	v_mfma_f32_16x16x32_bf16 v[98:101], v[156:159], v[202:205], v[98:101]
	s_barrier
	s_add_i32 s20, 0, 0x1c000
	s_add_i32 s0, s48, s27
	v_add_u32_e32 v218, s20, v141
	v_lshl_add_u64 v[176:177], v[176:177], 0, s[86:87]
	s_mov_b32 m0, s0
	ds_read_b128 v[206:209], v218
	ds_read_b128 v[210:213], v218 offset:1024
	ds_read_b128 v[214:217], v218 offset:2048
	ds_read_b128 v[218:221], v218 offset:3072
	global_load_lds_dwordx4 v[176:177], off
	s_add_i32 m0, s0, 0x2000
	v_lshl_add_u64 v[176:177], v[186:187], 0, s[86:87]
	global_load_lds_dwordx4 v[176:177], off
	s_barrier
	s_waitcnt lgkmcnt(0)
	v_mfma_f32_16x16x32_bf16 v[70:73], v[206:209], v[160:163], v[70:73]
	v_mfma_f32_16x16x32_bf16 v[66:69], v[214:217], v[160:163], v[66:69]
	v_mfma_f32_16x16x32_bf16 v[54:57], v[206:209], v[168:171], v[54:57]
	v_mfma_f32_16x16x32_bf16 v[50:53], v[214:217], v[168:171], v[50:53]
	v_mfma_f32_16x16x32_bf16 v[46:49], v[206:209], v[190:193], v[46:49]
	v_mfma_f32_16x16x32_bf16 v[42:45], v[214:217], v[190:193], v[42:45]
	v_mfma_f32_16x16x32_bf16 v[38:41], v[206:209], v[198:201], v[38:41]
	v_mfma_f32_16x16x32_bf16 v[34:37], v[214:217], v[198:201], v[34:37]
	v_mfma_f32_16x16x32_bf16 v[70:73], v[210:213], v[164:167], v[70:73]
	v_mfma_f32_16x16x32_bf16 v[66:69], v[218:221], v[164:167], v[66:69]
	v_mfma_f32_16x16x32_bf16 v[54:57], v[210:213], v[172:175], v[54:57]
	v_mfma_f32_16x16x32_bf16 v[50:53], v[218:221], v[172:175], v[50:53]
	v_mfma_f32_16x16x32_bf16 v[46:49], v[210:213], v[194:197], v[46:49]
	v_mfma_f32_16x16x32_bf16 v[42:45], v[218:221], v[194:197], v[42:45]
	v_mfma_f32_16x16x32_bf16 v[38:41], v[210:213], v[202:205], v[38:41]
	v_mfma_f32_16x16x32_bf16 v[34:37], v[218:221], v[202:205], v[34:37]
	s_mov_b32 m0, s34
	v_lshl_add_u64 v[176:177], v[222:223], 0, s[86:87]
	s_barrier
	ds_read_b128 v[160:163], v143 offset:49152
	ds_read_b128 v[164:167], v143 offset:50176
	ds_read_b128 v[168:171], v143 offset:51200
	ds_read_b128 v[172:175], v143 offset:52224
	ds_read_b128 v[190:193], v143 offset:53248
	ds_read_b128 v[194:197], v143 offset:54272
	ds_read_b128 v[198:201], v143 offset:55296
	ds_read_b128 v[202:205], v143 offset:56320
	global_load_lds_dwordx4 v[176:177], off
	s_mov_b32 m0, s35
	v_lshl_add_u64 v[176:177], v[224:225], 0, s[86:87]
	global_load_lds_dwordx4 v[176:177], off
	s_barrier
; __device__ __forceinline__ unsigned cvt_pk_bf16(float lo, float hi) { unsigned r; asm volatile("s_nop 0\n\tv_cvt_pk_bf16_f32 %0, %1, %2" : "=v"(r) : "v"(lo), "v"(hi)); return r; }
; #define PG8_STAGE(bufoff, gbase, voff) do { _Pragma("unroll") for (int _i = 0; _i < 2; ++_i) \
;         __builtin_amdgcn_global_load_lds((const unsigned*)((const char*)(gbase) + (voff)[_i]), (LAS unsigned*)(lds + (bufoff) + ldsw + _i * 8192), 16, 0, 0); } while (0)
; #define PG8_MMA(ai, bj, At, Bt) do { __builtin_amdgcn_s_setprio(1); _Pragma("unroll") for (int m = 0; m < 4; ++m) _Pragma("unroll") for (int n = 0; n < 2; ++n) _Pragma("unroll") for (int k = 0; k < 2; ++k) \
;         acc[ai][bj][m][n] = __builtin_amdgcn_mfma_f32_16x16x32_bf16(Bt[n][k], At[m][k], acc[ai][bj][m][n], 0, 0, 0); __builtin_amdgcn_s_setprio(0); } while (0)
; #define PG8_WAIT_V(n) asm volatile("s_waitcnt vmcnt(" #n ")" ::: "memory")
; #define PG8_WAIT_L(n) asm volatile("s_waitcnt lgkmcnt(" #n ")" ::: "memory")
; #define PG8_BAR __builtin_amdgcn_s_barrier()
; #define PG8_SCHED __builtin_amdgcn_sched_barrier(0)
; template <class Epi>
; __device__ __forceinline__ void gemm_phase(LAS unsigned char* lds, const Gemm g, const StaticOrder& S, const Epi& E) {
;     ...
;             PG8_BAR; PG8_WAIT_L(0); PG8_MMA(1, 0, At, B0); PG8_BAR; PG8_SCHED;
;             PG8_STAGE(PG8_SB(1, 1), b3 + hstep, voffB);
;             PG8_WAIT_V(6); PG8_BAR; PG8_MMA(1, 1, At, B1); PG8_BAR;
;     __device__ __forceinline__ void operator()(const f32x4 (&acc)[2][2][4][2], const Unit& u, int wr, int wc, int fr, int fq) const {
;     ...
;         for (int bj = 0; bj < 2; ++bj) {
;             const f32x4 s0 = swv[2 * bj], s1 = swv[2 * bj + 1];
; #pragma unroll
;             for (int ai = 0; ai < 2; ++ai)
; #pragma unroll
;                 for (int m = 0; m < 4; ++m) { const int r = row0 + ai * 128 + m * 16;
;                     const float rstd = ai ? rb[m] : ra[m];
;                     const f32x4 v0 = acc[ai][bj][m][0] * rstd + s0, v1 = acc[ai][bj][m][1] * rstd + s1;
;                     uint4 st; st.x = cvt_pk_bf16(v0[0], v0[1]); st.y = cvt_pk_bf16(v0[2], v0[3]); st.z = cvt_pk_bf16(v1[0], v1[1]); st.w = cvt_pk_bf16(v1[2], v1[3]);
;                     *(uint4*)(O + (size_t)r * ldc + col0 + bj * 128) = st; }
	s_waitcnt lgkmcnt(0)
	v_mfma_f32_16x16x32_bf16 v[94:97], v[144:147], v[160:163], v[94:97]
	v_mfma_f32_16x16x32_bf16 v[90:93], v[152:155], v[160:163], v[90:93]
	v_mfma_f32_16x16x32_bf16 v[86:89], v[144:147], v[168:171], v[86:89]
	v_mfma_f32_16x16x32_bf16 v[82:85], v[152:155], v[168:171], v[82:85]
	v_mfma_f32_16x16x32_bf16 v[78:81], v[144:147], v[190:193], v[78:81]
	v_mfma_f32_16x16x32_bf16 v[74:77], v[152:155], v[190:193], v[74:77]
	v_mfma_f32_16x16x32_bf16 v[62:65], v[144:147], v[198:201], v[62:65]
	v_mfma_f32_16x16x32_bf16 v[58:61], v[152:155], v[198:201], v[58:61]
	v_mfma_f32_16x16x32_bf16 v[94:97], v[148:151], v[164:167], v[94:97]
	v_mfma_f32_16x16x32_bf16 v[90:93], v[156:159], v[164:167], v[90:93]
	v_mfma_f32_16x16x32_bf16 v[86:89], v[148:151], v[172:175], v[86:89]
	v_mfma_f32_16x16x32_bf16 v[82:85], v[156:159], v[172:175], v[82:85]
	v_mfma_f32_16x16x32_bf16 v[78:81], v[148:151], v[194:197], v[78:81]
	v_mfma_f32_16x16x32_bf16 v[74:77], v[156:159], v[194:197], v[74:77]
	v_mfma_f32_16x16x32_bf16 v[62:65], v[148:151], v[202:205], v[62:65]
	v_mfma_f32_16x16x32_bf16 v[58:61], v[156:159], v[202:205], v[58:61]
	s_barrier
	s_add_u32 s0, s18, 0x20080
	s_addc_u32 s1, s19, 0
	s_add_i32 s18, s20, s27
	s_mov_b32 m0, s18
	v_lshl_add_u64 v[144:145], s[0:1], 0, v[4:5]
	global_load_lds_dwordx4 v[144:145], off
	s_add_i32 m0, s18, 0x2000
	v_lshl_add_u64 v[144:145], s[0:1], 0, v[130:131]
	global_load_lds_dwordx4 v[144:145], off
	s_waitcnt vmcnt(6)
	s_barrier
	v_mfma_f32_16x16x32_bf16 v[30:33], v[206:209], v[160:163], v[30:33]
	v_mfma_f32_16x16x32_bf16 v[26:29], v[214:217], v[160:163], v[26:29]
	v_mfma_f32_16x16x32_bf16 v[22:25], v[206:209], v[168:171], v[22:25]
	v_mfma_f32_16x16x32_bf16 v[18:21], v[214:217], v[168:171], v[18:21]
	v_mfma_f32_16x16x32_bf16 v[14:17], v[206:209], v[190:193], v[14:17]
	v_mfma_f32_16x16x32_bf16 v[10:13], v[214:217], v[190:193], v[10:13]
	v_mfma_f32_16x16x32_bf16 v[6:9], v[206:209], v[198:201], v[6:9]
	v_mfma_f32_16x16x32_bf16 v[0:3], v[214:217], v[198:201], v[0:3]
	v_mfma_f32_16x16x32_bf16 v[30:33], v[210:213], v[164:167], v[30:33]
	v_mfma_f32_16x16x32_bf16 v[26:29], v[218:221], v[164:167], v[26:29]
	v_mfma_f32_16x16x32_bf16 v[22:25], v[210:213], v[172:175], v[22:25]
	v_mfma_f32_16x16x32_bf16 v[18:21], v[218:221], v[172:175], v[18:21]
	v_mfma_f32_16x16x32_bf16 v[14:17], v[210:213], v[194:197], v[14:17]
	v_mfma_f32_16x16x32_bf16 v[10:13], v[218:221], v[194:197], v[10:13]
	v_mfma_f32_16x16x32_bf16 v[6:9], v[210:213], v[202:205], v[6:9]
	v_mfma_f32_16x16x32_bf16 v[0:3], v[218:221], v[202:205], v[0:3]
	s_add_i32 s43, s43, 2
	s_add_u32 s16, s16, 0x100
	s_addc_u32 s17, s17, 0
	s_add_u32 s41, s41, 0x100
	s_addc_u32 s42, s42, 0
	s_cmp_gt_u32 s43, 5
	s_barrier
	s_cbranch_scc0 .LBB0_2732
	v_lshl_add_u32 v144, s38, 8, v140
	v_lshl_or_b32 v146, s37, 8, v142
	v_ashrrev_i32_e32 v145, 31, v144
	v_pk_add_f32 v[126:127], v[126:127], 0 op_sel_hi:[1,0]
	v_ashrrev_i32_e32 v147, 31, v146
	v_pk_add_f32 v[128:129], v[128:129], 0 op_sel_hi:[1,0]
	v_pk_add_f32 v[148:149], v[124:125], 0 op_sel_hi:[1,0]
	v_pk_add_f32 v[124:125], v[122:123], 0 op_sel_hi:[1,0]
	s_nop 0
	v_cvt_pk_bf16_f32 v122, v126, v127
	v_lshlrev_b64 v[126:127], 11, v[144:145]
	s_nop 0
	v_cvt_pk_bf16_f32 v123, v128, v129
	v_lshl_add_u64 v[126:127], s[6:7], 0, v[126:127]
	v_lshlrev_b64 v[128:129], 1, v[146:147]
	v_lshl_add_u64 v[126:127], v[126:127], 0, v[128:129]
	s_nop 0
	v_cvt_pk_bf16_f32 v124, v124, v125
	s_nop 0
	v_cvt_pk_bf16_f32 v125, v148, v149
	global_store_dwordx4 v[126:127], v[122:125], off
	v_pk_add_f32 v[118:119], v[118:119], 0 op_sel_hi:[1,0]
	v_pk_add_f32 v[120:121], v[120:121], 0 op_sel_hi:[1,0]
	v_or_b32_e32 v122, 16, v144
	v_ashrrev_i32_e32 v123, 31, v122
	v_pk_add_f32 v[124:125], v[116:117], 0 op_sel_hi:[1,0]
	v_pk_add_f32 v[116:117], v[114:115], 0 op_sel_hi:[1,0]
	s_nop 0
	v_cvt_pk_bf16_f32 v114, v118, v119
	v_lshlrev_b64 v[118:119], 11, v[122:123]
	v_lshl_add_u64 v[118:119], s[6:7], 0, v[118:119]
	v_lshl_add_u64 v[118:119], v[118:119], 0, v[128:129]
	s_nop 0
	v_cvt_pk_bf16_f32 v115, v120, v121
	s_nop 0
	v_cvt_pk_bf16_f32 v116, v116, v117
	s_nop 0
	v_cvt_pk_bf16_f32 v117, v124, v125
	global_store_dwordx4 v[118:119], v[114:117], off
	v_pk_add_f32 v[110:111], v[110:111], 0 op_sel_hi:[1,0]
	v_pk_add_f32 v[112:113], v[112:113], 0 op_sel_hi:[1,0]
	v_or_b32_e32 v114, 32, v144
	v_ashrrev_i32_e32 v115, 31, v114
	v_pk_add_f32 v[116:117], v[108:109], 0 op_sel_hi:[1,0]
	v_pk_add_f32 v[108:109], v[106:107], 0 op_sel_hi:[1,0]
	s_nop 0
	v_cvt_pk_bf16_f32 v106, v110, v111
	v_lshlrev_b64 v[110:111], 11, v[114:115]
	v_lshl_add_u64 v[110:111], s[6:7], 0, v[110:111]
	v_lshl_add_u64 v[110:111], v[110:111], 0, v[128:129]
	s_nop 0
	v_cvt_pk_bf16_f32 v107, v112, v113
	s_nop 0
	v_cvt_pk_bf16_f32 v108, v108, v109
	s_nop 0
	v_cvt_pk_bf16_f32 v109, v116, v117
	global_store_dwordx4 v[110:111], v[106:109], off
	v_pk_add_f32 v[102:103], v[102:103], 0 op_sel_hi:[1,0]
	v_pk_add_f32 v[104:105], v[104:105], 0 op_sel_hi:[1,0]
	v_or_b32_e32 v106, 48, v144
	v_ashrrev_i32_e32 v107, 31, v106
	v_pk_add_f32 v[108:109], v[100:101], 0 op_sel_hi:[1,0]
	v_pk_add_f32 v[100:101], v[98:99], 0 op_sel_hi:[1,0]
	s_nop 0
	v_cvt_pk_bf16_f32 v98, v102, v103
	v_lshlrev_b64 v[102:103], 11, v[106:107]
	v_lshl_add_u64 v[102:103], s[6:7], 0, v[102:103]
	s_nop 0
	v_cvt_pk_bf16_f32 v99, v104, v105
	v_lshl_add_u64 v[102:103], v[102:103], 0, v[128:129]
	v_pk_add_f32 v[96:97], v[96:97], 0 op_sel_hi:[1,0]
	s_nop 0
	v_cvt_pk_bf16_f32 v100, v100, v101
	s_nop 0
	v_cvt_pk_bf16_f32 v101, v108, v109
	global_store_dwordx4 v[102:103], v[98:101], off
	v_pk_add_f32 v[94:95], v[94:95], 0 op_sel_hi:[1,0]
	s_mov_b64 s[0:1], 0x40000
; __device__ __forceinline__ unsigned cvt_pk_bf16(float lo, float hi) { unsigned r; asm volatile("s_nop 0\n\tv_cvt_pk_bf16_f32 %0, %1, %2" : "=v"(r) : "v"(lo), "v"(hi)); return r; }
; #define PG8_WAIT_V(n) asm volatile("s_waitcnt vmcnt(" #n ")" ::: "memory")
; #define PG8_BAR __builtin_amdgcn_s_barrier()
; template <class Epi>
; __device__ __forceinline__ void gemm_phase(LAS unsigned char* lds, const Gemm g, const StaticOrder& S, const Epi& E) {
;     ...
;         E(acc, cur, wr, wc, fr, fq);
;         if (!has_next) break;
; #pragma unroll
;         for (int a = 0; a < 2; ++a)
; #pragma unroll
;             for (int b = 0; b < 2; ++b)
; #pragma unroll
;                 for (int m = 0; m < 4; ++m)
; #pragma unroll
;                     for (int n = 0; n < 2; ++n) acc[a][b][m][n] = (f32x4){0.f, 0.f, 0.f, 0.f};
;         cur = nxt; cA = nA; cB = nB; ++ui;
;     }
;     PG8_WAIT_V(0);
;     if (wr == 0) PG8_BAR;
;     PG8_BAR;
;     __device__ __forceinline__ void operator()(const f32x4 (&acc)[2][2][4][2], const Unit& u, int wr, int wc, int fr, int fq) const {
;     ...
;         for (int bj = 0; bj < 2; ++bj) {
;             const f32x4 s0 = swv[2 * bj], s1 = swv[2 * bj + 1];
; #pragma unroll
;             for (int ai = 0; ai < 2; ++ai)
; #pragma unroll
;                 for (int m = 0; m < 4; ++m) { const int r = row0 + ai * 128 + m * 16;
;                     const float rstd = ai ? rb[m] : ra[m];
;                     const f32x4 v0 = acc[ai][bj][m][0] * rstd + s0, v1 = acc[ai][bj][m][1] * rstd + s1;
;                     uint4 st; st.x = cvt_pk_bf16(v0[0], v0[1]); st.y = cvt_pk_bf16(v0[2], v0[3]); st.z = cvt_pk_bf16(v1[0], v1[1]); st.w = cvt_pk_bf16(v1[2], v1[3]);
;                     *(uint4*)(O + (size_t)r * ldc + col0 + bj * 128) = st; }
	v_pk_add_f32 v[98:99], v[92:93], 0 op_sel_hi:[1,0]
	v_pk_add_f32 v[92:93], v[90:91], 0 op_sel_hi:[1,0]
	s_nop 0
	v_cvt_pk_bf16_f32 v90, v94, v95
	s_nop 0
	v_cvt_pk_bf16_f32 v91, v96, v97
	v_add_co_u32_e32 v96, vcc, s85, v126
	v_lshl_add_u64 v[94:95], v[126:127], 0, s[0:1]
	s_nop 0
	v_addc_co_u32_e32 v97, vcc, 0, v127, vcc
	v_pk_add_f32 v[86:87], v[86:87], 0 op_sel_hi:[1,0]
	s_mov_b64 s[0:1], 0x48000
	s_nop 0
	v_cvt_pk_bf16_f32 v92, v92, v93
	s_nop 0
	v_cvt_pk_bf16_f32 v93, v98, v99
	global_store_dwordx4 v[96:97], v[90:93], off
	v_pk_add_f32 v[88:89], v[88:89], 0 op_sel_hi:[1,0]
	v_pk_add_f32 v[78:79], v[78:79], 0 op_sel_hi:[1,0]
	v_pk_add_f32 v[90:91], v[84:85], 0 op_sel_hi:[1,0]
	v_pk_add_f32 v[84:85], v[82:83], 0 op_sel_hi:[1,0]
	s_nop 0
	v_cvt_pk_bf16_f32 v82, v86, v87
	v_lshl_add_u64 v[86:87], v[126:127], 0, s[0:1]
	s_mov_b32 s0, 0x48000
	s_nop 0
	v_cvt_pk_bf16_f32 v83, v88, v89
	v_add_co_u32_e32 v88, vcc, s0, v126
	s_mov_b64 s[0:1], 0x50000
	s_nop 0
	v_addc_co_u32_e32 v89, vcc, 0, v127, vcc
	s_nop 0
	v_cvt_pk_bf16_f32 v84, v84, v85
	s_nop 0
	v_cvt_pk_bf16_f32 v85, v90, v91
	global_store_dwordx4 v[88:89], v[82:85], off
	v_pk_add_f32 v[80:81], v[80:81], 0 op_sel_hi:[1,0]
	v_pk_add_f32 v[62:63], v[62:63], 0 op_sel_hi:[1,0]
	v_pk_add_f32 v[82:83], v[76:77], 0 op_sel_hi:[1,0]
	v_pk_add_f32 v[76:77], v[74:75], 0 op_sel_hi:[1,0]
	s_nop 0
	v_cvt_pk_bf16_f32 v74, v78, v79
	v_lshl_add_u64 v[78:79], v[126:127], 0, s[0:1]
	s_mov_b32 s0, 0x50000
	s_nop 0
	v_cvt_pk_bf16_f32 v75, v80, v81
	v_add_co_u32_e32 v80, vcc, s0, v126
	s_mov_b64 s[0:1], 0x58000
	s_nop 0
	v_addc_co_u32_e32 v81, vcc, 0, v127, vcc
	s_nop 0
	v_cvt_pk_bf16_f32 v76, v76, v77
	s_nop 0
	v_cvt_pk_bf16_f32 v77, v82, v83
	global_store_dwordx4 v[80:81], v[74:77], off
	v_pk_add_f32 v[64:65], v[64:65], 0 op_sel_hi:[1,0]
	v_pk_add_f32 v[66:67], v[66:67], 0 op_sel_hi:[1,0]
	v_pk_add_f32 v[74:75], v[60:61], 0 op_sel_hi:[1,0]
	v_pk_add_f32 v[60:61], v[58:59], 0 op_sel_hi:[1,0]
	s_nop 0
	v_cvt_pk_bf16_f32 v58, v62, v63
	v_lshl_add_u64 v[62:63], v[126:127], 0, s[0:1]
	s_mov_b32 s0, 0x58000
	s_nop 0
	v_cvt_pk_bf16_f32 v59, v64, v65
	v_add_co_u32_e32 v64, vcc, s0, v126
	s_nop 0
	v_cvt_pk_bf16_f32 v60, v60, v61
	s_nop 0
	v_cvt_pk_bf16_f32 v61, v74, v75
	v_pk_add_f32 v[56:57], v[56:57], 0 op_sel_hi:[1,0]
	s_nop 0
	v_addc_co_u32_e32 v65, vcc, 0, v127, vcc
	global_store_dwordx4 v[64:65], v[58:61], off
	v_pk_add_f32 v[64:65], v[68:69], 0 op_sel_hi:[1,0]
	v_pk_add_f32 v[54:55], v[54:55], 0 op_sel_hi:[1,0]
	v_pk_add_f32 v[58:59], v[70:71], 0 op_sel_hi:[1,0]
	v_pk_add_f32 v[60:61], v[72:73], 0 op_sel_hi:[1,0]
	s_nop 0
	v_cvt_pk_bf16_f32 v58, v58, v59
	v_pk_add_f32 v[48:49], v[48:49], 0 op_sel_hi:[1,0]
	s_nop 0
	v_cvt_pk_bf16_f32 v59, v60, v61
	s_nop 0
	v_cvt_pk_bf16_f32 v60, v66, v67
	s_nop 0
	v_cvt_pk_bf16_f32 v61, v64, v65
	global_store_dwordx4 v[126:127], v[58:61], off offset:256
	v_pk_add_f32 v[46:47], v[46:47], 0 op_sel_hi:[1,0]
	v_pk_add_f32 v[40:41], v[40:41], 0 op_sel_hi:[1,0]
	v_pk_add_f32 v[58:59], v[52:53], 0 op_sel_hi:[1,0]
	v_pk_add_f32 v[52:53], v[50:51], 0 op_sel_hi:[1,0]
	s_nop 0
	v_cvt_pk_bf16_f32 v50, v54, v55
	s_nop 0
	v_cvt_pk_bf16_f32 v51, v56, v57
	v_pk_add_f32 v[38:39], v[38:39], 0 op_sel_hi:[1,0]
	s_nop 0
	v_cvt_pk_bf16_f32 v52, v52, v53
	s_nop 0
	v_cvt_pk_bf16_f32 v53, v58, v59
	global_store_dwordx4 v[118:119], v[50:53], off offset:256
	v_pk_add_f32 v[32:33], v[32:33], 0 op_sel_hi:[1,0]
	v_pk_add_f32 v[30:31], v[30:31], 0 op_sel_hi:[1,0]
	v_pk_add_f32 v[50:51], v[44:45], 0 op_sel_hi:[1,0]
	v_pk_add_f32 v[44:45], v[42:43], 0 op_sel_hi:[1,0]
	s_nop 0
	v_cvt_pk_bf16_f32 v42, v46, v47
	s_nop 0
	v_cvt_pk_bf16_f32 v43, v48, v49
	v_pk_add_f32 v[24:25], v[24:25], 0 op_sel_hi:[1,0]
	s_nop 0
	v_cvt_pk_bf16_f32 v44, v44, v45
	s_nop 0
	v_cvt_pk_bf16_f32 v45, v50, v51
	global_store_dwordx4 v[110:111], v[42:45], off offset:256
	v_pk_add_f32 v[22:23], v[22:23], 0 op_sel_hi:[1,0]
	v_pk_add_f32 v[16:17], v[16:17], 0 op_sel_hi:[1,0]
	v_pk_add_f32 v[42:43], v[36:37], 0 op_sel_hi:[1,0]
	v_pk_add_f32 v[36:37], v[34:35], 0 op_sel_hi:[1,0]
	s_nop 0
	v_cvt_pk_bf16_f32 v34, v38, v39
	s_nop 0
	v_cvt_pk_bf16_f32 v35, v40, v41
	v_pk_add_f32 v[14:15], v[14:15], 0 op_sel_hi:[1,0]
	s_nop 0
	v_cvt_pk_bf16_f32 v36, v36, v37
	s_nop 0
	v_cvt_pk_bf16_f32 v37, v42, v43
	global_store_dwordx4 v[102:103], v[34:37], off offset:256
	s_and_b64 vcc, exec, s[4:5]
	s_mov_b32 s37, s8
	v_pk_add_f32 v[34:35], v[28:29], 0 op_sel_hi:[1,0]
	v_pk_add_f32 v[28:29], v[26:27], 0 op_sel_hi:[1,0]
	s_nop 0
	v_cvt_pk_bf16_f32 v26, v30, v31
	s_nop 0
	v_cvt_pk_bf16_f32 v27, v32, v33
	s_mov_b32 s38, s10
	s_nop 0
	v_cvt_pk_bf16_f32 v28, v28, v29
	s_nop 0
	v_cvt_pk_bf16_f32 v29, v34, v35
	global_store_dwordx4 v[94:95], v[26:29], off offset:256
	s_mov_b64 s[18:19], s[14:15]
	s_mov_b64 s[16:17], s[12:13]
	v_pk_add_f32 v[26:27], v[20:21], 0 op_sel_hi:[1,0]
	v_pk_add_f32 v[20:21], v[18:19], 0 op_sel_hi:[1,0]
	s_nop 0
	v_cvt_pk_bf16_f32 v18, v22, v23
	s_nop 0
	v_cvt_pk_bf16_f32 v19, v24, v25
	v_pk_add_f32 v[8:9], v[8:9], 0 op_sel_hi:[1,0]
	s_nop 0
	v_cvt_pk_bf16_f32 v20, v20, v21
	s_nop 0
	v_cvt_pk_bf16_f32 v21, v26, v27
	global_store_dwordx4 v[86:87], v[18:21], off offset:256
	v_pk_add_f32 v[6:7], v[6:7], 0 op_sel_hi:[1,0]
	s_nop 0
	v_pk_add_f32 v[18:19], v[12:13], 0 op_sel_hi:[1,0]
	v_pk_add_f32 v[12:13], v[10:11], 0 op_sel_hi:[1,0]
	s_nop 0
	v_cvt_pk_bf16_f32 v10, v14, v15
	s_nop 0
	v_cvt_pk_bf16_f32 v11, v16, v17
	s_nop 0
	s_nop 0
	v_cvt_pk_bf16_f32 v12, v12, v13
	s_nop 0
	v_cvt_pk_bf16_f32 v13, v18, v19
	global_store_dwordx4 v[78:79], v[10:13], off offset:256
	s_nop 1
	v_pk_add_f32 v[10:11], v[2:3], 0 op_sel_hi:[1,0]
	v_pk_add_f32 v[2:3], v[0:1], 0 op_sel_hi:[1,0]
	s_nop 0
	v_cvt_pk_bf16_f32 v0, v6, v7
	s_nop 0
	v_cvt_pk_bf16_f32 v1, v8, v9
	s_nop 0
	s_nop 0
	v_cvt_pk_bf16_f32 v2, v2, v3
	s_nop 0
	v_cvt_pk_bf16_f32 v3, v10, v11
	global_store_dwordx4 v[62:63], v[0:3], off offset:256
	s_cbranch_vccz .LBB0_2725
	s_waitcnt vmcnt(0)
	s_cmpk_gt_u32 s22, 0xff
	s_cbranch_scc1 .LBB0_2736
	s_barrier

; #define PG8_STAGE(bufoff, gbase, voff) do { _Pragma("unroll") for (int _i = 0; _i < 2; ++_i) \
;         __builtin_amdgcn_global_load_lds((const unsigned*)((const char*)(gbase) + (voff)[_i]), (LAS unsigned*)(lds + (bufoff) + ldsw + _i * 8192), 16, 0, 0); } while (0)
; #define PG8_LDA(dst, b, h) do { _Pragma("unroll") for (int m = 0; m < 4; ++m) _Pragma("unroll") for (int k = 0; k < 2; ++k) dst[m][k] = *(const LAS bf16x8*)(lds + PG8_SA(b, h) + aoff + m * 2048 + k * 1024); } while (0)
; #define PG8_LDB(dst, b, h) do { _Pragma("unroll") for (int n = 0; n < 2; ++n) _Pragma("unroll") for (int k = 0; k < 2; ++k) dst[n][k] = *(const LAS bf16x8*)(lds + PG8_SB(b, h) + boff + n * 2048 + k * 1024); } while (0)
; #define PG8_MMA(ai, bj, At, Bt) do { __builtin_amdgcn_s_setprio(1); _Pragma("unroll") for (int m = 0; m < 4; ++m) _Pragma("unroll") for (int n = 0; n < 2; ++n) _Pragma("unroll") for (int k = 0; k < 2; ++k) \
;         acc[ai][bj][m][n] = __builtin_amdgcn_mfma_f32_16x16x32_bf16(Bt[n][k], At[m][k], acc[ai][bj][m][n], 0, 0, 0); __builtin_amdgcn_s_setprio(0); } while (0)
; #define PG8_WAIT_L(n) asm volatile("s_waitcnt lgkmcnt(" #n ")" ::: "memory")
; #define PG8_BAR __builtin_amdgcn_s_barrier()
; template <class Epi>
; __device__ __forceinline__ void gemm_phase(LAS unsigned char* lds, const Gemm g, const StaticOrder& S, const Epi& E) {
;     ...
;         const char* nA = has_next ? (const char*)g.A + (size_t)nxt.pm * tstep : cA; const char* nB = has_next ? (const char*)g.Bt + (size_t)nxt.pn * tstep : cB;
;         for (int t = 0; t < nt; t += 2) {
;             const bool last = (t == nt - 2);
;             const char* a1 = cA + (size_t)(t + 1) * kstep;
;             const char* a2 = last ? nA : cA + (size_t)(t + 2) * kstep; const char* b2 = last ? nB : cB + (size_t)(t + 2) * kstep;
;             const char* a3 = a2 + kstep; const char* b3 = b2 + kstep;
;             PG8_LDB(B0, 0, 0); PG8_SCHED; PG8_LDA(At, 0, 0); PG8_STAGE(PG8_SA(1, 1), a1 + hstep, voffA);
;             PG8_WAIT_L(8); PG8_BAR; PG8_WAIT_L(0); PG8_MMA(0, 0, At, B0); PG8_BAR; PG8_SCHED;
;             PG8_LDB(B1, 0, 1); PG8_STAGE(PG8_SB(0, 0), b2, voffB);
;             PG8_BAR; PG8_WAIT_L(0); PG8_MMA(0, 1, At, B1); PG8_BAR;
;             PG8_LDA(At, 0, 1); PG8_STAGE(PG8_SA(0, 0), a2, voffA);
;             PG8_BAR; PG8_WAIT_L(0); PG8_MMA(1, 0, At, B0); PG8_BAR; PG8_SCHED;
.LBB0_2801:
	s_add_u32 s0, s6, 0xfffc0080
	s_addc_u32 s1, s7, -1
	s_add_i32 s55, 0, 0x10000
	v_add_u32_e32 v130, s55, v243
	ds_read_b128 v[34:37], v130
	ds_read_b128 v[38:41], v130 offset:1024
	ds_read_b128 v[122:125], v130 offset:2048
	ds_read_b128 v[130:133], v130 offset:3072
	s_cmp_eq_u32 s54, 12
	s_cselect_b32 s25, s17, s1
	s_cselect_b32 s24, s49, s0
	s_cselect_b32 s23, s15, s52
	s_cselect_b32 s22, s50, s51
	v_lshl_add_u64 v[186:187], s[6:7], 0, v[196:197]
	s_add_i32 m0, s34, 0xc000
	ds_read_b128 v[146:149], v245
	ds_read_b128 v[150:153], v245 offset:1024
	ds_read_b128 v[154:157], v245 offset:2048
	ds_read_b128 v[158:161], v245 offset:3072
	ds_read_b128 v[162:165], v245 offset:4096
	ds_read_b128 v[166:169], v245 offset:5120
	ds_read_b128 v[170:173], v245 offset:6144
	ds_read_b128 v[174:177], v245 offset:7168
	global_load_lds_dwordx4 v[186:187], off
	s_add_i32 m0, s34, 0xe000
	v_lshl_add_u64 v[186:187], s[6:7], 0, v[198:199]
	global_load_lds_dwordx4 v[186:187], off
	s_waitcnt lgkmcnt(8)
	s_barrier
	s_waitcnt lgkmcnt(0)
	v_mfma_f32_16x16x32_bf16 v[142:145], v[34:37], v[146:149], v[142:145]
	v_mfma_f32_16x16x32_bf16 v[138:141], v[122:125], v[146:149], v[138:141]
	v_mfma_f32_16x16x32_bf16 v[134:137], v[34:37], v[154:157], v[134:137]
	v_mfma_f32_16x16x32_bf16 v[126:129], v[122:125], v[154:157], v[126:129]
	v_mfma_f32_16x16x32_bf16 v[118:121], v[34:37], v[162:165], v[118:121]
	v_mfma_f32_16x16x32_bf16 v[114:117], v[122:125], v[162:165], v[114:117]
	v_mfma_f32_16x16x32_bf16 v[110:113], v[34:37], v[170:173], v[110:113]
	v_mfma_f32_16x16x32_bf16 v[106:109], v[122:125], v[170:173], v[106:109]
	v_mfma_f32_16x16x32_bf16 v[142:145], v[38:41], v[150:153], v[142:145]
	v_mfma_f32_16x16x32_bf16 v[138:141], v[130:133], v[150:153], v[138:141]
	v_mfma_f32_16x16x32_bf16 v[134:137], v[38:41], v[158:161], v[134:137]
	v_mfma_f32_16x16x32_bf16 v[126:129], v[130:133], v[158:161], v[126:129]
	v_mfma_f32_16x16x32_bf16 v[118:121], v[38:41], v[166:169], v[118:121]
	v_mfma_f32_16x16x32_bf16 v[114:117], v[130:133], v[166:169], v[114:117]
	v_mfma_f32_16x16x32_bf16 v[110:113], v[38:41], v[174:177], v[110:113]
	v_mfma_f32_16x16x32_bf16 v[106:109], v[130:133], v[174:177], v[106:109]
	s_barrier
	s_add_i32 s56, 0, 0x14000
	v_add_u32_e32 v186, s56, v243
	s_add_i32 s0, s55, s31
	ds_read_b128 v[200:203], v186
	ds_read_b128 v[204:207], v186 offset:1024
	ds_read_b128 v[208:211], v186 offset:2048
	ds_read_b128 v[212:215], v186 offset:3072
	v_lshl_add_u64 v[186:187], s[22:23], 0, v[4:5]
	s_mov_b32 m0, s0
	v_lshl_add_u64 v[216:217], s[22:23], 0, v[190:191]
	global_load_lds_dwordx4 v[186:187], off
	s_add_i32 m0, s0, 0x2000
	s_nop 0
	global_load_lds_dwordx4 v[216:217], off
	s_barrier
	s_waitcnt lgkmcnt(0)
	v_mfma_f32_16x16x32_bf16 v[70:73], v[200:203], v[146:149], v[70:73]
	v_mfma_f32_16x16x32_bf16 v[66:69], v[208:211], v[146:149], v[66:69]
	v_mfma_f32_16x16x32_bf16 v[62:65], v[200:203], v[154:157], v[62:65]
	v_mfma_f32_16x16x32_bf16 v[58:61], v[208:211], v[154:157], v[58:61]
	v_mfma_f32_16x16x32_bf16 v[54:57], v[200:203], v[162:165], v[54:57]
	v_mfma_f32_16x16x32_bf16 v[50:53], v[208:211], v[162:165], v[50:53]
	v_mfma_f32_16x16x32_bf16 v[46:49], v[200:203], v[170:173], v[46:49]
	v_mfma_f32_16x16x32_bf16 v[42:45], v[208:211], v[170:173], v[42:45]
	v_mfma_f32_16x16x32_bf16 v[70:73], v[204:207], v[150:153], v[70:73]
	v_mfma_f32_16x16x32_bf16 v[66:69], v[212:215], v[150:153], v[66:69]
	v_mfma_f32_16x16x32_bf16 v[62:65], v[204:207], v[158:161], v[62:65]
	v_mfma_f32_16x16x32_bf16 v[58:61], v[212:215], v[158:161], v[58:61]
	v_mfma_f32_16x16x32_bf16 v[54:57], v[204:207], v[166:169], v[54:57]
	v_mfma_f32_16x16x32_bf16 v[50:53], v[212:215], v[166:169], v[50:53]
	v_mfma_f32_16x16x32_bf16 v[46:49], v[204:207], v[174:177], v[46:49]
	v_mfma_f32_16x16x32_bf16 v[42:45], v[212:215], v[174:177], v[42:45]
	s_mov_b32 m0, s34
	v_lshl_add_u64 v[218:219], s[24:25], 0, v[194:195]
	s_barrier
	ds_read_b128 v[146:149], v245 offset:16384
	ds_read_b128 v[150:153], v245 offset:17408
	ds_read_b128 v[154:157], v245 offset:18432
	ds_read_b128 v[158:161], v245 offset:19456
	ds_read_b128 v[162:165], v245 offset:20480
	ds_read_b128 v[166:169], v245 offset:21504
	ds_read_b128 v[170:173], v245 offset:22528
	ds_read_b128 v[174:177], v245 offset:23552
	global_load_lds_dwordx4 v[218:219], off
	s_mov_b32 m0, s35
	v_lshl_add_u64 v[220:221], s[24:25], 0, v[192:193]
	global_load_lds_dwordx4 v[220:221], off
	s_barrier
	s_waitcnt lgkmcnt(0)
	v_mfma_f32_16x16x32_bf16 v[102:105], v[34:37], v[146:149], v[102:105]
	v_mfma_f32_16x16x32_bf16 v[98:101], v[122:125], v[146:149], v[98:101]
	v_mfma_f32_16x16x32_bf16 v[94:97], v[34:37], v[154:157], v[94:97]
	v_mfma_f32_16x16x32_bf16 v[90:93], v[122:125], v[154:157], v[90:93]
	v_mfma_f32_16x16x32_bf16 v[86:89], v[34:37], v[162:165], v[86:89]
	v_mfma_f32_16x16x32_bf16 v[82:85], v[122:125], v[162:165], v[82:85]
	v_mfma_f32_16x16x32_bf16 v[34:37], v[34:37], v[170:173], v[78:81]
	v_mfma_f32_16x16x32_bf16 v[102:105], v[38:41], v[150:153], v[102:105]
	v_mfma_f32_16x16x32_bf16 v[98:101], v[130:133], v[150:153], v[98:101]
	v_mfma_f32_16x16x32_bf16 v[94:97], v[38:41], v[158:161], v[94:97]
	v_mfma_f32_16x16x32_bf16 v[90:93], v[130:133], v[158:161], v[90:93]
	v_mfma_f32_16x16x32_bf16 v[86:89], v[38:41], v[166:169], v[86:89]
	v_mfma_f32_16x16x32_bf16 v[82:85], v[130:133], v[166:169], v[82:85]
	v_mfma_f32_16x16x32_bf16 v[34:37], v[38:41], v[174:177], v[34:37]
	v_mfma_f32_16x16x32_bf16 v[38:41], v[122:125], v[170:173], v[74:77]
	v_mfma_f32_16x16x32_bf16 v[38:41], v[130:133], v[174:177], v[38:41]
	s_barrier
; #define PG8_STAGE(bufoff, gbase, voff) do { _Pragma("unroll") for (int _i = 0; _i < 2; ++_i) \
;         __builtin_amdgcn_global_load_lds((const unsigned*)((const char*)(gbase) + (voff)[_i]), (LAS unsigned*)(lds + (bufoff) + ldsw + _i * 8192), 16, 0, 0); } while (0)
; #define PG8_LDA(dst, b, h) do { _Pragma("unroll") for (int m = 0; m < 4; ++m) _Pragma("unroll") for (int k = 0; k < 2; ++k) dst[m][k] = *(const LAS bf16x8*)(lds + PG8_SA(b, h) + aoff + m * 2048 + k * 1024); } while (0)
; #define PG8_LDB(dst, b, h) do { _Pragma("unroll") for (int n = 0; n < 2; ++n) _Pragma("unroll") for (int k = 0; k < 2; ++k) dst[n][k] = *(const LAS bf16x8*)(lds + PG8_SB(b, h) + boff + n * 2048 + k * 1024); } while (0)
; #define PG8_MMA(ai, bj, At, Bt) do { __builtin_amdgcn_s_setprio(1); _Pragma("unroll") for (int m = 0; m < 4; ++m) _Pragma("unroll") for (int n = 0; n < 2; ++n) _Pragma("unroll") for (int k = 0; k < 2; ++k) \
;         acc[ai][bj][m][n] = __builtin_amdgcn_mfma_f32_16x16x32_bf16(Bt[n][k], At[m][k], acc[ai][bj][m][n], 0, 0, 0); __builtin_amdgcn_s_setprio(0); } while (0)
; #define PG8_WAIT_V(n) asm volatile("s_waitcnt vmcnt(" #n ")" ::: "memory")
; #define PG8_WAIT_L(n) asm volatile("s_waitcnt lgkmcnt(" #n ")" ::: "memory")
; #define PG8_BAR __builtin_amdgcn_s_barrier()
; #define PG8_SCHED __builtin_amdgcn_sched_barrier(0)
; template <class Epi>
; __device__ __forceinline__ void gemm_phase(LAS unsigned char* lds, const Gemm g, const StaticOrder& S, const Epi& E) {
;     ...
;             PG8_BAR; PG8_WAIT_L(0); PG8_MMA(1, 0, At, B0); PG8_BAR; PG8_SCHED;
;             PG8_STAGE(PG8_SB(0, 1), b2 + hstep, voffB);
;             PG8_WAIT_V(6); PG8_BAR; PG8_MMA(1, 1, At, B1); PG8_BAR;
;             PG8_LDB(B0, 1, 0); PG8_SCHED; PG8_LDA(At, 1, 0); PG8_STAGE(PG8_SA(0, 1), a2 + hstep, voffA);
;             PG8_WAIT_L(8); PG8_BAR; PG8_WAIT_L(0); PG8_MMA(0, 0, At, B0); PG8_BAR; PG8_SCHED;
;             PG8_LDB(B1, 1, 1); PG8_STAGE(PG8_SB(1, 0), b3, voffB);
;             PG8_BAR; PG8_WAIT_L(0); PG8_MMA(0, 1, At, B1); PG8_BAR;
;             PG8_LDA(At, 1, 1); PG8_STAGE(PG8_SA(1, 0), a3, voffA);
;             PG8_BAR; PG8_WAIT_L(0); PG8_MMA(1, 0, At, B0); PG8_BAR; PG8_SCHED;
	s_add_u32 s0, s22, 0x40000
	s_addc_u32 s1, s23, 0
	s_add_i32 s55, s56, s31
	s_mov_b32 m0, s55
	v_lshl_add_u64 v[74:75], s[0:1], 0, v[4:5]
	global_load_lds_dwordx4 v[74:75], off
	s_add_i32 m0, s55, 0x2000
	v_lshl_add_u64 v[74:75], s[0:1], 0, v[190:191]
	global_load_lds_dwordx4 v[74:75], off
	s_waitcnt vmcnt(6)
	s_barrier
	v_mfma_f32_16x16x32_bf16 v[30:33], v[200:203], v[146:149], v[30:33]
	v_mfma_f32_16x16x32_bf16 v[26:29], v[208:211], v[146:149], v[26:29]
	v_mfma_f32_16x16x32_bf16 v[22:25], v[200:203], v[154:157], v[22:25]
	v_mfma_f32_16x16x32_bf16 v[18:21], v[208:211], v[154:157], v[18:21]
	v_mfma_f32_16x16x32_bf16 v[14:17], v[200:203], v[162:165], v[14:17]
	v_mfma_f32_16x16x32_bf16 v[10:13], v[208:211], v[162:165], v[10:13]
	v_mfma_f32_16x16x32_bf16 v[6:9], v[200:203], v[170:173], v[6:9]
	v_mfma_f32_16x16x32_bf16 v[0:3], v[208:211], v[170:173], v[0:3]
	v_mfma_f32_16x16x32_bf16 v[30:33], v[204:207], v[150:153], v[30:33]
	v_mfma_f32_16x16x32_bf16 v[26:29], v[212:215], v[150:153], v[26:29]
	v_mfma_f32_16x16x32_bf16 v[22:25], v[204:207], v[158:161], v[22:25]
	v_mfma_f32_16x16x32_bf16 v[18:21], v[212:215], v[158:161], v[18:21]
	v_mfma_f32_16x16x32_bf16 v[14:17], v[204:207], v[166:169], v[14:17]
	v_mfma_f32_16x16x32_bf16 v[10:13], v[212:215], v[166:169], v[10:13]
	v_mfma_f32_16x16x32_bf16 v[6:9], v[204:207], v[174:177], v[6:9]
	v_mfma_f32_16x16x32_bf16 v[0:3], v[212:215], v[174:177], v[0:3]
	s_add_i32 s55, 0, 0x18000
	v_add_u32_e32 v130, s55, v243
	s_barrier
	ds_read_b128 v[74:77], v130
	ds_read_b128 v[78:81], v130 offset:1024
	ds_read_b128 v[122:125], v130 offset:2048
	ds_read_b128 v[130:133], v130 offset:3072
	s_add_u32 s0, s24, 0x40000
	s_addc_u32 s1, s25, 0
	s_mov_b32 m0, s36
	v_lshl_add_u64 v[200:201], s[0:1], 0, v[194:195]
	ds_read_b128 v[146:149], v245 offset:32768
	ds_read_b128 v[150:153], v245 offset:33792
	ds_read_b128 v[154:157], v245 offset:34816
	ds_read_b128 v[158:161], v245 offset:35840
	ds_read_b128 v[162:165], v245 offset:36864
	ds_read_b128 v[166:169], v245 offset:37888
	ds_read_b128 v[170:173], v245 offset:38912
	ds_read_b128 v[174:177], v245 offset:39936
	global_load_lds_dwordx4 v[200:201], off
	s_mov_b32 m0, s37
	v_lshl_add_u64 v[200:201], s[0:1], 0, v[192:193]
	global_load_lds_dwordx4 v[200:201], off
	s_waitcnt lgkmcnt(8)
	s_barrier
	s_waitcnt lgkmcnt(0)
	v_mfma_f32_16x16x32_bf16 v[142:145], v[74:77], v[146:149], v[142:145]
	v_mfma_f32_16x16x32_bf16 v[138:141], v[122:125], v[146:149], v[138:141]
	v_mfma_f32_16x16x32_bf16 v[134:137], v[74:77], v[154:157], v[134:137]
	v_mfma_f32_16x16x32_bf16 v[126:129], v[122:125], v[154:157], v[126:129]
	v_mfma_f32_16x16x32_bf16 v[118:121], v[74:77], v[162:165], v[118:121]
	v_mfma_f32_16x16x32_bf16 v[114:117], v[122:125], v[162:165], v[114:117]
	v_mfma_f32_16x16x32_bf16 v[110:113], v[74:77], v[170:173], v[110:113]
	v_mfma_f32_16x16x32_bf16 v[106:109], v[122:125], v[170:173], v[106:109]
	v_mfma_f32_16x16x32_bf16 v[142:145], v[78:81], v[150:153], v[142:145]
	v_mfma_f32_16x16x32_bf16 v[138:141], v[130:133], v[150:153], v[138:141]
	v_mfma_f32_16x16x32_bf16 v[134:137], v[78:81], v[158:161], v[134:137]
	v_mfma_f32_16x16x32_bf16 v[126:129], v[130:133], v[158:161], v[126:129]
	v_mfma_f32_16x16x32_bf16 v[118:121], v[78:81], v[166:169], v[118:121]
	v_mfma_f32_16x16x32_bf16 v[114:117], v[130:133], v[166:169], v[114:117]
	v_mfma_f32_16x16x32_bf16 v[110:113], v[78:81], v[174:177], v[110:113]
	v_mfma_f32_16x16x32_bf16 v[106:109], v[130:133], v[174:177], v[106:109]
	s_barrier
	s_add_i32 s24, 0, 0x1c000
	s_add_i32 s0, s55, s31
	v_add_u32_e32 v212, s24, v243
	v_lshl_add_u64 v[186:187], v[186:187], 0, s[86:87]
	s_mov_b32 m0, s0
	ds_read_b128 v[200:203], v212
	ds_read_b128 v[204:207], v212 offset:1024
	ds_read_b128 v[208:211], v212 offset:2048
	ds_read_b128 v[212:215], v212 offset:3072
	global_load_lds_dwordx4 v[186:187], off
	s_add_i32 m0, s0, 0x2000
	v_lshl_add_u64 v[186:187], v[216:217], 0, s[86:87]
	global_load_lds_dwordx4 v[186:187], off
	s_barrier
	s_waitcnt lgkmcnt(0)
	v_mfma_f32_16x16x32_bf16 v[70:73], v[200:203], v[146:149], v[70:73]
	v_mfma_f32_16x16x32_bf16 v[66:69], v[208:211], v[146:149], v[66:69]
	v_mfma_f32_16x16x32_bf16 v[62:65], v[200:203], v[154:157], v[62:65]
	v_mfma_f32_16x16x32_bf16 v[58:61], v[208:211], v[154:157], v[58:61]
	v_mfma_f32_16x16x32_bf16 v[54:57], v[200:203], v[162:165], v[54:57]
	v_mfma_f32_16x16x32_bf16 v[50:53], v[208:211], v[162:165], v[50:53]
	v_mfma_f32_16x16x32_bf16 v[46:49], v[200:203], v[170:173], v[46:49]
	v_mfma_f32_16x16x32_bf16 v[42:45], v[208:211], v[170:173], v[42:45]
	v_mfma_f32_16x16x32_bf16 v[70:73], v[204:207], v[150:153], v[70:73]
	v_mfma_f32_16x16x32_bf16 v[66:69], v[212:215], v[150:153], v[66:69]
	v_mfma_f32_16x16x32_bf16 v[62:65], v[204:207], v[158:161], v[62:65]
	v_mfma_f32_16x16x32_bf16 v[58:61], v[212:215], v[158:161], v[58:61]
	v_mfma_f32_16x16x32_bf16 v[54:57], v[204:207], v[166:169], v[54:57]
	v_mfma_f32_16x16x32_bf16 v[50:53], v[212:215], v[166:169], v[50:53]
	v_mfma_f32_16x16x32_bf16 v[46:49], v[204:207], v[174:177], v[46:49]
	v_mfma_f32_16x16x32_bf16 v[42:45], v[212:215], v[174:177], v[42:45]
	s_mov_b32 m0, s40
	v_lshl_add_u64 v[186:187], v[218:219], 0, s[86:87]
	s_barrier
; #define PG8_STAGE(bufoff, gbase, voff) do { _Pragma("unroll") for (int _i = 0; _i < 2; ++_i) \
;         __builtin_amdgcn_global_load_lds((const unsigned*)((const char*)(gbase) + (voff)[_i]), (LAS unsigned*)(lds + (bufoff) + ldsw + _i * 8192), 16, 0, 0); } while (0)
; #define PG8_MMA(ai, bj, At, Bt) do { __builtin_amdgcn_s_setprio(1); _Pragma("unroll") for (int m = 0; m < 4; ++m) _Pragma("unroll") for (int n = 0; n < 2; ++n) _Pragma("unroll") for (int k = 0; k < 2; ++k) \
;         acc[ai][bj][m][n] = __builtin_amdgcn_mfma_f32_16x16x32_bf16(Bt[n][k], At[m][k], acc[ai][bj][m][n], 0, 0, 0); __builtin_amdgcn_s_setprio(0); } while (0)
; #define PG8_WAIT_V(n) asm volatile("s_waitcnt vmcnt(" #n ")" ::: "memory")
; #define PG8_WAIT_L(n) asm volatile("s_waitcnt lgkmcnt(" #n ")" ::: "memory")
; #define PG8_BAR __builtin_amdgcn_s_barrier()
; #define PG8_SCHED __builtin_amdgcn_sched_barrier(0)
; template <class Epi>
; __device__ __forceinline__ void gemm_phase(LAS unsigned char* lds, const Gemm g, const StaticOrder& S, const Epi& E) {
;     ...
;             PG8_BAR; PG8_WAIT_L(0); PG8_MMA(1, 0, At, B0); PG8_BAR; PG8_SCHED;
;             PG8_STAGE(PG8_SB(1, 1), b3 + hstep, voffB);
;             PG8_WAIT_V(6); PG8_BAR; PG8_MMA(1, 1, At, B1); PG8_BAR;
;     __device__ __forceinline__ void operator()(const f32x4 (&acc)[2][2][4][2], const Unit& u, int wr, int wc, int fr, int fq) const {
;         const int row0 = u.pm * 256 + wr * 64 + fr, col0 = u.pn * 256 + wc * 32 + 8 * fq;
;         f32x4 ra, rb; load_rstd(ss, row0, ra, rb);
;         const float* swp = sw + (size_t)(u.pm >> 3) * 3072 + col0;
;         const f32x4 swv[4] = {*(const f32x4*)(swp), *(const f32x4*)(swp + 4), *(const f32x4*)(swp + 128), *(const f32x4*)(swp + 132)};
; #pragma unroll
;         for (int bj = 0; bj < 2; ++bj) {
;             const f32x4 s0 = swv[2 * bj], s1 = swv[2 * bj + 1];
; #pragma unroll
;             for (int ai = 0; ai < 2; ++ai) {
;                 uint4 yld[4], zld[4];
; #pragma unroll
;                 for (int i = 0; i < 4; ++i) { const size_t off = (size_t)(row0 + ai * 128 + i * 16) * DM + col0 + bj * 128;
;                     yld[i] = *(const uint4*)(Y + off); zld[i] = first ? make_uint4(0u, 0u, 0u, 0u) : *(const uint4*)(Z + off); }
	ds_read_b128 v[146:149], v245 offset:49152
	ds_read_b128 v[150:153], v245 offset:50176
	ds_read_b128 v[154:157], v245 offset:51200
	ds_read_b128 v[158:161], v245 offset:52224
	ds_read_b128 v[162:165], v245 offset:53248
	ds_read_b128 v[166:169], v245 offset:54272
	ds_read_b128 v[170:173], v245 offset:55296
	ds_read_b128 v[174:177], v245 offset:56320
	global_load_lds_dwordx4 v[186:187], off
	s_mov_b32 m0, s41
	v_lshl_add_u64 v[186:187], v[220:221], 0, s[86:87]
	global_load_lds_dwordx4 v[186:187], off
	s_barrier
	s_waitcnt lgkmcnt(0)
	v_mfma_f32_16x16x32_bf16 v[102:105], v[74:77], v[146:149], v[102:105]
	v_mfma_f32_16x16x32_bf16 v[94:97], v[74:77], v[154:157], v[94:97]
	v_mfma_f32_16x16x32_bf16 v[86:89], v[74:77], v[162:165], v[86:89]
	v_mfma_f32_16x16x32_bf16 v[34:37], v[74:77], v[170:173], v[34:37]
	v_mfma_f32_16x16x32_bf16 v[102:105], v[78:81], v[150:153], v[102:105]
	v_mfma_f32_16x16x32_bf16 v[98:101], v[122:125], v[146:149], v[98:101]
	v_mfma_f32_16x16x32_bf16 v[94:97], v[78:81], v[158:161], v[94:97]
	v_mfma_f32_16x16x32_bf16 v[90:93], v[122:125], v[154:157], v[90:93]
	v_mfma_f32_16x16x32_bf16 v[86:89], v[78:81], v[166:169], v[86:89]
	v_mfma_f32_16x16x32_bf16 v[82:85], v[122:125], v[162:165], v[82:85]
	v_mfma_f32_16x16x32_bf16 v[78:81], v[78:81], v[174:177], v[34:37]
	v_mfma_f32_16x16x32_bf16 v[34:37], v[122:125], v[170:173], v[38:41]
	v_mfma_f32_16x16x32_bf16 v[98:101], v[130:133], v[150:153], v[98:101]
	v_mfma_f32_16x16x32_bf16 v[90:93], v[130:133], v[158:161], v[90:93]
	v_mfma_f32_16x16x32_bf16 v[82:85], v[130:133], v[166:169], v[82:85]
	v_mfma_f32_16x16x32_bf16 v[74:77], v[130:133], v[174:177], v[34:37]
	s_barrier
	s_add_u32 s0, s22, 0x40080
	s_addc_u32 s1, s23, 0
	s_add_i32 s22, s24, s31
	s_mov_b32 m0, s22
	v_lshl_add_u64 v[34:35], s[0:1], 0, v[4:5]
	global_load_lds_dwordx4 v[34:35], off
	s_add_i32 m0, s22, 0x2000
	v_lshl_add_u64 v[34:35], s[0:1], 0, v[190:191]
	global_load_lds_dwordx4 v[34:35], off
	s_waitcnt vmcnt(6)
	s_barrier
	v_mfma_f32_16x16x32_bf16 v[30:33], v[200:203], v[146:149], v[30:33]
	v_mfma_f32_16x16x32_bf16 v[26:29], v[208:211], v[146:149], v[26:29]
	v_mfma_f32_16x16x32_bf16 v[22:25], v[200:203], v[154:157], v[22:25]
	v_mfma_f32_16x16x32_bf16 v[18:21], v[208:211], v[154:157], v[18:21]
	v_mfma_f32_16x16x32_bf16 v[14:17], v[200:203], v[162:165], v[14:17]
	v_mfma_f32_16x16x32_bf16 v[10:13], v[208:211], v[162:165], v[10:13]
	v_mfma_f32_16x16x32_bf16 v[6:9], v[200:203], v[170:173], v[6:9]
	v_mfma_f32_16x16x32_bf16 v[0:3], v[208:211], v[170:173], v[0:3]
	v_mfma_f32_16x16x32_bf16 v[30:33], v[204:207], v[150:153], v[30:33]
	v_mfma_f32_16x16x32_bf16 v[26:29], v[212:215], v[150:153], v[26:29]
	v_mfma_f32_16x16x32_bf16 v[22:25], v[204:207], v[158:161], v[22:25]
	v_mfma_f32_16x16x32_bf16 v[18:21], v[212:215], v[158:161], v[18:21]
	v_mfma_f32_16x16x32_bf16 v[14:17], v[204:207], v[166:169], v[14:17]
	v_mfma_f32_16x16x32_bf16 v[10:13], v[212:215], v[166:169], v[10:13]
	v_mfma_f32_16x16x32_bf16 v[6:9], v[204:207], v[174:177], v[6:9]
	v_mfma_f32_16x16x32_bf16 v[0:3], v[212:215], v[174:177], v[0:3]
	s_add_i32 s54, s54, 2
	s_add_u32 s6, s6, 0x100
	s_addc_u32 s7, s7, 0
	s_add_u32 s51, s51, 0x100
	s_addc_u32 s52, s52, 0
	s_cmp_gt_u32 s54, 13
	s_barrier
	s_cbranch_scc0 .LBB0_2801
	v_lshl_add_u32 v218, s43, 8, v242
	v_ashrrev_i32_e32 v219, 31, v218
	v_lshl_add_u64 v[34:35], v[218:219], 2, s[12:13]
	s_ashr_i32 s0, s43, 3
	global_load_dword v206, v[34:35], off
	global_load_dword v204, v[34:35], off offset:64
	global_load_dword v187, v[34:35], off offset:128
	global_load_dword v186, v[34:35], off offset:192
	global_load_dword v246, v[34:35], off offset:512
	global_load_dword v209, v[34:35], off offset:576
	global_load_dword v207, v[34:35], off offset:640
	global_load_dword v205, v[34:35], off offset:704
	s_mul_hi_i32 s1, s0, 0x3000
	s_mulk_i32 s0, 0x3000
	v_lshl_or_b32 v200, s48, 8, v244
	s_add_u32 s0, s38, s0
	s_addc_u32 s1, s39, s1
	v_ashrrev_i32_e32 v201, 31, v200
	v_lshl_add_u64 v[38:39], v[200:201], 2, s[0:1]
	v_lshlrev_b64 v[210:211], 10, v[218:219]
	global_load_dwordx4 v[122:125], v[38:39], off offset:16
	global_load_dwordx4 v[130:133], v[38:39], off
	global_load_dwordx4 v[34:37], v[38:39], off offset:528
	s_nop 0
	global_load_dwordx4 v[38:41], v[38:39], off offset:512
	v_lshl_add_u64 v[146:147], v[210:211], 0, v[200:201]
	v_lshl_add_u64 v[148:149], v[146:147], 1, s[10:11]
	global_load_dwordx4 v[174:177], v[148:149], off
	v_cndmask_b32_e64 v148, 0, 1, s[88:89]
	v_mov_b32_e32 v162, 0
	v_cmp_ne_u32_e64 s[6:7], 1, v148
	s_andn2_b64 vcc, exec, s[88:89]
	v_mov_b32_e32 v170, 0
	v_mov_b32_e32 v171, 0
	v_mov_b32_e32 v172, 0
	v_mov_b32_e32 v173, 0
	s_cbranch_vccnz .LBB0_2804
	v_lshl_add_u64 v[146:147], v[146:147], 1, s[8:9]
	global_load_dwordx4 v[170:173], v[146:147], off

; #define PG8_STAGE(bufoff, gbase, voff) do { _Pragma("unroll") for (int _i = 0; _i < 2; ++_i) \
;         __builtin_amdgcn_global_load_lds((const unsigned*)((const char*)(gbase) + (voff)[_i]), (LAS unsigned*)(lds + (bufoff) + ldsw + _i * 8192), 16, 0, 0); } while (0)
; #define PG8_LDA(dst, b, h) do { _Pragma("unroll") for (int m = 0; m < 4; ++m) _Pragma("unroll") for (int k = 0; k < 2; ++k) dst[m][k] = *(const LAS bf16x8*)(lds + PG8_SA(b, h) + aoff + m * 2048 + k * 1024); } while (0)
; #define PG8_LDB(dst, b, h) do { _Pragma("unroll") for (int n = 0; n < 2; ++n) _Pragma("unroll") for (int k = 0; k < 2; ++k) dst[n][k] = *(const LAS bf16x8*)(lds + PG8_SB(b, h) + boff + n * 2048 + k * 1024); } while (0)
; #define PG8_MMA(ai, bj, At, Bt) do { __builtin_amdgcn_s_setprio(1); _Pragma("unroll") for (int m = 0; m < 4; ++m) _Pragma("unroll") for (int n = 0; n < 2; ++n) _Pragma("unroll") for (int k = 0; k < 2; ++k) \
;         acc[ai][bj][m][n] = __builtin_amdgcn_mfma_f32_16x16x32_bf16(Bt[n][k], At[m][k], acc[ai][bj][m][n], 0, 0, 0); __builtin_amdgcn_s_setprio(0); } while (0)
; #define PG8_WAIT_L(n) asm volatile("s_waitcnt lgkmcnt(" #n ")" ::: "memory")
; #define PG8_BAR __builtin_amdgcn_s_barrier()
; template <class Epi>
; __device__ __forceinline__ void gemm_phase(LAS unsigned char* lds, const Gemm g, const StaticOrder& S, const Epi& E) {
;     ...
;         const char* nA = has_next ? (const char*)g.A + (size_t)nxt.pm * tstep : cA; const char* nB = has_next ? (const char*)g.Bt + (size_t)nxt.pn * tstep : cB;
;         for (int t = 0; t < nt; t += 2) {
;             const bool last = (t == nt - 2);
;             const char* a1 = cA + (size_t)(t + 1) * kstep;
;             const char* a2 = last ? nA : cA + (size_t)(t + 2) * kstep; const char* b2 = last ? nB : cB + (size_t)(t + 2) * kstep;
;             const char* a3 = a2 + kstep; const char* b3 = b2 + kstep;
;             PG8_LDB(B0, 0, 0); PG8_SCHED; PG8_LDA(At, 0, 0); PG8_STAGE(PG8_SA(1, 1), a1 + hstep, voffA);
;             PG8_WAIT_L(8); PG8_BAR; PG8_WAIT_L(0); PG8_MMA(0, 0, At, B0); PG8_BAR; PG8_SCHED;
;             PG8_LDB(B1, 0, 1); PG8_STAGE(PG8_SB(0, 0), b2, voffB);
;             PG8_BAR; PG8_WAIT_L(0); PG8_MMA(0, 1, At, B1); PG8_BAR;
;             PG8_LDA(At, 0, 1); PG8_STAGE(PG8_SA(0, 0), a2, voffA);
;             PG8_BAR; PG8_WAIT_L(0); PG8_MMA(1, 0, At, B0); PG8_BAR; PG8_SCHED;
.LBB0_2897:
	s_add_u32 s0, s18, 0xfffc0080
	s_addc_u32 s1, s19, -1
	s_add_i32 s54, 0, 0x10000
	v_add_u32_e32 v78, s54, v161
	ds_read_b128 v[66:69], v78
	ds_read_b128 v[70:73], v78 offset:1024
	ds_read_b128 v[74:77], v78 offset:2048
	ds_read_b128 v[78:81], v78 offset:3072
	s_cmp_eq_u32 s52, 12
	s_cselect_b32 s23, s13, s1
	s_cselect_b32 s22, s48, s0
	s_cselect_b32 s21, s11, s51
	s_cselect_b32 s20, s49, s50
	v_lshl_add_u64 v[156:157], s[18:19], 0, v[152:153]
	s_add_i32 m0, s30, 0xc000
	ds_read_b128 v[168:171], v165
	ds_read_b128 v[172:175], v165 offset:1024
	ds_read_b128 v[190:193], v165 offset:2048
	ds_read_b128 v[194:197], v165 offset:3072
	ds_read_b128 v[198:201], v165 offset:4096
	ds_read_b128 v[202:205], v165 offset:5120
	ds_read_b128 v[206:209], v165 offset:6144
	ds_read_b128 v[210:213], v165 offset:7168
	global_load_lds_dwordx4 v[156:157], off
	s_add_i32 m0, s30, 0xe000
	v_lshl_add_u64 v[156:157], s[18:19], 0, v[154:155]
	global_load_lds_dwordx4 v[156:157], off
	s_waitcnt lgkmcnt(8)
	s_barrier
	s_waitcnt lgkmcnt(0)
	v_mfma_f32_16x16x32_bf16 v[142:145], v[66:69], v[168:171], v[142:145]
	v_mfma_f32_16x16x32_bf16 v[138:141], v[74:77], v[168:171], v[138:141]
	v_mfma_f32_16x16x32_bf16 v[126:129], v[66:69], v[190:193], v[126:129]
	v_mfma_f32_16x16x32_bf16 v[122:125], v[74:77], v[190:193], v[122:125]
	v_mfma_f32_16x16x32_bf16 v[110:113], v[66:69], v[198:201], v[110:113]
	v_mfma_f32_16x16x32_bf16 v[106:109], v[74:77], v[198:201], v[106:109]
	v_mfma_f32_16x16x32_bf16 v[94:97], v[66:69], v[206:209], v[94:97]
	v_mfma_f32_16x16x32_bf16 v[90:93], v[74:77], v[206:209], v[90:93]
	v_mfma_f32_16x16x32_bf16 v[142:145], v[70:73], v[172:175], v[142:145]
	v_mfma_f32_16x16x32_bf16 v[138:141], v[78:81], v[172:175], v[138:141]
	v_mfma_f32_16x16x32_bf16 v[126:129], v[70:73], v[194:197], v[126:129]
	v_mfma_f32_16x16x32_bf16 v[122:125], v[78:81], v[194:197], v[122:125]
	v_mfma_f32_16x16x32_bf16 v[110:113], v[70:73], v[202:205], v[110:113]
	v_mfma_f32_16x16x32_bf16 v[106:109], v[78:81], v[202:205], v[106:109]
	v_mfma_f32_16x16x32_bf16 v[94:97], v[70:73], v[210:213], v[94:97]
	v_mfma_f32_16x16x32_bf16 v[90:93], v[78:81], v[210:213], v[90:93]
	s_barrier
	s_add_i32 s0, 0, 0x14000
	v_add_u32_e32 v156, s0, v161
	s_add_i32 s1, s54, s29
	ds_read_b128 v[214:217], v156
	ds_read_b128 v[218:221], v156 offset:1024
	ds_read_b128 v[222:225], v156 offset:2048
	ds_read_b128 v[242:245], v156 offset:3072
	v_lshl_add_u64 v[156:157], s[20:21], 0, v[4:5]
	s_mov_b32 m0, s1
	v_lshl_add_u64 v[176:177], s[20:21], 0, v[146:147]
	global_load_lds_dwordx4 v[156:157], off
	s_add_i32 m0, s1, 0x2000
	s_nop 0
	global_load_lds_dwordx4 v[176:177], off
	s_barrier
	s_waitcnt lgkmcnt(0)
	v_mfma_f32_16x16x32_bf16 v[134:137], v[214:217], v[168:171], v[134:137]
	v_mfma_f32_16x16x32_bf16 v[130:133], v[222:225], v[168:171], v[130:133]
	v_mfma_f32_16x16x32_bf16 v[118:121], v[214:217], v[190:193], v[118:121]
	v_mfma_f32_16x16x32_bf16 v[114:117], v[222:225], v[190:193], v[114:117]
	v_mfma_f32_16x16x32_bf16 v[102:105], v[214:217], v[198:201], v[102:105]
	v_mfma_f32_16x16x32_bf16 v[98:101], v[222:225], v[198:201], v[98:101]
	v_mfma_f32_16x16x32_bf16 v[86:89], v[214:217], v[206:209], v[86:89]
	v_mfma_f32_16x16x32_bf16 v[82:85], v[222:225], v[206:209], v[82:85]
	v_mfma_f32_16x16x32_bf16 v[134:137], v[218:221], v[172:175], v[134:137]
	v_mfma_f32_16x16x32_bf16 v[130:133], v[242:245], v[172:175], v[130:133]
	v_mfma_f32_16x16x32_bf16 v[118:121], v[218:221], v[194:197], v[118:121]
	v_mfma_f32_16x16x32_bf16 v[114:117], v[242:245], v[194:197], v[114:117]
	v_mfma_f32_16x16x32_bf16 v[102:105], v[218:221], v[202:205], v[102:105]
	v_mfma_f32_16x16x32_bf16 v[98:101], v[242:245], v[202:205], v[98:101]
	v_mfma_f32_16x16x32_bf16 v[86:89], v[218:221], v[210:213], v[86:89]
	v_mfma_f32_16x16x32_bf16 v[82:85], v[242:245], v[210:213], v[82:85]
	s_mov_b32 m0, s30
	v_lshl_add_u64 v[186:187], s[22:23], 0, v[150:151]
	s_barrier
	ds_read_b128 v[168:171], v165 offset:16384
	ds_read_b128 v[172:175], v165 offset:17408
	ds_read_b128 v[190:193], v165 offset:18432
	ds_read_b128 v[194:197], v165 offset:19456
	ds_read_b128 v[198:201], v165 offset:20480
	ds_read_b128 v[202:205], v165 offset:21504
	ds_read_b128 v[206:209], v165 offset:22528
	ds_read_b128 v[210:213], v165 offset:23552
	global_load_lds_dwordx4 v[186:187], off
	s_mov_b32 m0, s31
	v_lshl_add_u64 v[226:227], s[22:23], 0, v[148:149]
	global_load_lds_dwordx4 v[226:227], off
	s_barrier
	s_waitcnt lgkmcnt(0)
	v_mfma_f32_16x16x32_bf16 v[62:65], v[66:69], v[168:171], v[62:65]
	v_mfma_f32_16x16x32_bf16 v[58:61], v[74:77], v[168:171], v[58:61]
	v_mfma_f32_16x16x32_bf16 v[46:49], v[66:69], v[190:193], v[46:49]
	v_mfma_f32_16x16x32_bf16 v[42:45], v[74:77], v[190:193], v[42:45]
	v_mfma_f32_16x16x32_bf16 v[30:33], v[66:69], v[198:201], v[30:33]
	v_mfma_f32_16x16x32_bf16 v[26:29], v[74:77], v[198:201], v[26:29]
	v_mfma_f32_16x16x32_bf16 v[14:17], v[66:69], v[206:209], v[14:17]
	v_mfma_f32_16x16x32_bf16 v[10:13], v[74:77], v[206:209], v[10:13]
	v_mfma_f32_16x16x32_bf16 v[62:65], v[70:73], v[172:175], v[62:65]
	v_mfma_f32_16x16x32_bf16 v[58:61], v[78:81], v[172:175], v[58:61]
	v_mfma_f32_16x16x32_bf16 v[46:49], v[70:73], v[194:197], v[46:49]
	v_mfma_f32_16x16x32_bf16 v[42:45], v[78:81], v[194:197], v[42:45]
	v_mfma_f32_16x16x32_bf16 v[30:33], v[70:73], v[202:205], v[30:33]
	v_mfma_f32_16x16x32_bf16 v[26:29], v[78:81], v[202:205], v[26:29]
	v_mfma_f32_16x16x32_bf16 v[14:17], v[70:73], v[210:213], v[14:17]
	v_mfma_f32_16x16x32_bf16 v[10:13], v[78:81], v[210:213], v[10:13]
	s_barrier
; #define PG8_STAGE(bufoff, gbase, voff) do { _Pragma("unroll") for (int _i = 0; _i < 2; ++_i) \
;         __builtin_amdgcn_global_load_lds((const unsigned*)((const char*)(gbase) + (voff)[_i]), (LAS unsigned*)(lds + (bufoff) + ldsw + _i * 8192), 16, 0, 0); } while (0)
; #define PG8_LDA(dst, b, h) do { _Pragma("unroll") for (int m = 0; m < 4; ++m) _Pragma("unroll") for (int k = 0; k < 2; ++k) dst[m][k] = *(const LAS bf16x8*)(lds + PG8_SA(b, h) + aoff + m * 2048 + k * 1024); } while (0)
; #define PG8_LDB(dst, b, h) do { _Pragma("unroll") for (int n = 0; n < 2; ++n) _Pragma("unroll") for (int k = 0; k < 2; ++k) dst[n][k] = *(const LAS bf16x8*)(lds + PG8_SB(b, h) + boff + n * 2048 + k * 1024); } while (0)
; #define PG8_MMA(ai, bj, At, Bt) do { __builtin_amdgcn_s_setprio(1); _Pragma("unroll") for (int m = 0; m < 4; ++m) _Pragma("unroll") for (int n = 0; n < 2; ++n) _Pragma("unroll") for (int k = 0; k < 2; ++k) \
;         acc[ai][bj][m][n] = __builtin_amdgcn_mfma_f32_16x16x32_bf16(Bt[n][k], At[m][k], acc[ai][bj][m][n], 0, 0, 0); __builtin_amdgcn_s_setprio(0); } while (0)
; #define PG8_WAIT_V(n) asm volatile("s_waitcnt vmcnt(" #n ")" ::: "memory")
; #define PG8_WAIT_L(n) asm volatile("s_waitcnt lgkmcnt(" #n ")" ::: "memory")
; #define PG8_BAR __builtin_amdgcn_s_barrier()
; #define PG8_SCHED __builtin_amdgcn_sched_barrier(0)
; template <class Epi>
; __device__ __forceinline__ void gemm_phase(LAS unsigned char* lds, const Gemm g, const StaticOrder& S, const Epi& E) {
;     ...
;             PG8_BAR; PG8_WAIT_L(0); PG8_MMA(1, 0, At, B0); PG8_BAR; PG8_SCHED;
;             PG8_STAGE(PG8_SB(0, 1), b2 + hstep, voffB);
;             PG8_WAIT_V(6); PG8_BAR; PG8_MMA(1, 1, At, B1); PG8_BAR;
;             PG8_LDB(B0, 1, 0); PG8_SCHED; PG8_LDA(At, 1, 0); PG8_STAGE(PG8_SA(0, 1), a2 + hstep, voffA);
;             PG8_WAIT_L(8); PG8_BAR; PG8_WAIT_L(0); PG8_MMA(0, 0, At, B0); PG8_BAR; PG8_SCHED;
;             PG8_LDB(B1, 1, 1); PG8_STAGE(PG8_SB(1, 0), b3, voffB);
;             PG8_BAR; PG8_WAIT_L(0); PG8_MMA(0, 1, At, B1); PG8_BAR;
;             PG8_LDA(At, 1, 1); PG8_STAGE(PG8_SA(1, 0), a3, voffA);
;             PG8_BAR; PG8_WAIT_L(0); PG8_MMA(1, 0, At, B0); PG8_BAR; PG8_SCHED;
	s_add_u32 s54, s20, 0x40000
	s_addc_u32 s55, s21, 0
	s_add_i32 s0, s0, s29
	s_mov_b32 m0, s0
	v_lshl_add_u64 v[66:67], s[54:55], 0, v[4:5]
	global_load_lds_dwordx4 v[66:67], off
	s_add_i32 m0, s0, 0x2000
	v_lshl_add_u64 v[66:67], s[54:55], 0, v[146:147]
	global_load_lds_dwordx4 v[66:67], off
	s_waitcnt vmcnt(6)
	s_barrier
	v_mfma_f32_16x16x32_bf16 v[54:57], v[214:217], v[168:171], v[54:57]
	v_mfma_f32_16x16x32_bf16 v[50:53], v[222:225], v[168:171], v[50:53]
	v_mfma_f32_16x16x32_bf16 v[38:41], v[214:217], v[190:193], v[38:41]
	v_mfma_f32_16x16x32_bf16 v[34:37], v[222:225], v[190:193], v[34:37]
	v_mfma_f32_16x16x32_bf16 v[22:25], v[214:217], v[198:201], v[22:25]
	v_mfma_f32_16x16x32_bf16 v[18:21], v[222:225], v[198:201], v[18:21]
	v_mfma_f32_16x16x32_bf16 v[6:9], v[214:217], v[206:209], v[6:9]
	v_mfma_f32_16x16x32_bf16 v[0:3], v[222:225], v[206:209], v[0:3]
	v_mfma_f32_16x16x32_bf16 v[54:57], v[218:221], v[172:175], v[54:57]
	v_mfma_f32_16x16x32_bf16 v[50:53], v[242:245], v[172:175], v[50:53]
	v_mfma_f32_16x16x32_bf16 v[38:41], v[218:221], v[194:197], v[38:41]
	v_mfma_f32_16x16x32_bf16 v[34:37], v[242:245], v[194:197], v[34:37]
	v_mfma_f32_16x16x32_bf16 v[22:25], v[218:221], v[202:205], v[22:25]
	v_mfma_f32_16x16x32_bf16 v[18:21], v[242:245], v[202:205], v[18:21]
	v_mfma_f32_16x16x32_bf16 v[6:9], v[218:221], v[210:213], v[6:9]
	v_mfma_f32_16x16x32_bf16 v[0:3], v[242:245], v[210:213], v[0:3]
	s_add_i32 s0, 0, 0x18000
	v_add_u32_e32 v78, s0, v161
	s_barrier
	ds_read_b128 v[66:69], v78
	ds_read_b128 v[70:73], v78 offset:1024
	ds_read_b128 v[74:77], v78 offset:2048
	ds_read_b128 v[78:81], v78 offset:3072
	s_add_u32 s22, s22, 0x40000
	s_addc_u32 s23, s23, 0
	s_mov_b32 m0, s34
	v_lshl_add_u64 v[214:215], s[22:23], 0, v[150:151]
	ds_read_b128 v[168:171], v165 offset:32768
	ds_read_b128 v[172:175], v165 offset:33792
	ds_read_b128 v[190:193], v165 offset:34816
	ds_read_b128 v[194:197], v165 offset:35840
	ds_read_b128 v[198:201], v165 offset:36864
	ds_read_b128 v[202:205], v165 offset:37888
	ds_read_b128 v[206:209], v165 offset:38912
	ds_read_b128 v[210:213], v165 offset:39936
	global_load_lds_dwordx4 v[214:215], off
	s_mov_b32 m0, s35
	v_lshl_add_u64 v[214:215], s[22:23], 0, v[148:149]
	global_load_lds_dwordx4 v[214:215], off
	s_waitcnt lgkmcnt(8)
	s_barrier
	s_waitcnt lgkmcnt(0)
	v_mfma_f32_16x16x32_bf16 v[142:145], v[66:69], v[168:171], v[142:145]
	v_mfma_f32_16x16x32_bf16 v[138:141], v[74:77], v[168:171], v[138:141]
	v_mfma_f32_16x16x32_bf16 v[126:129], v[66:69], v[190:193], v[126:129]
	v_mfma_f32_16x16x32_bf16 v[122:125], v[74:77], v[190:193], v[122:125]
	v_mfma_f32_16x16x32_bf16 v[110:113], v[66:69], v[198:201], v[110:113]
	v_mfma_f32_16x16x32_bf16 v[106:109], v[74:77], v[198:201], v[106:109]
	v_mfma_f32_16x16x32_bf16 v[94:97], v[66:69], v[206:209], v[94:97]
	v_mfma_f32_16x16x32_bf16 v[90:93], v[74:77], v[206:209], v[90:93]
	v_mfma_f32_16x16x32_bf16 v[142:145], v[70:73], v[172:175], v[142:145]
	v_mfma_f32_16x16x32_bf16 v[138:141], v[78:81], v[172:175], v[138:141]
	v_mfma_f32_16x16x32_bf16 v[126:129], v[70:73], v[194:197], v[126:129]
	v_mfma_f32_16x16x32_bf16 v[122:125], v[78:81], v[194:197], v[122:125]
	v_mfma_f32_16x16x32_bf16 v[110:113], v[70:73], v[202:205], v[110:113]
	v_mfma_f32_16x16x32_bf16 v[106:109], v[78:81], v[202:205], v[106:109]
	v_mfma_f32_16x16x32_bf16 v[94:97], v[70:73], v[210:213], v[94:97]
	v_mfma_f32_16x16x32_bf16 v[90:93], v[78:81], v[210:213], v[90:93]
	s_barrier
	s_add_i32 s1, 0, 0x1c000
	s_add_i32 s0, s0, s29
	v_add_u32_e32 v158, s1, v161
	v_lshl_add_u64 v[156:157], v[156:157], 0, s[86:87]
	s_mov_b32 m0, s0
	ds_read_b128 v[214:217], v158
	ds_read_b128 v[218:221], v158 offset:1024
	ds_read_b128 v[222:225], v158 offset:2048
	ds_read_b128 v[242:245], v158 offset:3072
	global_load_lds_dwordx4 v[156:157], off
	s_add_i32 m0, s0, 0x2000
	v_lshl_add_u64 v[156:157], v[176:177], 0, s[86:87]
	global_load_lds_dwordx4 v[156:157], off
	s_barrier
	s_waitcnt lgkmcnt(0)
	v_mfma_f32_16x16x32_bf16 v[134:137], v[214:217], v[168:171], v[134:137]
	v_mfma_f32_16x16x32_bf16 v[130:133], v[222:225], v[168:171], v[130:133]
	v_mfma_f32_16x16x32_bf16 v[118:121], v[214:217], v[190:193], v[118:121]
	v_mfma_f32_16x16x32_bf16 v[114:117], v[222:225], v[190:193], v[114:117]
	v_mfma_f32_16x16x32_bf16 v[102:105], v[214:217], v[198:201], v[102:105]
	v_mfma_f32_16x16x32_bf16 v[98:101], v[222:225], v[198:201], v[98:101]
	v_mfma_f32_16x16x32_bf16 v[86:89], v[214:217], v[206:209], v[86:89]
	v_mfma_f32_16x16x32_bf16 v[82:85], v[222:225], v[206:209], v[82:85]
	v_mfma_f32_16x16x32_bf16 v[134:137], v[218:221], v[172:175], v[134:137]
	v_mfma_f32_16x16x32_bf16 v[130:133], v[242:245], v[172:175], v[130:133]
	v_mfma_f32_16x16x32_bf16 v[118:121], v[218:221], v[194:197], v[118:121]
	v_mfma_f32_16x16x32_bf16 v[114:117], v[242:245], v[194:197], v[114:117]
	v_mfma_f32_16x16x32_bf16 v[102:105], v[218:221], v[202:205], v[102:105]
	v_mfma_f32_16x16x32_bf16 v[98:101], v[242:245], v[202:205], v[98:101]
	v_mfma_f32_16x16x32_bf16 v[86:89], v[218:221], v[210:213], v[86:89]
	v_mfma_f32_16x16x32_bf16 v[82:85], v[242:245], v[210:213], v[82:85]
	s_mov_b32 m0, s38
	v_lshl_add_u64 v[156:157], v[186:187], 0, s[86:87]
	s_barrier
	ds_read_b128 v[168:171], v165 offset:49152
	ds_read_b128 v[172:175], v165 offset:50176
	ds_read_b128 v[190:193], v165 offset:51200
	ds_read_b128 v[194:197], v165 offset:52224
	ds_read_b128 v[198:201], v165 offset:53248
	ds_read_b128 v[202:205], v165 offset:54272
	ds_read_b128 v[206:209], v165 offset:55296
	ds_read_b128 v[210:213], v165 offset:56320
	global_load_lds_dwordx4 v[156:157], off
	s_mov_b32 m0, s39
	v_lshl_add_u64 v[156:157], v[226:227], 0, s[86:87]
	global_load_lds_dwordx4 v[156:157], off
	s_barrier
; #define PG8_STAGE(bufoff, gbase, voff) do { _Pragma("unroll") for (int _i = 0; _i < 2; ++_i) \
;         __builtin_amdgcn_global_load_lds((const unsigned*)((const char*)(gbase) + (voff)[_i]), (LAS unsigned*)(lds + (bufoff) + ldsw + _i * 8192), 16, 0, 0); } while (0)
; #define PG8_MMA(ai, bj, At, Bt) do { __builtin_amdgcn_s_setprio(1); _Pragma("unroll") for (int m = 0; m < 4; ++m) _Pragma("unroll") for (int n = 0; n < 2; ++n) _Pragma("unroll") for (int k = 0; k < 2; ++k) \
;         acc[ai][bj][m][n] = __builtin_amdgcn_mfma_f32_16x16x32_bf16(Bt[n][k], At[m][k], acc[ai][bj][m][n], 0, 0, 0); __builtin_amdgcn_s_setprio(0); } while (0)
; #define PG8_WAIT_V(n) asm volatile("s_waitcnt vmcnt(" #n ")" ::: "memory")
; #define PG8_WAIT_L(n) asm volatile("s_waitcnt lgkmcnt(" #n ")" ::: "memory")
; #define PG8_BAR __builtin_amdgcn_s_barrier()
; #define PG8_SCHED __builtin_amdgcn_sched_barrier(0)
; template <class Epi>
; __device__ __forceinline__ void gemm_phase(LAS unsigned char* lds, const Gemm g, const StaticOrder& S, const Epi& E) {
;     ...
;             PG8_BAR; PG8_WAIT_L(0); PG8_MMA(1, 0, At, B0); PG8_BAR; PG8_SCHED;
;             PG8_STAGE(PG8_SB(1, 1), b3 + hstep, voffB);
;             PG8_WAIT_V(6); PG8_BAR; PG8_MMA(1, 1, At, B1); PG8_BAR;
; __device__ __forceinline__ void load_rstd(const float* ss, int row0, f32x4& ra, f32x4& rb) {
;     float t[8];
; #pragma unroll
;     for (int i = 0; i < 8; ++i) t[i] = ss[row0 + (i >> 2) * 128 + (i & 3) * 16];
; #pragma unroll
;     for (int i = 0; i < 4; ++i) { ra[i] = __builtin_amdgcn_rsqf(t[i] * (1.f / 1024.f) + 1e-6f); rb[i] = __builtin_amdgcn_rsqf(t[4 + i] * (1.f / 1024.f) + 1e-6f); }
; }
;     __device__ __forceinline__ void operator()(const f32x4 (&acc)[2][2][4][2], const Unit& u, int wr, int wc, int fr, int fq) const {
;         const int row0 = u.pm * 256 + wr * 64 + fr, hc0 = u.pn * 128 + wc * 32 + fq * 8;
;         const float* swp = sw + (size_t)(u.pm >> 3) * 5632 + u.pn * 256 + wc * 32 + 8 * fq;
;         f32x4 ra, rb; load_rstd(ss, row0, ra, rb);
;         const f32x4 sg0 = *(const f32x4*)(swp), sg1 = *(const f32x4*)(swp + 4), su0 = *(const f32x4*)(swp + 128), su1 = *(const f32x4*)(swp + 132);
	s_waitcnt lgkmcnt(0)
	v_mfma_f32_16x16x32_bf16 v[62:65], v[66:69], v[168:171], v[62:65]
	v_mfma_f32_16x16x32_bf16 v[58:61], v[74:77], v[168:171], v[58:61]
	v_mfma_f32_16x16x32_bf16 v[46:49], v[66:69], v[190:193], v[46:49]
	v_mfma_f32_16x16x32_bf16 v[42:45], v[74:77], v[190:193], v[42:45]
	v_mfma_f32_16x16x32_bf16 v[30:33], v[66:69], v[198:201], v[30:33]
	v_mfma_f32_16x16x32_bf16 v[26:29], v[74:77], v[198:201], v[26:29]
	v_mfma_f32_16x16x32_bf16 v[14:17], v[66:69], v[206:209], v[14:17]
	v_mfma_f32_16x16x32_bf16 v[10:13], v[74:77], v[206:209], v[10:13]
	v_mfma_f32_16x16x32_bf16 v[62:65], v[70:73], v[172:175], v[62:65]
	v_mfma_f32_16x16x32_bf16 v[58:61], v[78:81], v[172:175], v[58:61]
	v_mfma_f32_16x16x32_bf16 v[46:49], v[70:73], v[194:197], v[46:49]
	v_mfma_f32_16x16x32_bf16 v[42:45], v[78:81], v[194:197], v[42:45]
	v_mfma_f32_16x16x32_bf16 v[30:33], v[70:73], v[202:205], v[30:33]
	v_mfma_f32_16x16x32_bf16 v[26:29], v[78:81], v[202:205], v[26:29]
	v_mfma_f32_16x16x32_bf16 v[14:17], v[70:73], v[210:213], v[14:17]
	v_mfma_f32_16x16x32_bf16 v[10:13], v[78:81], v[210:213], v[10:13]
	s_barrier
	s_add_u32 s20, s20, 0x40080
	s_addc_u32 s21, s21, 0
	s_add_i32 s0, s1, s29
	s_mov_b32 m0, s0
	v_lshl_add_u64 v[66:67], s[20:21], 0, v[4:5]
	global_load_lds_dwordx4 v[66:67], off
	s_add_i32 m0, s0, 0x2000
	v_lshl_add_u64 v[66:67], s[20:21], 0, v[146:147]
	global_load_lds_dwordx4 v[66:67], off
	s_waitcnt vmcnt(6)
	s_barrier
	v_mfma_f32_16x16x32_bf16 v[54:57], v[214:217], v[168:171], v[54:57]
	v_mfma_f32_16x16x32_bf16 v[50:53], v[222:225], v[168:171], v[50:53]
	v_mfma_f32_16x16x32_bf16 v[38:41], v[214:217], v[190:193], v[38:41]
	v_mfma_f32_16x16x32_bf16 v[34:37], v[222:225], v[190:193], v[34:37]
	v_mfma_f32_16x16x32_bf16 v[22:25], v[214:217], v[198:201], v[22:25]
	v_mfma_f32_16x16x32_bf16 v[18:21], v[222:225], v[198:201], v[18:21]
	v_mfma_f32_16x16x32_bf16 v[6:9], v[214:217], v[206:209], v[6:9]
	v_mfma_f32_16x16x32_bf16 v[0:3], v[222:225], v[206:209], v[0:3]
	v_mfma_f32_16x16x32_bf16 v[54:57], v[218:221], v[172:175], v[54:57]
	v_mfma_f32_16x16x32_bf16 v[50:53], v[242:245], v[172:175], v[50:53]
	v_mfma_f32_16x16x32_bf16 v[38:41], v[218:221], v[194:197], v[38:41]
	v_mfma_f32_16x16x32_bf16 v[34:37], v[242:245], v[194:197], v[34:37]
	v_mfma_f32_16x16x32_bf16 v[22:25], v[218:221], v[202:205], v[22:25]
	v_mfma_f32_16x16x32_bf16 v[18:21], v[242:245], v[202:205], v[18:21]
	v_mfma_f32_16x16x32_bf16 v[6:9], v[218:221], v[210:213], v[6:9]
	v_mfma_f32_16x16x32_bf16 v[0:3], v[242:245], v[210:213], v[0:3]
	s_add_i32 s52, s52, 2
	s_add_u32 s18, s18, 0x100
	s_addc_u32 s19, s19, 0
	s_add_u32 s50, s50, 0x100
	s_addc_u32 s51, s51, 0
	s_cmp_gt_u32 s52, 13
	s_barrier
	s_cbranch_scc0 .LBB0_2897
	v_lshl_add_u32 v156, s43, 8, v159
	v_ashrrev_i32_e32 v157, 31, v156
	v_lshl_add_u64 v[66:67], v[156:157], 2, s[8:9]
	global_load_dword v190, v[66:67], off
	global_load_dword v191, v[66:67], off offset:64
	global_load_dword v192, v[66:67], off offset:128
	global_load_dword v193, v[66:67], off offset:192
	global_load_dword v194, v[66:67], off offset:512
	global_load_dword v195, v[66:67], off offset:576
	global_load_dword v196, v[66:67], off offset:640
	global_load_dword v197, v[66:67], off offset:704
	s_ashr_i32 s0, s43, 3
	s_mul_hi_i32 s1, s0, 0x5800
	s_mulk_i32 s0, 0x5800
	s_add_u32 s0, s36, s0
	s_addc_u32 s1, s37, s1
	s_lshl_b32 s18, s42, 8
	s_ashr_i32 s19, s18, 31
	s_lshl_b64 s[18:19], s[18:19], 2
	s_add_u32 s0, s0, s18
	s_addc_u32 s1, s1, s19
	s_add_u32 s18, s0, s41
	s_addc_u32 s19, s1, 0
	v_lshl_or_b32 v170, s42, 7, v163
	v_ashrrev_i32_e32 v171, 31, v170
	global_load_dwordx4 v[66:69], v167, s[18:19] offset:16
	global_load_dwordx4 v[74:77], v167, s[18:19]
	global_load_dwordx4 v[70:73], v167, s[18:19] offset:528
	global_load_dwordx4 v[78:81], v167, s[18:19] offset:512
	s_and_b64 vcc, exec, s[4:5]
	s_mov_b32 s42, s10
	s_mov_b32 s43, s12
	s_mov_b64 s[20:21], s[16:17]
	s_waitcnt vmcnt(4)
	v_fmamk_f32 v198, v190, 0x3a800000, v229
	v_rsq_f32_e32 v174, v198
	v_fmamk_f32 v198, v194, 0x3a800000, v229
	v_rsq_f32_e32 v164, v198
	v_fmamk_f32 v198, v191, 0x3a800000, v229
	v_rsq_f32_e32 v172, v198
	v_fmamk_f32 v198, v195, 0x3a800000, v229
	v_rsq_f32_e32 v162, v198
	v_fmamk_f32 v198, v192, 0x3a800000, v229
	v_rsq_f32_e32 v168, v198
	v_fmamk_f32 v198, v196, 0x3a800000, v229
	v_rsq_f32_e32 v160, v198
	v_fmamk_f32 v198, v193, 0x3a800000, v229
	v_fmamk_f32 v199, v197, 0x3a800000, v229
	v_rsq_f32_e32 v166, v198
	v_rsq_f32_e32 v158, v199
	s_waitcnt vmcnt(0)
; __device__ __forceinline__ unsigned cvt_pk_bf16(float lo, float hi) { unsigned r; asm volatile("s_nop 0\n\tv_cvt_pk_bf16_f32 %0, %1, %2" : "=v"(r) : "v"(lo), "v"(hi)); return r; }
; __device__ __forceinline__ float siluf_(float x) { return x * __builtin_amdgcn_rcpf(1.f + __expf(-x)); }
;     __device__ __forceinline__ void operator()(const f32x4 (&acc)[2][2][4][2], const Unit& u, int wr, int wc, int fr, int fq) const {
;     ...
;             for (int m = 0; m < 4; ++m) { const int r = row0 + ai * 128 + m * 16;
;                 const float rstd = ai ? rb[m] : ra[m];
;                 const f32x4 g0 = acc[ai][0][m][0] * rstd + sg0, g1 = acc[ai][0][m][1] * rstd + sg1, u0 = acc[ai][1][m][0] * rstd + su0, u1 = acc[ai][1][m][1] * rstd + su1;
;                 uint4 st; st.x = cvt_pk_bf16(siluf_(g0[0]) * u0[0], siluf_(g0[1]) * u0[1]); st.y = cvt_pk_bf16(siluf_(g0[2]) * u0[2], siluf_(g0[3]) * u0[3]);
;                 st.z = cvt_pk_bf16(siluf_(g1[0]) * u1[0], siluf_(g1[1]) * u1[1]); st.w = cvt_pk_bf16(siluf_(g1[2]) * u1[2], siluf_(g1[3]) * u1[3]);
;                 *(uint4*)(hid + (size_t)r * DFF + hc0) = st; }
	v_pk_fma_f32 v[138:139], v[138:139], v[174:175], v[66:67] op_sel_hi:[1,0,1]
	v_pk_fma_f32 v[142:143], v[142:143], v[174:175], v[74:75] op_sel_hi:[1,0,1]
	v_pk_fma_f32 v[144:145], v[144:145], v[174:175], v[76:77] op_sel_hi:[1,0,1]
	v_pk_fma_f32 v[176:177], v[134:135], v[174:175], v[78:79] op_sel_hi:[1,0,1]
	v_pk_fma_f32 v[134:135], v[132:133], v[174:175], v[72:73] op_sel_hi:[1,0,1]
	v_pk_fma_f32 v[132:133], v[130:131], v[174:175], v[70:71] op_sel_hi:[1,0,1]
	v_mul_f32_e32 v130, 0xbfb8aa3b, v142
	v_mul_f32_e32 v131, 0xbfb8aa3b, v143
	v_exp_f32_e32 v130, v130
	v_exp_f32_e32 v131, v131
	v_pk_fma_f32 v[136:137], v[136:137], v[174:175], v[80:81] op_sel_hi:[1,0,1]
	v_pk_fma_f32 v[140:141], v[140:141], v[174:175], v[68:69] op_sel_hi:[1,0,1]
	v_add_f32_e32 v130, 1.0, v130
	v_add_f32_e32 v131, 1.0, v131
	v_rcp_f32_e32 v130, v130
	v_rcp_f32_e32 v131, v131
	v_pk_fma_f32 v[126:127], v[126:127], v[172:173], v[74:75] op_sel_hi:[1,0,1]
	v_pk_fma_f32 v[118:119], v[118:119], v[172:173], v[78:79] op_sel_hi:[1,0,1]
	v_mul_f32_e32 v130, v142, v130
	v_mul_f32_e32 v131, v143, v131
	v_mul_f32_e32 v130, v176, v130
	v_mul_f32_e32 v131, v177, v131
	s_nop 0
	v_cvt_pk_bf16_f32 v130, v130, v131
	v_mul_f32_e32 v131, 0xbfb8aa3b, v144
	v_exp_f32_e32 v131, v131
	v_pk_fma_f32 v[128:129], v[128:129], v[172:173], v[76:77] op_sel_hi:[1,0,1]
	v_pk_fma_f32 v[120:121], v[120:121], v[172:173], v[80:81] op_sel_hi:[1,0,1]
	v_pk_fma_f32 v[122:123], v[122:123], v[172:173], v[66:67] op_sel_hi:[1,0,1]
	v_add_f32_e32 v131, 1.0, v131
	v_rcp_f32_e32 v131, v131
	v_pk_fma_f32 v[124:125], v[124:125], v[172:173], v[68:69] op_sel_hi:[1,0,1]
	v_pk_fma_f32 v[110:111], v[110:111], v[168:169], v[74:75] op_sel_hi:[1,0,1]
	v_pk_fma_f32 v[102:103], v[102:103], v[168:169], v[78:79] op_sel_hi:[1,0,1]
	v_mul_f32_e32 v131, v144, v131
	v_mul_f32_e32 v131, v136, v131
	v_mul_f32_e32 v136, 0xbfb8aa3b, v145
	v_exp_f32_e32 v136, v136
	v_pk_fma_f32 v[112:113], v[112:113], v[168:169], v[76:77] op_sel_hi:[1,0,1]
	v_pk_fma_f32 v[104:105], v[104:105], v[168:169], v[80:81] op_sel_hi:[1,0,1]
	v_pk_fma_f32 v[106:107], v[106:107], v[168:169], v[66:67] op_sel_hi:[1,0,1]
	v_add_f32_e32 v136, 1.0, v136
	v_rcp_f32_e32 v136, v136
	v_pk_fma_f32 v[108:109], v[108:109], v[168:169], v[68:69] op_sel_hi:[1,0,1]
	v_pk_fma_f32 v[94:95], v[94:95], v[166:167], v[74:75] op_sel_hi:[1,0,1]
	v_pk_fma_f32 v[86:87], v[86:87], v[166:167], v[78:79] op_sel_hi:[1,0,1]
	v_mul_f32_e32 v136, v145, v136
	v_mul_f32_e32 v136, v137, v136
	s_nop 0
	v_cvt_pk_bf16_f32 v131, v131, v136
	v_mul_f32_e32 v136, 0xbfb8aa3b, v138
	v_exp_f32_e32 v136, v136
	v_pk_fma_f32 v[96:97], v[96:97], v[166:167], v[76:77] op_sel_hi:[1,0,1]
	v_pk_fma_f32 v[88:89], v[88:89], v[166:167], v[80:81] op_sel_hi:[1,0,1]
	v_pk_fma_f32 v[90:91], v[90:91], v[166:167], v[66:67] op_sel_hi:[1,0,1]
	v_add_f32_e32 v136, 1.0, v136
	v_rcp_f32_e32 v136, v136
	v_pk_fma_f32 v[92:93], v[92:93], v[166:167], v[68:69] op_sel_hi:[1,0,1]
	v_pk_fma_f32 v[62:63], v[62:63], v[164:165], v[74:75] op_sel_hi:[1,0,1]
	v_pk_fma_f32 v[54:55], v[54:55], v[164:165], v[78:79] op_sel_hi:[1,0,1]
	v_mul_f32_e32 v136, v138, v136
	v_mul_f32_e32 v132, v132, v136
	v_mul_f32_e32 v136, 0xbfb8aa3b, v139
	v_exp_f32_e32 v136, v136
	v_pk_fma_f32 v[64:65], v[64:65], v[164:165], v[76:77] op_sel_hi:[1,0,1]
	v_pk_fma_f32 v[56:57], v[56:57], v[164:165], v[80:81] op_sel_hi:[1,0,1]
	v_pk_fma_f32 v[58:59], v[58:59], v[164:165], v[66:67] op_sel_hi:[1,0,1]
	v_add_f32_e32 v136, 1.0, v136
	v_rcp_f32_e32 v136, v136
	v_pk_fma_f32 v[60:61], v[60:61], v[164:165], v[68:69] op_sel_hi:[1,0,1]
	v_pk_fma_f32 v[46:47], v[46:47], v[162:163], v[74:75] op_sel_hi:[1,0,1]
	v_pk_fma_f32 v[38:39], v[38:39], v[162:163], v[78:79] op_sel_hi:[1,0,1]
	v_mul_f32_e32 v136, v139, v136
	v_mul_f32_e32 v133, v133, v136
	s_nop 0
	v_cvt_pk_bf16_f32 v132, v132, v133
	v_mul_f32_e32 v133, 0xbfb8aa3b, v140
	v_exp_f32_e32 v133, v133
	v_lshlrev_b64 v[136:137], 1, v[170:171]
	v_pk_fma_f32 v[48:49], v[48:49], v[162:163], v[76:77] op_sel_hi:[1,0,1]
	v_pk_fma_f32 v[40:41], v[40:41], v[162:163], v[80:81] op_sel_hi:[1,0,1]
	v_add_f32_e32 v133, 1.0, v133
	v_rcp_f32_e32 v133, v133
	v_pk_fma_f32 v[42:43], v[42:43], v[162:163], v[66:67] op_sel_hi:[1,0,1]
	v_pk_fma_f32 v[44:45], v[44:45], v[162:163], v[68:69] op_sel_hi:[1,0,1]
	v_pk_fma_f32 v[30:31], v[30:31], v[160:161], v[74:75] op_sel_hi:[1,0,1]
	v_mul_f32_e32 v133, v140, v133
	v_mul_f32_e32 v133, v134, v133
	v_mul_f32_e32 v134, 0xbfb8aa3b, v141
	v_exp_f32_e32 v134, v134
	v_pk_fma_f32 v[22:23], v[22:23], v[160:161], v[78:79] op_sel_hi:[1,0,1]
	v_pk_fma_f32 v[32:33], v[32:33], v[160:161], v[76:77] op_sel_hi:[1,0,1]
	v_pk_fma_f32 v[24:25], v[24:25], v[160:161], v[80:81] op_sel_hi:[1,0,1]
	v_add_f32_e32 v134, 1.0, v134
	v_rcp_f32_e32 v134, v134
	v_pk_fma_f32 v[26:27], v[26:27], v[160:161], v[66:67] op_sel_hi:[1,0,1]
	v_pk_fma_f32 v[28:29], v[28:29], v[160:161], v[68:69] op_sel_hi:[1,0,1]
	v_pk_fma_f32 v[14:15], v[14:15], v[158:159], v[74:75] op_sel_hi:[1,0,1]
	v_mul_f32_e32 v134, v141, v134
	v_mul_f32_e32 v134, v135, v134
	s_nop 0
	v_cvt_pk_bf16_f32 v133, v133, v134
	v_mov_b64_e32 v[134:135], s[6:7]
	v_mad_i64_i32 v[138:139], s[18:19], v156, s74, v[134:135]
	v_lshl_add_u64 v[138:139], v[138:139], 0, v[136:137]
	global_store_dwordx4 v[138:139], v[130:133], off
	v_pk_fma_f32 v[6:7], v[6:7], v[158:159], v[78:79] op_sel_hi:[1,0,1]
	v_pk_fma_f32 v[16:17], v[16:17], v[158:159], v[76:77] op_sel_hi:[1,0,1]
	v_pk_fma_f32 v[130:131], v[116:117], v[172:173], v[72:73] op_sel_hi:[1,0,1]
	v_pk_fma_f32 v[116:117], v[114:115], v[172:173], v[70:71] op_sel_hi:[1,0,1]
	v_mul_f32_e32 v114, 0xbfb8aa3b, v126
	v_mul_f32_e32 v115, 0xbfb8aa3b, v127
; __device__ __forceinline__ unsigned cvt_pk_bf16(float lo, float hi) { unsigned r; asm volatile("s_nop 0\n\tv_cvt_pk_bf16_f32 %0, %1, %2" : "=v"(r) : "v"(lo), "v"(hi)); return r; }
; __device__ __forceinline__ float siluf_(float x) { return x * __builtin_amdgcn_rcpf(1.f + __expf(-x)); }
;     __device__ __forceinline__ void operator()(const f32x4 (&acc)[2][2][4][2], const Unit& u, int wr, int wc, int fr, int fq) const {
;     ...
;             for (int m = 0; m < 4; ++m) { const int r = row0 + ai * 128 + m * 16;
;                 const float rstd = ai ? rb[m] : ra[m];
;                 const f32x4 g0 = acc[ai][0][m][0] * rstd + sg0, g1 = acc[ai][0][m][1] * rstd + sg1, u0 = acc[ai][1][m][0] * rstd + su0, u1 = acc[ai][1][m][1] * rstd + su1;
;                 uint4 st; st.x = cvt_pk_bf16(siluf_(g0[0]) * u0[0], siluf_(g0[1]) * u0[1]); st.y = cvt_pk_bf16(siluf_(g0[2]) * u0[2], siluf_(g0[3]) * u0[3]);
;                 st.z = cvt_pk_bf16(siluf_(g1[0]) * u1[0], siluf_(g1[1]) * u1[1]); st.w = cvt_pk_bf16(siluf_(g1[2]) * u1[2], siluf_(g1[3]) * u1[3]);
;                 *(uint4*)(hid + (size_t)r * DFF + hc0) = st; }
	v_exp_f32_e32 v114, v114
	v_exp_f32_e32 v115, v115
	v_or_b32_e32 v132, 16, v156
	v_pk_fma_f32 v[8:9], v[8:9], v[158:159], v[80:81] op_sel_hi:[1,0,1]
	v_add_f32_e32 v114, 1.0, v114
	v_add_f32_e32 v115, 1.0, v115
	v_rcp_f32_e32 v114, v114
	v_rcp_f32_e32 v115, v115
	v_pk_fma_f32 v[10:11], v[10:11], v[158:159], v[66:67] op_sel_hi:[1,0,1]
	v_pk_fma_f32 v[12:13], v[12:13], v[158:159], v[68:69] op_sel_hi:[1,0,1]
	v_mul_f32_e32 v114, v126, v114
	v_mul_f32_e32 v115, v127, v115
	v_mul_f32_e32 v114, v118, v114
	v_mul_f32_e32 v115, v119, v115
	s_nop 0
	v_cvt_pk_bf16_f32 v114, v114, v115
	v_mul_f32_e32 v115, 0xbfb8aa3b, v128
	v_mul_f32_e32 v118, 0xbfb8aa3b, v129
	v_exp_f32_e32 v115, v115
	v_exp_f32_e32 v118, v118
	v_add_f32_e32 v115, 1.0, v115
	v_add_f32_e32 v118, 1.0, v118
	v_rcp_f32_e32 v115, v115
	v_rcp_f32_e32 v118, v118
	v_mul_f32_e32 v115, v128, v115
	v_mul_f32_e32 v118, v129, v118
	v_mul_f32_e32 v115, v120, v115
	v_mul_f32_e32 v118, v121, v118
	s_nop 0
	v_cvt_pk_bf16_f32 v115, v115, v118
	v_mul_f32_e32 v118, 0xbfb8aa3b, v122
	v_exp_f32_e32 v118, v118
	s_nop 0
	v_add_f32_e32 v118, 1.0, v118
	v_rcp_f32_e32 v118, v118
	s_nop 0
	v_mul_f32_e32 v118, v122, v118
	v_mul_f32_e32 v116, v116, v118
	v_mul_f32_e32 v118, 0xbfb8aa3b, v123
	v_exp_f32_e32 v118, v118
	s_nop 0
	v_add_f32_e32 v118, 1.0, v118
	v_rcp_f32_e32 v118, v118
	s_nop 0
	v_mul_f32_e32 v118, v123, v118
	v_mul_f32_e32 v117, v117, v118
	s_nop 0
	v_cvt_pk_bf16_f32 v116, v116, v117
	v_mul_f32_e32 v117, 0xbfb8aa3b, v124
	v_mul_f32_e32 v118, 0xbfb8aa3b, v125
	v_exp_f32_e32 v117, v117
	v_exp_f32_e32 v118, v118
	v_add_f32_e32 v117, 1.0, v117
	v_add_f32_e32 v118, 1.0, v118
	v_rcp_f32_e32 v117, v117
	v_rcp_f32_e32 v118, v118
	v_mul_f32_e32 v117, v124, v117
	v_mul_f32_e32 v118, v125, v118
	v_mul_f32_e32 v117, v130, v117
	v_mul_f32_e32 v118, v131, v118
	s_nop 0
	v_cvt_pk_bf16_f32 v117, v117, v118
	v_mad_i64_i32 v[118:119], s[18:19], v132, s74, v[134:135]
	v_lshl_add_u64 v[118:119], v[118:119], 0, v[136:137]
	global_store_dwordx4 v[118:119], v[114:117], off
	s_nop 1
	v_pk_fma_f32 v[114:115], v[100:101], v[168:169], v[72:73] op_sel_hi:[1,0,1]
	v_pk_fma_f32 v[100:101], v[98:99], v[168:169], v[70:71] op_sel_hi:[1,0,1]
	v_mul_f32_e32 v98, 0xbfb8aa3b, v110
	v_mul_f32_e32 v99, 0xbfb8aa3b, v111
	v_exp_f32_e32 v98, v98
	v_exp_f32_e32 v99, v99
	v_or_b32_e32 v116, 32, v156
	v_add_f32_e32 v98, 1.0, v98
	v_add_f32_e32 v99, 1.0, v99
	v_rcp_f32_e32 v98, v98
	v_rcp_f32_e32 v99, v99
	v_mul_f32_e32 v98, v110, v98
	v_mul_f32_e32 v99, v111, v99
	v_mul_f32_e32 v98, v102, v98
	v_mul_f32_e32 v99, v103, v99
	s_nop 0
	v_cvt_pk_bf16_f32 v98, v98, v99
	v_mul_f32_e32 v99, 0xbfb8aa3b, v112
	v_mul_f32_e32 v102, 0xbfb8aa3b, v113
	v_exp_f32_e32 v99, v99
	v_exp_f32_e32 v102, v102
	v_add_f32_e32 v99, 1.0, v99
	v_add_f32_e32 v102, 1.0, v102
	v_rcp_f32_e32 v99, v99
	v_rcp_f32_e32 v102, v102
	v_mul_f32_e32 v99, v112, v99
	v_mul_f32_e32 v102, v113, v102
	v_mul_f32_e32 v99, v104, v99
	v_mul_f32_e32 v102, v105, v102
	s_nop 0
	v_cvt_pk_bf16_f32 v99, v99, v102
	v_mul_f32_e32 v102, 0xbfb8aa3b, v106
	v_exp_f32_e32 v102, v102
	s_nop 0
	v_add_f32_e32 v102, 1.0, v102
	v_rcp_f32_e32 v102, v102
	s_nop 0
	v_mul_f32_e32 v102, v106, v102
	v_mul_f32_e32 v100, v100, v102
	v_mul_f32_e32 v102, 0xbfb8aa3b, v107
	v_exp_f32_e32 v102, v102
	s_nop 0
	v_add_f32_e32 v102, 1.0, v102
	v_rcp_f32_e32 v102, v102
	s_nop 0
	v_mul_f32_e32 v102, v107, v102
	v_mul_f32_e32 v101, v101, v102
	s_nop 0
	v_cvt_pk_bf16_f32 v100, v100, v101
	v_mul_f32_e32 v101, 0xbfb8aa3b, v108
	v_mul_f32_e32 v102, 0xbfb8aa3b, v109
	v_exp_f32_e32 v101, v101
	v_exp_f32_e32 v102, v102
	v_add_f32_e32 v101, 1.0, v101
	v_add_f32_e32 v102, 1.0, v102
	v_rcp_f32_e32 v101, v101
	v_rcp_f32_e32 v102, v102
	v_mul_f32_e32 v101, v108, v101
	v_mul_f32_e32 v102, v109, v102
	v_mul_f32_e32 v101, v114, v101
	v_mul_f32_e32 v102, v115, v102
	s_nop 0
	v_cvt_pk_bf16_f32 v101, v101, v102
	v_mad_i64_i32 v[102:103], s[18:19], v116, s74, v[134:135]
	v_lshl_add_u64 v[102:103], v[102:103], 0, v[136:137]
	global_store_dwordx4 v[102:103], v[98:101], off
	s_nop 1
	v_pk_fma_f32 v[98:99], v[84:85], v[166:167], v[72:73] op_sel_hi:[1,0,1]
	v_pk_fma_f32 v[84:85], v[82:83], v[166:167], v[70:71] op_sel_hi:[1,0,1]
	v_mul_f32_e32 v82, 0xbfb8aa3b, v94
	v_mul_f32_e32 v83, 0xbfb8aa3b, v95
	v_exp_f32_e32 v82, v82
	v_exp_f32_e32 v83, v83
	v_or_b32_e32 v100, 48, v156
	v_add_f32_e32 v82, 1.0, v82
	v_add_f32_e32 v83, 1.0, v83
	v_rcp_f32_e32 v82, v82
	v_rcp_f32_e32 v83, v83
	v_mul_f32_e32 v82, v94, v82
	v_mul_f32_e32 v83, v95, v83
	v_mul_f32_e32 v82, v86, v82
	v_mul_f32_e32 v83, v87, v83
	s_nop 0
	v_cvt_pk_bf16_f32 v82, v82, v83
	v_mul_f32_e32 v83, 0xbfb8aa3b, v96
	v_mul_f32_e32 v86, 0xbfb8aa3b, v97
	v_exp_f32_e32 v83, v83
	v_exp_f32_e32 v86, v86
	v_add_f32_e32 v83, 1.0, v83
	v_add_f32_e32 v86, 1.0, v86
	v_rcp_f32_e32 v83, v83
	v_rcp_f32_e32 v86, v86
	v_mul_f32_e32 v83, v96, v83
	v_mul_f32_e32 v86, v97, v86
	v_mul_f32_e32 v83, v88, v83
	v_mul_f32_e32 v86, v89, v86
	s_nop 0
	v_cvt_pk_bf16_f32 v83, v83, v86
	v_mul_f32_e32 v86, 0xbfb8aa3b, v90
	v_exp_f32_e32 v86, v86
	s_nop 0
	v_add_f32_e32 v86, 1.0, v86
	v_rcp_f32_e32 v86, v86
	s_nop 0
	v_mul_f32_e32 v86, v90, v86
	v_mul_f32_e32 v84, v84, v86
	v_mul_f32_e32 v86, 0xbfb8aa3b, v91
	v_exp_f32_e32 v86, v86
	s_nop 0
	v_add_f32_e32 v86, 1.0, v86
	v_rcp_f32_e32 v86, v86
	s_nop 0
	v_mul_f32_e32 v86, v91, v86
	v_mul_f32_e32 v85, v85, v86
	s_nop 0
	v_cvt_pk_bf16_f32 v84, v84, v85
	v_mul_f32_e32 v85, 0xbfb8aa3b, v92
	v_mul_f32_e32 v86, 0xbfb8aa3b, v93
	v_exp_f32_e32 v85, v85
	v_exp_f32_e32 v86, v86
	v_add_f32_e32 v85, 1.0, v85
	v_add_f32_e32 v86, 1.0, v86
	v_rcp_f32_e32 v85, v85
	v_rcp_f32_e32 v86, v86
; __device__ __forceinline__ unsigned cvt_pk_bf16(float lo, float hi) { unsigned r; asm volatile("s_nop 0\n\tv_cvt_pk_bf16_f32 %0, %1, %2" : "=v"(r) : "v"(lo), "v"(hi)); return r; }
; __device__ __forceinline__ float siluf_(float x) { return x * __builtin_amdgcn_rcpf(1.f + __expf(-x)); }
;     __device__ __forceinline__ void operator()(const f32x4 (&acc)[2][2][4][2], const Unit& u, int wr, int wc, int fr, int fq) const {
;     ...
;             for (int m = 0; m < 4; ++m) { const int r = row0 + ai * 128 + m * 16;
;                 const float rstd = ai ? rb[m] : ra[m];
;                 const f32x4 g0 = acc[ai][0][m][0] * rstd + sg0, g1 = acc[ai][0][m][1] * rstd + sg1, u0 = acc[ai][1][m][0] * rstd + su0, u1 = acc[ai][1][m][1] * rstd + su1;
;                 uint4 st; st.x = cvt_pk_bf16(siluf_(g0[0]) * u0[0], siluf_(g0[1]) * u0[1]); st.y = cvt_pk_bf16(siluf_(g0[2]) * u0[2], siluf_(g0[3]) * u0[3]);
;                 st.z = cvt_pk_bf16(siluf_(g1[0]) * u1[0], siluf_(g1[1]) * u1[1]); st.w = cvt_pk_bf16(siluf_(g1[2]) * u1[2], siluf_(g1[3]) * u1[3]);
;                 *(uint4*)(hid + (size_t)r * DFF + hc0) = st; }
	v_mul_f32_e32 v85, v92, v85
	v_mul_f32_e32 v86, v93, v86
	v_mul_f32_e32 v85, v98, v85
	v_mul_f32_e32 v86, v99, v86
	s_nop 0
	v_cvt_pk_bf16_f32 v85, v85, v86
	v_mad_i64_i32 v[86:87], s[18:19], v100, s74, v[134:135]
	v_lshl_add_u64 v[86:87], v[86:87], 0, v[136:137]
	global_store_dwordx4 v[86:87], v[82:85], off
	s_nop 1
	v_pk_fma_f32 v[82:83], v[52:53], v[164:165], v[72:73] op_sel_hi:[1,0,1]
	v_pk_fma_f32 v[52:53], v[50:51], v[164:165], v[70:71] op_sel_hi:[1,0,1]
	v_mul_f32_e32 v50, 0xbfb8aa3b, v62
	v_mul_f32_e32 v51, 0xbfb8aa3b, v63
	v_exp_f32_e32 v50, v50
	v_exp_f32_e32 v51, v51
	v_add_u32_e32 v84, 0x80, v156
	v_add_f32_e32 v50, 1.0, v50
	v_add_f32_e32 v51, 1.0, v51
	v_rcp_f32_e32 v50, v50
	v_rcp_f32_e32 v51, v51
	v_mul_f32_e32 v50, v62, v50
	v_mul_f32_e32 v51, v63, v51
	v_mul_f32_e32 v50, v54, v50
	v_mul_f32_e32 v51, v55, v51
	s_nop 0
	v_cvt_pk_bf16_f32 v50, v50, v51
	v_mul_f32_e32 v51, 0xbfb8aa3b, v64
	v_mul_f32_e32 v54, 0xbfb8aa3b, v65
	v_exp_f32_e32 v51, v51
	v_exp_f32_e32 v54, v54
	v_add_f32_e32 v51, 1.0, v51
	v_add_f32_e32 v54, 1.0, v54
	v_rcp_f32_e32 v51, v51
	v_rcp_f32_e32 v54, v54
	v_mul_f32_e32 v51, v64, v51
	v_mul_f32_e32 v54, v65, v54
	v_mul_f32_e32 v51, v56, v51
	v_mul_f32_e32 v54, v57, v54
	s_nop 0
	v_cvt_pk_bf16_f32 v51, v51, v54
	v_mul_f32_e32 v54, 0xbfb8aa3b, v58
	v_exp_f32_e32 v54, v54
	s_nop 0
	v_add_f32_e32 v54, 1.0, v54
	v_rcp_f32_e32 v54, v54
	s_nop 0
	v_mul_f32_e32 v54, v58, v54
	v_mul_f32_e32 v52, v52, v54
	v_mul_f32_e32 v54, 0xbfb8aa3b, v59
	v_exp_f32_e32 v54, v54
	s_nop 0
	v_add_f32_e32 v54, 1.0, v54
	v_rcp_f32_e32 v54, v54
	s_nop 0
	v_mul_f32_e32 v54, v59, v54
	v_mul_f32_e32 v53, v53, v54
	s_nop 0
	v_cvt_pk_bf16_f32 v52, v52, v53
	v_mul_f32_e32 v53, 0xbfb8aa3b, v60
	v_mul_f32_e32 v54, 0xbfb8aa3b, v61
	v_exp_f32_e32 v53, v53
	v_exp_f32_e32 v54, v54
	v_add_f32_e32 v53, 1.0, v53
	v_add_f32_e32 v54, 1.0, v54
	v_rcp_f32_e32 v53, v53
	v_rcp_f32_e32 v54, v54
	v_mul_f32_e32 v53, v60, v53
	v_mul_f32_e32 v54, v61, v54
	v_mul_f32_e32 v53, v82, v53
	v_mul_f32_e32 v54, v83, v54
	s_nop 0
	v_cvt_pk_bf16_f32 v53, v53, v54
	v_mad_i64_i32 v[54:55], s[18:19], v84, s74, v[134:135]
	v_lshl_add_u64 v[54:55], v[54:55], 0, v[136:137]
	global_store_dwordx4 v[54:55], v[50:53], off
	s_nop 1
	v_pk_fma_f32 v[50:51], v[36:37], v[162:163], v[72:73] op_sel_hi:[1,0,1]
	v_pk_fma_f32 v[36:37], v[34:35], v[162:163], v[70:71] op_sel_hi:[1,0,1]
	v_mul_f32_e32 v34, 0xbfb8aa3b, v46
	v_mul_f32_e32 v35, 0xbfb8aa3b, v47
	v_exp_f32_e32 v34, v34
	v_exp_f32_e32 v35, v35
	v_add_u32_e32 v52, 0x90, v156
	v_add_f32_e32 v34, 1.0, v34
	v_add_f32_e32 v35, 1.0, v35
	v_rcp_f32_e32 v34, v34
	v_rcp_f32_e32 v35, v35
	v_mul_f32_e32 v34, v46, v34
	v_mul_f32_e32 v35, v47, v35
	v_mul_f32_e32 v34, v38, v34
	v_mul_f32_e32 v35, v39, v35
	s_nop 0
	v_cvt_pk_bf16_f32 v34, v34, v35
	v_mul_f32_e32 v35, 0xbfb8aa3b, v48
	v_mul_f32_e32 v38, 0xbfb8aa3b, v49
	v_exp_f32_e32 v35, v35
	v_exp_f32_e32 v38, v38
	v_add_f32_e32 v35, 1.0, v35
	v_add_f32_e32 v38, 1.0, v38
	v_rcp_f32_e32 v35, v35
	v_rcp_f32_e32 v38, v38
	v_mul_f32_e32 v35, v48, v35
	v_mul_f32_e32 v38, v49, v38
	v_mul_f32_e32 v35, v40, v35
	v_mul_f32_e32 v38, v41, v38
	s_nop 0
	v_cvt_pk_bf16_f32 v35, v35, v38
	v_mul_f32_e32 v38, 0xbfb8aa3b, v42
	v_exp_f32_e32 v38, v38
	s_nop 0
	v_add_f32_e32 v38, 1.0, v38
	v_rcp_f32_e32 v38, v38
	s_nop 0
	v_mul_f32_e32 v38, v42, v38
	v_mul_f32_e32 v36, v36, v38
	v_mul_f32_e32 v38, 0xbfb8aa3b, v43
	v_exp_f32_e32 v38, v38
	s_nop 0
	v_add_f32_e32 v38, 1.0, v38
	v_rcp_f32_e32 v38, v38
	s_nop 0
	v_mul_f32_e32 v38, v43, v38
	v_mul_f32_e32 v37, v37, v38
	s_nop 0
	v_cvt_pk_bf16_f32 v36, v36, v37
	v_mul_f32_e32 v37, 0xbfb8aa3b, v44
	v_mul_f32_e32 v38, 0xbfb8aa3b, v45
	v_exp_f32_e32 v37, v37
	v_exp_f32_e32 v38, v38
	v_add_f32_e32 v37, 1.0, v37
	v_add_f32_e32 v38, 1.0, v38
	v_rcp_f32_e32 v37, v37
	v_rcp_f32_e32 v38, v38
	v_mul_f32_e32 v37, v44, v37
	v_mul_f32_e32 v38, v45, v38
	v_mul_f32_e32 v37, v50, v37
	v_mul_f32_e32 v38, v51, v38
	s_nop 0
	v_cvt_pk_bf16_f32 v37, v37, v38
; __device__ __forceinline__ unsigned cvt_pk_bf16(float lo, float hi) { unsigned r; asm volatile("s_nop 0\n\tv_cvt_pk_bf16_f32 %0, %1, %2" : "=v"(r) : "v"(lo), "v"(hi)); return r; }
; __device__ __forceinline__ float siluf_(float x) { return x * __builtin_amdgcn_rcpf(1.f + __expf(-x)); }
; #define PG8_WAIT_V(n) asm volatile("s_waitcnt vmcnt(" #n ")" ::: "memory")
; #define PG8_BAR __builtin_amdgcn_s_barrier()
; template <class Epi>
; __device__ __forceinline__ void gemm_phase(LAS unsigned char* lds, const Gemm g, const StaticOrder& S, const Epi& E) {
;     ...
;         E(acc, cur, wr, wc, fr, fq);
;         if (!has_next) break;
; #pragma unroll
;         for (int a = 0; a < 2; ++a)
; #pragma unroll
;             for (int b = 0; b < 2; ++b)
; #pragma unroll
;                 for (int m = 0; m < 4; ++m)
; #pragma unroll
;                     for (int n = 0; n < 2; ++n) acc[a][b][m][n] = (f32x4){0.f, 0.f, 0.f, 0.f};
;         cur = nxt; cA = nA; cB = nB; ++ui;
;     }
;     PG8_WAIT_V(0);
;     if (wr == 0) PG8_BAR;
;     PG8_BAR;
;     __device__ __forceinline__ void operator()(const f32x4 (&acc)[2][2][4][2], const Unit& u, int wr, int wc, int fr, int fq) const {
;     ...
;             for (int m = 0; m < 4; ++m) { const int r = row0 + ai * 128 + m * 16;
;                 const float rstd = ai ? rb[m] : ra[m];
;                 const f32x4 g0 = acc[ai][0][m][0] * rstd + sg0, g1 = acc[ai][0][m][1] * rstd + sg1, u0 = acc[ai][1][m][0] * rstd + su0, u1 = acc[ai][1][m][1] * rstd + su1;
;                 uint4 st; st.x = cvt_pk_bf16(siluf_(g0[0]) * u0[0], siluf_(g0[1]) * u0[1]); st.y = cvt_pk_bf16(siluf_(g0[2]) * u0[2], siluf_(g0[3]) * u0[3]);
;                 st.z = cvt_pk_bf16(siluf_(g1[0]) * u1[0], siluf_(g1[1]) * u1[1]); st.w = cvt_pk_bf16(siluf_(g1[2]) * u1[2], siluf_(g1[3]) * u1[3]);
;                 *(uint4*)(hid + (size_t)r * DFF + hc0) = st; }
	v_mad_i64_i32 v[38:39], s[18:19], v52, s74, v[134:135]
	v_lshl_add_u64 v[38:39], v[38:39], 0, v[136:137]
	global_store_dwordx4 v[38:39], v[34:37], off
	s_nop 1
	v_pk_fma_f32 v[34:35], v[20:21], v[160:161], v[72:73] op_sel_hi:[1,0,1]
	v_pk_fma_f32 v[20:21], v[18:19], v[160:161], v[70:71] op_sel_hi:[1,0,1]
	v_mul_f32_e32 v18, 0xbfb8aa3b, v30
	v_mul_f32_e32 v19, 0xbfb8aa3b, v31
	v_exp_f32_e32 v18, v18
	v_exp_f32_e32 v19, v19
	v_add_u32_e32 v36, 0xa0, v156
	v_add_f32_e32 v18, 1.0, v18
	v_add_f32_e32 v19, 1.0, v19
	v_rcp_f32_e32 v18, v18
	v_rcp_f32_e32 v19, v19
	v_mul_f32_e32 v18, v30, v18
	v_mul_f32_e32 v19, v31, v19
	v_mul_f32_e32 v18, v22, v18
	v_mul_f32_e32 v19, v23, v19
	s_nop 0
	v_cvt_pk_bf16_f32 v18, v18, v19
	v_mul_f32_e32 v19, 0xbfb8aa3b, v32
	v_mul_f32_e32 v22, 0xbfb8aa3b, v33
	v_exp_f32_e32 v19, v19
	v_exp_f32_e32 v22, v22
	v_add_f32_e32 v19, 1.0, v19
	v_add_f32_e32 v22, 1.0, v22
	v_rcp_f32_e32 v19, v19
	v_rcp_f32_e32 v22, v22
	v_mul_f32_e32 v19, v32, v19
	v_mul_f32_e32 v22, v33, v22
	v_mul_f32_e32 v19, v24, v19
	v_mul_f32_e32 v22, v25, v22
	s_nop 0
	v_cvt_pk_bf16_f32 v19, v19, v22
	v_mul_f32_e32 v22, 0xbfb8aa3b, v26
	v_exp_f32_e32 v22, v22
	s_nop 0
	v_add_f32_e32 v22, 1.0, v22
	v_rcp_f32_e32 v22, v22
	s_nop 0
	v_mul_f32_e32 v22, v26, v22
	v_mul_f32_e32 v20, v20, v22
	v_mul_f32_e32 v22, 0xbfb8aa3b, v27
	v_exp_f32_e32 v22, v22
	s_nop 0
	v_add_f32_e32 v22, 1.0, v22
	v_rcp_f32_e32 v22, v22
	s_nop 0
	v_mul_f32_e32 v22, v27, v22
	v_mul_f32_e32 v21, v21, v22
	s_nop 0
	v_cvt_pk_bf16_f32 v20, v20, v21
	v_mul_f32_e32 v21, 0xbfb8aa3b, v28
	v_mul_f32_e32 v22, 0xbfb8aa3b, v29
	v_exp_f32_e32 v21, v21
	v_exp_f32_e32 v22, v22
	v_add_f32_e32 v21, 1.0, v21
	v_add_f32_e32 v22, 1.0, v22
	v_rcp_f32_e32 v21, v21
	v_rcp_f32_e32 v22, v22
	v_mul_f32_e32 v21, v28, v21
	v_mul_f32_e32 v22, v29, v22
	v_mul_f32_e32 v21, v34, v21
	v_mul_f32_e32 v22, v35, v22
	s_nop 0
	v_cvt_pk_bf16_f32 v21, v21, v22
	v_mad_i64_i32 v[22:23], s[18:19], v36, s74, v[134:135]
	v_lshl_add_u64 v[22:23], v[22:23], 0, v[136:137]
	global_store_dwordx4 v[22:23], v[18:21], off
	s_nop 1
	v_pk_fma_f32 v[18:19], v[2:3], v[158:159], v[72:73] op_sel_hi:[1,0,1]
	v_pk_fma_f32 v[2:3], v[0:1], v[158:159], v[70:71] op_sel_hi:[1,0,1]
	v_mul_f32_e32 v0, 0xbfb8aa3b, v14
	v_mul_f32_e32 v1, 0xbfb8aa3b, v15
	v_exp_f32_e32 v0, v0
	v_exp_f32_e32 v1, v1
	v_add_u32_e32 v20, 0xb0, v156
	v_add_f32_e32 v0, 1.0, v0
	v_add_f32_e32 v1, 1.0, v1
	v_rcp_f32_e32 v0, v0
	v_rcp_f32_e32 v1, v1
	v_mul_f32_e32 v0, v14, v0
	v_mul_f32_e32 v1, v15, v1
	v_mul_f32_e32 v0, v6, v0
	v_mul_f32_e32 v1, v7, v1
	s_nop 0
	v_cvt_pk_bf16_f32 v0, v0, v1
	v_mul_f32_e32 v1, 0xbfb8aa3b, v16
	v_mul_f32_e32 v6, 0xbfb8aa3b, v17
	v_exp_f32_e32 v1, v1
	v_exp_f32_e32 v6, v6
	v_add_f32_e32 v1, 1.0, v1
	v_add_f32_e32 v6, 1.0, v6
	v_rcp_f32_e32 v1, v1
	v_rcp_f32_e32 v6, v6
	v_mul_f32_e32 v1, v16, v1
	v_mul_f32_e32 v6, v17, v6
	v_mul_f32_e32 v1, v8, v1
	v_mul_f32_e32 v6, v9, v6
	s_nop 0
	v_cvt_pk_bf16_f32 v1, v1, v6
	v_mul_f32_e32 v6, 0xbfb8aa3b, v10
	v_exp_f32_e32 v6, v6
	s_nop 0
	v_add_f32_e32 v6, 1.0, v6
	v_rcp_f32_e32 v6, v6
	s_nop 0
	v_mul_f32_e32 v6, v10, v6
	v_mul_f32_e32 v2, v2, v6
	v_mul_f32_e32 v6, 0xbfb8aa3b, v11
	v_exp_f32_e32 v6, v6
	s_nop 0
	v_add_f32_e32 v6, 1.0, v6
	v_rcp_f32_e32 v6, v6
	s_nop 0
	v_mul_f32_e32 v6, v11, v6
	v_mul_f32_e32 v3, v3, v6
	s_nop 0
	v_cvt_pk_bf16_f32 v2, v2, v3
	v_mul_f32_e32 v3, 0xbfb8aa3b, v12
	v_mul_f32_e32 v6, 0xbfb8aa3b, v13
	v_exp_f32_e32 v3, v3
	v_exp_f32_e32 v6, v6
	v_add_f32_e32 v3, 1.0, v3
	v_add_f32_e32 v6, 1.0, v6
	v_rcp_f32_e32 v3, v3
	v_rcp_f32_e32 v6, v6
	v_mul_f32_e32 v3, v12, v3
	v_mul_f32_e32 v6, v13, v6
	v_mul_f32_e32 v3, v18, v3
	v_mul_f32_e32 v6, v19, v6
	s_nop 0
	v_cvt_pk_bf16_f32 v3, v3, v6
	v_mad_i64_i32 v[6:7], s[18:19], v20, s74, v[134:135]
	v_lshl_add_u64 v[6:7], v[6:7], 0, v[136:137]
	s_mov_b64 s[18:19], s[14:15]
	global_store_dwordx4 v[6:7], v[0:3], off
	s_cbranch_vccz .LBB0_2894
	s_waitcnt vmcnt(0)
	s_cmpk_gt_u32 s24, 0xff
	s_cbranch_scc1 .LBB0_2901
	s_barrier

; #define PG8_STAGE(bufoff, gbase, voff) do { _Pragma("unroll") for (int _i = 0; _i < 2; ++_i) \
;         __builtin_amdgcn_global_load_lds((const unsigned*)((const char*)(gbase) + (voff)[_i]), (LAS unsigned*)(lds + (bufoff) + ldsw + _i * 8192), 16, 0, 0); } while (0)
; #define PG8_LDA(dst, b, h) do { _Pragma("unroll") for (int m = 0; m < 4; ++m) _Pragma("unroll") for (int k = 0; k < 2; ++k) dst[m][k] = *(const LAS bf16x8*)(lds + PG8_SA(b, h) + aoff + m * 2048 + k * 1024); } while (0)
; #define PG8_LDB(dst, b, h) do { _Pragma("unroll") for (int n = 0; n < 2; ++n) _Pragma("unroll") for (int k = 0; k < 2; ++k) dst[n][k] = *(const LAS bf16x8*)(lds + PG8_SB(b, h) + boff + n * 2048 + k * 1024); } while (0)
; #define PG8_MMA(ai, bj, At, Bt) do { __builtin_amdgcn_s_setprio(1); _Pragma("unroll") for (int m = 0; m < 4; ++m) _Pragma("unroll") for (int n = 0; n < 2; ++n) _Pragma("unroll") for (int k = 0; k < 2; ++k) \
;         acc[ai][bj][m][n] = __builtin_amdgcn_mfma_f32_16x16x32_bf16(Bt[n][k], At[m][k], acc[ai][bj][m][n], 0, 0, 0); __builtin_amdgcn_s_setprio(0); } while (0)
; #define PG8_WAIT_L(n) asm volatile("s_waitcnt lgkmcnt(" #n ")" ::: "memory")
; #define PG8_BAR __builtin_amdgcn_s_barrier()
; template <class Epi>
; __device__ __forceinline__ void gemm_phase(LAS unsigned char* lds, const Gemm g, const StaticOrder& S, const Epi& E) {
;     ...
;         const char* nA = has_next ? (const char*)g.A + (size_t)nxt.pm * tstep : cA; const char* nB = has_next ? (const char*)g.Bt + (size_t)nxt.pn * tstep : cB;
;         for (int t = 0; t < nt; t += 2) {
;             const bool last = (t == nt - 2);
;             const char* a1 = cA + (size_t)(t + 1) * kstep;
;             const char* a2 = last ? nA : cA + (size_t)(t + 2) * kstep; const char* b2 = last ? nB : cB + (size_t)(t + 2) * kstep;
;             const char* a3 = a2 + kstep; const char* b3 = b2 + kstep;
;             PG8_LDB(B0, 0, 0); PG8_SCHED; PG8_LDA(At, 0, 0); PG8_STAGE(PG8_SA(1, 1), a1 + hstep, voffA);
;             PG8_WAIT_L(8); PG8_BAR; PG8_WAIT_L(0); PG8_MMA(0, 0, At, B0); PG8_BAR; PG8_SCHED;
;             PG8_LDB(B1, 0, 1); PG8_STAGE(PG8_SB(0, 0), b2, voffB);
;             PG8_BAR; PG8_WAIT_L(0); PG8_MMA(0, 1, At, B1); PG8_BAR;
;             PG8_LDA(At, 0, 1); PG8_STAGE(PG8_SA(0, 0), a2, voffA);
;             PG8_BAR; PG8_WAIT_L(0); PG8_MMA(1, 0, At, B0); PG8_BAR; PG8_SCHED;
.LBB0_2974:
	s_add_i32 s64, s26, 2
	s_add_u32 s0, s8, 0x80
	s_addc_u32 s1, s9, 0
	s_add_i32 s65, 0, 0x10000
	v_add_u32_e32 v4, s65, v245
	ds_read_b128 v[132:135], v4
	ds_read_b128 v[136:139], v4 offset:1024
	ds_read_b128 v[140:143], v4 offset:2048
	ds_read_b128 v[144:147], v4 offset:3072
	s_cmp_eq_u32 s57, s26
	s_cselect_b32 s26, s24, s0
	s_cselect_b32 s27, s25, s1
	s_cselect_b32 s29, s11, s63
	s_cselect_b32 s28, s10, s62
	v_lshl_add_u64 v[6:7], s[8:9], 0, v[164:165]
	s_add_i32 m0, s39, 0xc000
	ds_read_b128 v[148:151], v249
	ds_read_b128 v[152:155], v249 offset:1024
	ds_read_b128 v[156:159], v249 offset:2048
	ds_read_b128 v[168:171], v249 offset:3072
	ds_read_b128 v[172:175], v249 offset:4096
	ds_read_b128 v[190:193], v249 offset:5120
	ds_read_b128 v[194:197], v249 offset:6144
	ds_read_b128 v[198:201], v249 offset:7168
	global_load_lds_dwordx4 v[6:7], off
	s_add_i32 m0, s39, 0xe000
	v_lshl_add_u64 v[6:7], s[8:9], 0, v[166:167]
	global_load_lds_dwordx4 v[6:7], off
	s_waitcnt lgkmcnt(8)
	s_barrier
	s_waitcnt lgkmcnt(0)
	v_mfma_f32_16x16x32_bf16 v[80:83], v[132:135], v[148:151], v[80:83]
	v_mfma_f32_16x16x32_bf16 v[104:107], v[140:143], v[148:151], v[104:107]
	v_mfma_f32_16x16x32_bf16 v[128:131], v[132:135], v[156:159], v[128:131]
	v_mfma_f32_16x16x32_bf16 v[100:103], v[140:143], v[156:159], v[100:103]
	v_mfma_f32_16x16x32_bf16 v[124:127], v[132:135], v[172:175], v[124:127]
	v_mfma_f32_16x16x32_bf16 v[96:99], v[140:143], v[172:175], v[96:99]
	v_mfma_f32_16x16x32_bf16 v[120:123], v[132:135], v[194:197], v[120:123]
	v_mfma_f32_16x16x32_bf16 v[88:91], v[140:143], v[194:197], v[88:91]
	v_mfma_f32_16x16x32_bf16 v[80:83], v[136:139], v[152:155], v[80:83]
	v_mfma_f32_16x16x32_bf16 v[104:107], v[144:147], v[152:155], v[104:107]
	v_mfma_f32_16x16x32_bf16 v[128:131], v[136:139], v[168:171], v[128:131]
	v_mfma_f32_16x16x32_bf16 v[100:103], v[144:147], v[168:171], v[100:103]
	v_mfma_f32_16x16x32_bf16 v[124:127], v[136:139], v[190:193], v[124:127]
	v_mfma_f32_16x16x32_bf16 v[96:99], v[144:147], v[190:193], v[96:99]
	v_mfma_f32_16x16x32_bf16 v[120:123], v[136:139], v[198:201], v[120:123]
	v_mfma_f32_16x16x32_bf16 v[88:91], v[144:147], v[198:201], v[88:91]
	s_barrier
	s_add_i32 s70, 0, 0x14000
	s_add_i32 s0, s65, s34
	v_add_u32_e32 v4, s70, v245
	v_lshl_add_u64 v[176:177], s[28:29], 0, v[162:163]
	s_mov_b32 m0, s0
	ds_read_b128 v[202:205], v4
	ds_read_b128 v[206:209], v4 offset:1024
	ds_read_b128 v[210:213], v4 offset:2048
	ds_read_b128 v[214:217], v4 offset:3072
	global_load_lds_dwordx4 v[176:177], off
	s_add_i32 m0, s0, 0x2000
	v_lshl_add_u64 v[186:187], s[28:29], 0, v[160:161]
	global_load_lds_dwordx4 v[186:187], off
	s_barrier
	s_waitcnt lgkmcnt(0)
	v_mfma_f32_16x16x32_bf16 v[64:67], v[202:205], v[148:151], v[64:67]
	v_mfma_f32_16x16x32_bf16 v[32:35], v[210:213], v[148:151], v[32:35]
	v_mfma_f32_16x16x32_bf16 v[60:63], v[202:205], v[156:159], v[60:63]
	v_mfma_f32_16x16x32_bf16 v[28:31], v[210:213], v[156:159], v[28:31]
	v_mfma_f32_16x16x32_bf16 v[56:59], v[202:205], v[172:175], v[56:59]
	v_mfma_f32_16x16x32_bf16 v[24:27], v[210:213], v[172:175], v[24:27]
	v_mfma_f32_16x16x32_bf16 v[52:55], v[202:205], v[194:197], v[52:55]
	v_mfma_f32_16x16x32_bf16 v[20:23], v[210:213], v[194:197], v[20:23]
	v_mfma_f32_16x16x32_bf16 v[64:67], v[206:209], v[152:155], v[64:67]
	v_mfma_f32_16x16x32_bf16 v[32:35], v[214:217], v[152:155], v[32:35]
	v_mfma_f32_16x16x32_bf16 v[60:63], v[206:209], v[168:171], v[60:63]
	v_mfma_f32_16x16x32_bf16 v[28:31], v[214:217], v[168:171], v[28:31]
	v_mfma_f32_16x16x32_bf16 v[56:59], v[206:209], v[190:193], v[56:59]
	v_mfma_f32_16x16x32_bf16 v[24:27], v[214:217], v[190:193], v[24:27]
	v_mfma_f32_16x16x32_bf16 v[52:55], v[206:209], v[198:201], v[52:55]
	v_mfma_f32_16x16x32_bf16 v[20:23], v[214:217], v[198:201], v[20:23]
	s_mov_b32 m0, s39
	v_lshl_add_u64 v[218:219], s[26:27], 0, v[162:163]
	s_barrier
	ds_read_b128 v[148:151], v249 offset:16384
	ds_read_b128 v[152:155], v249 offset:17408
	ds_read_b128 v[156:159], v249 offset:18432
	ds_read_b128 v[168:171], v249 offset:19456
	ds_read_b128 v[172:175], v249 offset:20480
	ds_read_b128 v[190:193], v249 offset:21504
	ds_read_b128 v[194:197], v249 offset:22528
	ds_read_b128 v[198:201], v249 offset:23552
	global_load_lds_dwordx4 v[218:219], off
	s_mov_b32 m0, s40
	v_lshl_add_u64 v[220:221], s[26:27], 0, v[160:161]
	global_load_lds_dwordx4 v[220:221], off
	s_barrier
	s_waitcnt lgkmcnt(0)
	v_mfma_f32_16x16x32_bf16 v[92:95], v[132:135], v[148:151], v[92:95]
	v_mfma_f32_16x16x32_bf16 v[84:87], v[140:143], v[148:151], v[84:87]
	v_mfma_f32_16x16x32_bf16 v[116:119], v[132:135], v[156:159], v[116:119]
	v_mfma_f32_16x16x32_bf16 v[76:79], v[140:143], v[156:159], v[76:79]
	v_mfma_f32_16x16x32_bf16 v[112:115], v[132:135], v[172:175], v[112:115]
	v_mfma_f32_16x16x32_bf16 v[72:75], v[140:143], v[172:175], v[72:75]
	v_mfma_f32_16x16x32_bf16 v[108:111], v[132:135], v[194:197], v[108:111]
	v_mfma_f32_16x16x32_bf16 v[68:71], v[140:143], v[194:197], v[68:71]
	v_mfma_f32_16x16x32_bf16 v[92:95], v[136:139], v[152:155], v[92:95]
	v_mfma_f32_16x16x32_bf16 v[84:87], v[144:147], v[152:155], v[84:87]
	v_mfma_f32_16x16x32_bf16 v[116:119], v[136:139], v[168:171], v[116:119]
	v_mfma_f32_16x16x32_bf16 v[76:79], v[144:147], v[168:171], v[76:79]
	v_mfma_f32_16x16x32_bf16 v[112:115], v[136:139], v[190:193], v[112:115]
	v_mfma_f32_16x16x32_bf16 v[72:75], v[144:147], v[190:193], v[72:75]
	v_mfma_f32_16x16x32_bf16 v[108:111], v[136:139], v[198:201], v[108:111]
	v_mfma_f32_16x16x32_bf16 v[68:71], v[144:147], v[198:201], v[68:71]
	s_barrier
; #define PG8_STAGE(bufoff, gbase, voff) do { _Pragma("unroll") for (int _i = 0; _i < 2; ++_i) \
;         __builtin_amdgcn_global_load_lds((const unsigned*)((const char*)(gbase) + (voff)[_i]), (LAS unsigned*)(lds + (bufoff) + ldsw + _i * 8192), 16, 0, 0); } while (0)
; #define PG8_LDA(dst, b, h) do { _Pragma("unroll") for (int m = 0; m < 4; ++m) _Pragma("unroll") for (int k = 0; k < 2; ++k) dst[m][k] = *(const LAS bf16x8*)(lds + PG8_SA(b, h) + aoff + m * 2048 + k * 1024); } while (0)
; #define PG8_LDB(dst, b, h) do { _Pragma("unroll") for (int n = 0; n < 2; ++n) _Pragma("unroll") for (int k = 0; k < 2; ++k) dst[n][k] = *(const LAS bf16x8*)(lds + PG8_SB(b, h) + boff + n * 2048 + k * 1024); } while (0)
; #define PG8_MMA(ai, bj, At, Bt) do { __builtin_amdgcn_s_setprio(1); _Pragma("unroll") for (int m = 0; m < 4; ++m) _Pragma("unroll") for (int n = 0; n < 2; ++n) _Pragma("unroll") for (int k = 0; k < 2; ++k) \
;         acc[ai][bj][m][n] = __builtin_amdgcn_mfma_f32_16x16x32_bf16(Bt[n][k], At[m][k], acc[ai][bj][m][n], 0, 0, 0); __builtin_amdgcn_s_setprio(0); } while (0)
; #define PG8_WAIT_V(n) asm volatile("s_waitcnt vmcnt(" #n ")" ::: "memory")
; #define PG8_WAIT_L(n) asm volatile("s_waitcnt lgkmcnt(" #n ")" ::: "memory")
; #define PG8_BAR __builtin_amdgcn_s_barrier()
; #define PG8_SCHED __builtin_amdgcn_sched_barrier(0)
; template <class Epi>
; __device__ __forceinline__ void gemm_phase(LAS unsigned char* lds, const Gemm g, const StaticOrder& S, const Epi& E) {
;     ...
;             PG8_BAR; PG8_WAIT_L(0); PG8_MMA(1, 0, At, B0); PG8_BAR; PG8_SCHED;
;             PG8_STAGE(PG8_SB(0, 1), b2 + hstep, voffB);
;             PG8_WAIT_V(6); PG8_BAR; PG8_MMA(1, 1, At, B1); PG8_BAR;
;             PG8_LDB(B0, 1, 0); PG8_SCHED; PG8_LDA(At, 1, 0); PG8_STAGE(PG8_SA(0, 1), a2 + hstep, voffA);
;             PG8_WAIT_L(8); PG8_BAR; PG8_WAIT_L(0); PG8_MMA(0, 0, At, B0); PG8_BAR; PG8_SCHED;
;             PG8_LDB(B1, 1, 1); PG8_STAGE(PG8_SB(1, 0), b3, voffB);
;             PG8_BAR; PG8_WAIT_L(0); PG8_MMA(0, 1, At, B1); PG8_BAR;
;             PG8_LDA(At, 1, 1); PG8_STAGE(PG8_SA(1, 0), a3, voffA);
;             PG8_BAR; PG8_WAIT_L(0); PG8_MMA(1, 0, At, B0); PG8_BAR; PG8_SCHED;
	s_add_u32 s0, s28, s52
	s_addc_u32 s1, s29, 0
	s_add_i32 s28, s70, s34
	v_lshl_add_u64 v[222:223], s[0:1], 0, v[162:163]
	s_mov_b32 m0, s28
	v_lshl_add_u64 v[224:225], s[0:1], 0, v[160:161]
	global_load_lds_dwordx4 v[222:223], off
	s_add_i32 m0, s28, 0x2000
	s_nop 0
	global_load_lds_dwordx4 v[224:225], off
	s_waitcnt vmcnt(6)
	s_barrier
	v_mfma_f32_16x16x32_bf16 v[48:51], v[202:205], v[148:151], v[48:51]
	v_mfma_f32_16x16x32_bf16 v[16:19], v[210:213], v[148:151], v[16:19]
	v_mfma_f32_16x16x32_bf16 v[44:47], v[202:205], v[156:159], v[44:47]
	v_mfma_f32_16x16x32_bf16 v[12:15], v[210:213], v[156:159], v[12:15]
	v_mfma_f32_16x16x32_bf16 v[40:43], v[202:205], v[172:175], v[40:43]
	v_mfma_f32_16x16x32_bf16 v[6:9], v[210:213], v[172:175], v[8:11]
	v_mfma_f32_16x16x32_bf16 v[36:39], v[202:205], v[194:197], v[36:39]
	v_mfma_f32_16x16x32_bf16 v[0:3], v[210:213], v[194:197], v[0:3]
	v_mfma_f32_16x16x32_bf16 v[48:51], v[206:209], v[152:155], v[48:51]
	v_mfma_f32_16x16x32_bf16 v[16:19], v[214:217], v[152:155], v[16:19]
	v_mfma_f32_16x16x32_bf16 v[44:47], v[206:209], v[168:171], v[44:47]
	v_mfma_f32_16x16x32_bf16 v[12:15], v[214:217], v[168:171], v[12:15]
	v_mfma_f32_16x16x32_bf16 v[40:43], v[206:209], v[190:193], v[40:43]
	v_mfma_f32_16x16x32_bf16 v[6:9], v[214:217], v[190:193], v[6:9]
	v_mfma_f32_16x16x32_bf16 v[36:39], v[206:209], v[198:201], v[36:39]
	v_mfma_f32_16x16x32_bf16 v[0:3], v[214:217], v[198:201], v[0:3]
	s_add_i32 s28, 0, 0x18000
	v_add_u32_e32 v4, s28, v245
	s_barrier
	ds_read_b128 v[132:135], v4
	ds_read_b128 v[136:139], v4 offset:1024
	ds_read_b128 v[140:143], v4 offset:2048
	ds_read_b128 v[144:147], v4 offset:3072
	s_add_u32 s0, s26, s52
	s_addc_u32 s1, s27, 0
	s_mov_b32 m0, s41
	v_lshl_add_u64 v[10:11], s[0:1], 0, v[162:163]
	ds_read_b128 v[148:151], v249 offset:32768
	ds_read_b128 v[152:155], v249 offset:33792
	ds_read_b128 v[156:159], v249 offset:34816
	ds_read_b128 v[168:171], v249 offset:35840
	ds_read_b128 v[172:175], v249 offset:36864
	ds_read_b128 v[190:193], v249 offset:37888
	ds_read_b128 v[194:197], v249 offset:38912
	ds_read_b128 v[198:201], v249 offset:39936
	global_load_lds_dwordx4 v[10:11], off
	s_mov_b32 m0, s42
	v_lshl_add_u64 v[10:11], s[0:1], 0, v[160:161]
	global_load_lds_dwordx4 v[10:11], off
	s_waitcnt lgkmcnt(8)
	s_barrier
	s_waitcnt lgkmcnt(0)
	v_mfma_f32_16x16x32_bf16 v[80:83], v[132:135], v[148:151], v[80:83]
	v_mfma_f32_16x16x32_bf16 v[104:107], v[140:143], v[148:151], v[104:107]
	v_mfma_f32_16x16x32_bf16 v[128:131], v[132:135], v[156:159], v[128:131]
	v_mfma_f32_16x16x32_bf16 v[100:103], v[140:143], v[156:159], v[100:103]
	v_mfma_f32_16x16x32_bf16 v[124:127], v[132:135], v[172:175], v[124:127]
	v_mfma_f32_16x16x32_bf16 v[96:99], v[140:143], v[172:175], v[96:99]
	v_mfma_f32_16x16x32_bf16 v[120:123], v[132:135], v[194:197], v[120:123]
	v_mfma_f32_16x16x32_bf16 v[88:91], v[140:143], v[194:197], v[88:91]
	v_mfma_f32_16x16x32_bf16 v[80:83], v[136:139], v[152:155], v[80:83]
	v_mfma_f32_16x16x32_bf16 v[104:107], v[144:147], v[152:155], v[104:107]
	v_mfma_f32_16x16x32_bf16 v[128:131], v[136:139], v[168:171], v[128:131]
	v_mfma_f32_16x16x32_bf16 v[100:103], v[144:147], v[168:171], v[100:103]
	v_mfma_f32_16x16x32_bf16 v[124:127], v[136:139], v[190:193], v[124:127]
	v_mfma_f32_16x16x32_bf16 v[96:99], v[144:147], v[190:193], v[96:99]
	v_mfma_f32_16x16x32_bf16 v[120:123], v[136:139], v[198:201], v[120:123]
	v_mfma_f32_16x16x32_bf16 v[88:91], v[144:147], v[198:201], v[88:91]
	s_barrier
	s_add_i32 s0, 0, 0x1c000
	s_add_i32 s1, s28, s34
	v_add_u32_e32 v4, s0, v245
	v_lshl_add_u64 v[10:11], v[176:177], 0, s[86:87]
	s_mov_b32 m0, s1
	ds_read_b128 v[202:205], v4
	ds_read_b128 v[206:209], v4 offset:1024
	ds_read_b128 v[210:213], v4 offset:2048
	ds_read_b128 v[214:217], v4 offset:3072
	global_load_lds_dwordx4 v[10:11], off
	s_add_i32 m0, s1, 0x2000
	v_lshl_add_u64 v[10:11], v[186:187], 0, s[86:87]
	global_load_lds_dwordx4 v[10:11], off
	s_barrier
	s_waitcnt lgkmcnt(0)
	v_mfma_f32_16x16x32_bf16 v[64:67], v[202:205], v[148:151], v[64:67]
	v_mfma_f32_16x16x32_bf16 v[32:35], v[210:213], v[148:151], v[32:35]
	v_mfma_f32_16x16x32_bf16 v[60:63], v[202:205], v[156:159], v[60:63]
	v_mfma_f32_16x16x32_bf16 v[28:31], v[210:213], v[156:159], v[28:31]
	v_mfma_f32_16x16x32_bf16 v[56:59], v[202:205], v[172:175], v[56:59]
	v_mfma_f32_16x16x32_bf16 v[24:27], v[210:213], v[172:175], v[24:27]
	v_mfma_f32_16x16x32_bf16 v[52:55], v[202:205], v[194:197], v[52:55]
	v_mfma_f32_16x16x32_bf16 v[20:23], v[210:213], v[194:197], v[20:23]
	v_mfma_f32_16x16x32_bf16 v[64:67], v[206:209], v[152:155], v[64:67]
	v_mfma_f32_16x16x32_bf16 v[32:35], v[214:217], v[152:155], v[32:35]
	v_mfma_f32_16x16x32_bf16 v[60:63], v[206:209], v[168:171], v[60:63]
	v_mfma_f32_16x16x32_bf16 v[28:31], v[214:217], v[168:171], v[28:31]
	v_mfma_f32_16x16x32_bf16 v[56:59], v[206:209], v[190:193], v[56:59]
	v_mfma_f32_16x16x32_bf16 v[24:27], v[214:217], v[190:193], v[24:27]
	v_mfma_f32_16x16x32_bf16 v[52:55], v[206:209], v[198:201], v[52:55]
	v_mfma_f32_16x16x32_bf16 v[20:23], v[214:217], v[198:201], v[20:23]
	s_mov_b32 m0, s55
	v_lshl_add_u64 v[10:11], v[218:219], 0, s[86:87]
	s_barrier
; #define PG8_STAGE(bufoff, gbase, voff) do { _Pragma("unroll") for (int _i = 0; _i < 2; ++_i) \
;         __builtin_amdgcn_global_load_lds((const unsigned*)((const char*)(gbase) + (voff)[_i]), (LAS unsigned*)(lds + (bufoff) + ldsw + _i * 8192), 16, 0, 0); } while (0)
; #define PG8_MMA(ai, bj, At, Bt) do { __builtin_amdgcn_s_setprio(1); _Pragma("unroll") for (int m = 0; m < 4; ++m) _Pragma("unroll") for (int n = 0; n < 2; ++n) _Pragma("unroll") for (int k = 0; k < 2; ++k) \
;         acc[ai][bj][m][n] = __builtin_amdgcn_mfma_f32_16x16x32_bf16(Bt[n][k], At[m][k], acc[ai][bj][m][n], 0, 0, 0); __builtin_amdgcn_s_setprio(0); } while (0)
; #define PG8_WAIT_V(n) asm volatile("s_waitcnt vmcnt(" #n ")" ::: "memory")
; #define PG8_WAIT_L(n) asm volatile("s_waitcnt lgkmcnt(" #n ")" ::: "memory")
; #define PG8_BAR __builtin_amdgcn_s_barrier()
; #define PG8_SCHED __builtin_amdgcn_sched_barrier(0)
; template <class Epi>
; __device__ __forceinline__ void gemm_phase(LAS unsigned char* lds, const Gemm g, const StaticOrder& S, const Epi& E) {
;     ...
;             PG8_BAR; PG8_WAIT_L(0); PG8_MMA(1, 0, At, B0); PG8_BAR; PG8_SCHED;
;             PG8_STAGE(PG8_SB(1, 1), b3 + hstep, voffB);
;             PG8_WAIT_V(6); PG8_BAR; PG8_MMA(1, 1, At, B1); PG8_BAR;
;     __device__ __forceinline__ void operator()(const f32x4 (&acc)[2][2][4][2], const Unit& u, int wr, int wc, int fr, int fq) const {
;         const int row0 = u.pm * 256 + wr * 64 + fr, col0 = u.pn * 256 + wc * 32 + 4 * fq;
;         const float* mvp = mv + (size_t)(u.pm >> 3) * 9216 + col0;
;         const float fac = __builtin_amdgcn_readfirstlane(ffn) ? 0.5f : 1.f;
;         const bool hb = __builtin_amdgcn_readfirstlane(has_next) != 0;
;         f32x4 rs0 = (f32x4){0.f, 0.f, 0.f, 0.f}, rs1 = rs0;
; #pragma unroll
;         for (int bj = 0; bj < 2; ++bj)
; #pragma unroll
;             for (int n = 0; n < 2; ++n) {
;                 const int co = bj * 128 + n * 16;
;                 const f32x4 mvv = *(const f32x4*)(mvp + co) * fac;
;                 f32x4 gn = (f32x4){0.f, 0.f, 0.f, 0.f};
;                 if (hb) gn = *(const f32x4*)(nwn + col0 + co) * (*(const f32x4*)(scn + (size_t)(u.pm >> 3) * 9216 + col0 + co) + 1.f);
	ds_read_b128 v[148:151], v249 offset:49152
	ds_read_b128 v[152:155], v249 offset:50176
	ds_read_b128 v[156:159], v249 offset:51200
	ds_read_b128 v[168:171], v249 offset:52224
	ds_read_b128 v[172:175], v249 offset:53248
	ds_read_b128 v[190:193], v249 offset:54272
	ds_read_b128 v[194:197], v249 offset:55296
	ds_read_b128 v[198:201], v249 offset:56320
	global_load_lds_dwordx4 v[10:11], off
	s_mov_b32 m0, s56
	v_lshl_add_u64 v[10:11], v[220:221], 0, s[86:87]
	global_load_lds_dwordx4 v[10:11], off
	s_barrier
	s_waitcnt lgkmcnt(0)
	v_mfma_f32_16x16x32_bf16 v[92:95], v[132:135], v[148:151], v[92:95]
	v_mfma_f32_16x16x32_bf16 v[84:87], v[140:143], v[148:151], v[84:87]
	v_mfma_f32_16x16x32_bf16 v[116:119], v[132:135], v[156:159], v[116:119]
	v_mfma_f32_16x16x32_bf16 v[76:79], v[140:143], v[156:159], v[76:79]
	v_mfma_f32_16x16x32_bf16 v[112:115], v[132:135], v[172:175], v[112:115]
	v_mfma_f32_16x16x32_bf16 v[72:75], v[140:143], v[172:175], v[72:75]
	v_mfma_f32_16x16x32_bf16 v[108:111], v[132:135], v[194:197], v[108:111]
	v_mfma_f32_16x16x32_bf16 v[68:71], v[140:143], v[194:197], v[68:71]
	v_mfma_f32_16x16x32_bf16 v[92:95], v[136:139], v[152:155], v[92:95]
	v_mfma_f32_16x16x32_bf16 v[84:87], v[144:147], v[152:155], v[84:87]
	v_mfma_f32_16x16x32_bf16 v[116:119], v[136:139], v[168:171], v[116:119]
	v_mfma_f32_16x16x32_bf16 v[76:79], v[144:147], v[168:171], v[76:79]
	v_mfma_f32_16x16x32_bf16 v[112:115], v[136:139], v[190:193], v[112:115]
	v_mfma_f32_16x16x32_bf16 v[72:75], v[144:147], v[190:193], v[72:75]
	v_mfma_f32_16x16x32_bf16 v[108:111], v[136:139], v[198:201], v[108:111]
	v_mfma_f32_16x16x32_bf16 v[68:71], v[144:147], v[198:201], v[68:71]
	s_barrier
	s_add_i32 s0, s0, s34
	s_mov_b32 m0, s0
	v_lshl_add_u64 v[10:11], v[222:223], 0, s[86:87]
	global_load_lds_dwordx4 v[10:11], off
	s_add_i32 m0, s0, 0x2000
	v_lshl_add_u64 v[10:11], v[224:225], 0, s[86:87]
	global_load_lds_dwordx4 v[10:11], off
	s_waitcnt vmcnt(6)
	s_barrier
	v_mfma_f32_16x16x32_bf16 v[48:51], v[202:205], v[148:151], v[48:51]
	v_mfma_f32_16x16x32_bf16 v[16:19], v[210:213], v[148:151], v[16:19]
	v_mfma_f32_16x16x32_bf16 v[44:47], v[202:205], v[156:159], v[44:47]
	v_mfma_f32_16x16x32_bf16 v[10:13], v[210:213], v[156:159], v[12:15]
	v_mfma_f32_16x16x32_bf16 v[40:43], v[202:205], v[172:175], v[40:43]
	v_mfma_f32_16x16x32_bf16 v[6:9], v[210:213], v[172:175], v[6:9]
	v_mfma_f32_16x16x32_bf16 v[36:39], v[202:205], v[194:197], v[36:39]
	v_mfma_f32_16x16x32_bf16 v[0:3], v[210:213], v[194:197], v[0:3]
	v_mfma_f32_16x16x32_bf16 v[48:51], v[206:209], v[152:155], v[48:51]
	v_mfma_f32_16x16x32_bf16 v[16:19], v[214:217], v[152:155], v[16:19]
	v_mfma_f32_16x16x32_bf16 v[44:47], v[206:209], v[168:171], v[44:47]
	v_mfma_f32_16x16x32_bf16 v[12:15], v[214:217], v[168:171], v[10:13]
	v_mfma_f32_16x16x32_bf16 v[40:43], v[206:209], v[190:193], v[40:43]
	v_mfma_f32_16x16x32_bf16 v[8:11], v[214:217], v[190:193], v[6:9]
	v_mfma_f32_16x16x32_bf16 v[36:39], v[206:209], v[198:201], v[36:39]
	v_mfma_f32_16x16x32_bf16 v[0:3], v[214:217], v[198:201], v[0:3]
	s_add_u32 s8, s8, 0x100
	s_addc_u32 s9, s9, 0
	s_add_u32 s62, s62, 0x100
	s_addc_u32 s63, s63, 0
	s_cmp_ge_u32 s64, s49
	s_mov_b32 s26, s64
	s_barrier
	s_cbranch_scc0 .LBB0_2974
	s_ashr_i32 s0, s60, 3
	s_mul_i32 s29, s0, 0x9000
	v_lshl_or_b32 v170, s61, 8, v248
	s_mul_hi_i32 s28, s0, 0x9000
	s_add_u32 s0, s50, s29
	s_addc_u32 s1, s51, s28
	v_ashrrev_i32_e32 v171, 31, v170
	v_lshl_add_u64 v[176:177], v[170:171], 2, s[0:1]
	global_load_dwordx4 v[132:135], v[176:177], off
	v_readfirstlane_b32 s0, v243
	s_cmp_lg_u32 s0, 0
	v_lshlrev_b64 v[168:169], 2, v[170:171]
	v_readfirstlane_b32 s8, v242
	s_cselect_b64 s[26:27], -1, 0
	s_cmp_eq_u32 s0, 0
	v_lshl_add_u64 v[190:191], s[18:19], 0, v[168:169]
	s_cbranch_scc1 .LBB0_2977
	s_add_u32 s0, s43, s29
	s_addc_u32 s1, s48, s28
	v_lshl_add_u64 v[6:7], s[0:1], 0, v[168:169]
	global_load_dwordx4 v[136:139], v[6:7], off
	global_load_dwordx4 v[140:143], v[190:191], off
	s_waitcnt vmcnt(0)
	v_pk_add_f32 v[6:7], v[138:139], 1.0 op_sel_hi:[1,0]
	v_pk_add_f32 v[136:137], v[136:137], 1.0 op_sel_hi:[1,0]
	v_pk_mul_f32 v[218:219], v[142:143], v[6:7]
	v_pk_mul_f32 v[216:217], v[140:141], v[136:137]
	s_branch .LBB0_2978
